# v16 variant: B0 fragment reads issued by the preceding load phase (P4/P8) instead of inside MFMA groups 3/7
# baseline (speedup 1.0000x reference)
; #define PG8_STAGE(bufoff, gbase, voff) do { _Pragma("unroll") for (int _i = 0; _i < 2; ++_i) \
;         __builtin_amdgcn_global_load_lds((const unsigned*)((const char*)(gbase) + (voff)[_i]), (LAS unsigned*)(lds + (bufoff) + ldsw + _i * 8192), 16, 0, 0); } while (0)
; #define PG8_LDA(dst, b, h) do { _Pragma("unroll") for (int m = 0; m < 4; ++m) _Pragma("unroll") for (int k = 0; k < 2; ++k) dst[m][k] = *(const LAS bf16x8*)(lds + PG8_SA(b, h) + aoff + m * 2048 + k * 1024); } while (0)
; #define PG8_LDB(dst, b, h) do { _Pragma("unroll") for (int n = 0; n < 2; ++n) _Pragma("unroll") for (int k = 0; k < 2; ++k) dst[n][k] = *(const LAS bf16x8*)(lds + PG8_SB(b, h) + boff + n * 2048 + k * 1024); } while (0)
; #define PG8_MMA(ai, bj, At, Bt) do { __builtin_amdgcn_s_setprio(1); _Pragma("unroll") for (int m = 0; m < 4; ++m) _Pragma("unroll") for (int n = 0; n < 2; ++n) _Pragma("unroll") for (int k = 0; k < 2; ++k) \
;         acc[ai][bj][m][n] = __builtin_amdgcn_mfma_f32_16x16x32_bf16(Bt[n][k], At[m][k], acc[ai][bj][m][n], 0, 0, 0); __builtin_amdgcn_s_setprio(0); } while (0)
; #define PG8_WAIT_L(n) asm volatile("s_waitcnt lgkmcnt(" #n ")" ::: "memory")
; template <class Epi, class Sched>
; __device__ __forceinline__ void gemm_phase(LAS unsigned char* lds, const Gemm g, const Sched& S, const Epi& E) {
;     ...
;         const bool has_next = S.next(ui + 1, nxt);
;         const char* nA = has_next ? PG8_APANEL(nxt.pm) : cA; const char* nB = has_next ? (const char*)g.Bt + (size_t)nxt.pn * tstep : cB;
;         for (int t = 0; t < nt; t += 2) {
;             const bool last = (t == nt - 2);
;             const char* a1 = cA + (size_t)(t + 1) * kstep;
;             const char* a2 = last ? nA : cA + (size_t)(t + 2) * kstep; const char* b2 = last ? nB : cB + (size_t)(t + 2) * kstep;
;             const char* a3 = a2 + kstep; const char* b3 = b2 + kstep;
;             PG8_LDB(B0, 0, 0); PG8_SCHED; PG8_LDA(At, 0, 0); PG8_STAGE(PG8_SA(1, 1), a1 + hstep, voffA);
;             PG8_WAIT_L(8); PG8_BAR; PG8_WAIT_L(0); PG8_MMA(0, 0, At, B0); PG8_BAR; PG8_SCHED;
;             PG8_LDB(B1, 0, 1); PG8_STAGE(PG8_SB(0, 0), b2, voffB);
;             PG8_BAR; PG8_WAIT_L(0); PG8_MMA(0, 1, At, B1); PG8_BAR;
;             PG8_LDA(At, 0, 1); PG8_STAGE(PG8_SA(0, 0), a2, voffA);
;             PG8_BAR; PG8_WAIT_L(0); PG8_MMA(1, 0, At, B0); PG8_BAR; PG8_SCHED;
.LBB0_164:
	s_cmp_lt_i32 s44, 0x100000
	s_cselect_b32 s24, s20, 0xffffff80
	s_cselect_b32 s25, s11, 0
	s_ashr_i32 s45, s44, 31
	s_lshl_b64 s[34:35], s[44:45], 19
	v_cmp_lt_i64_e32 vcc, s[46:47], v[152:153]
	s_add_u32 s46, s25, s34
	s_addc_u32 s47, s24, s35
	s_and_b64 s[34:35], vcc, exec
	s_cselect_b32 s34, s47, s49
	s_cselect_b32 s45, s46, s48
	s_ashr_i32 s43, s42, 31
	s_lshl_b64 s[60:61], s[42:43], 19
	s_add_u32 s76, s16, s60
	s_addc_u32 s77, s92, s61
	s_and_b64 s[60:61], vcc, exec
	s_cselect_b32 s43, s77, s39
	s_cselect_b32 s79, s76, s38
	s_add_u32 vcc_lo, s38, 0x100
	s_addc_u32 s35, s39, 0
	s_add_u32 s38, s48, 0x40080
	s_addc_u32 s39, s49, 0
	s_mov_b32 s50, -2
	v_add_u32_e32 v249, 0x10000, v167
	ds_read_b128 v[142:145], v249
	ds_read_b128 v[162:165], v249 offset:1024
	ds_read_b128 v[182:185], v249 offset:2048
	ds_read_b128 v[186:189], v249 offset:3072
	ds_read_b128 v[190:193], v169
	ds_read_b128 v[194:197], v169 offset:1024
	ds_read_b128 v[198:201], v169 offset:2048
	ds_read_b128 v[202:205], v169 offset:3072
	ds_read_b128 v[206:209], v169 offset:4096
	ds_read_b128 v[210:213], v169 offset:5120
	s_add_u32 s24, s38, 0xfffc0080
	s_addc_u32 s25, s39, -1
	s_add_i32 vcc_hi, 0, 0x10000
	s_cmp_eq_u32 s50, 12
	s_cselect_b32 s61, s34, s25
	s_cselect_b32 s60, s45, s24
	s_cselect_b32 s49, s43, s35
	s_cselect_b32 s48, s79, vcc_lo
	s_add_i32 m0, s93, 0xc000
	ds_read_b128 v[214:217], v169 offset:6144
	ds_read_b128 v[218:221], v169 offset:7168
	global_load_lds_dwordx4 v140, s[38:39]
	s_add_i32 m0, s93, 0xe000
	s_nop 0
	global_load_lds_dwordx4 v138, s[38:39]
	s_waitcnt lgkmcnt(8)
	s_barrier
	s_waitcnt lgkmcnt(0)
	s_setprio 1
	s_waitcnt lgkmcnt(0)
	v_mfma_f32_16x16x32_bf16 v[126:129], v[142:145], v[190:193], 0
	v_mfma_f32_16x16x32_bf16 v[126:129], v[162:165], v[194:197], v[126:129]
	v_mfma_f32_16x16x32_bf16 v[122:125], v[182:185], v[190:193], 0
	v_mfma_f32_16x16x32_bf16 v[122:125], v[186:189], v[194:197], v[122:125]
	v_mfma_f32_16x16x32_bf16 v[110:113], v[142:145], v[198:201], 0
	v_mfma_f32_16x16x32_bf16 v[110:113], v[162:165], v[202:205], v[110:113]
	v_mfma_f32_16x16x32_bf16 v[106:109], v[182:185], v[198:201], 0
	v_mfma_f32_16x16x32_bf16 v[106:109], v[186:189], v[202:205], v[106:109]
	v_mfma_f32_16x16x32_bf16 v[94:97], v[142:145], v[206:209], 0
	v_mfma_f32_16x16x32_bf16 v[94:97], v[162:165], v[210:213], v[94:97]
	v_mfma_f32_16x16x32_bf16 v[90:93], v[182:185], v[206:209], 0
	v_mfma_f32_16x16x32_bf16 v[90:93], v[186:189], v[210:213], v[90:93]
	v_mfma_f32_16x16x32_bf16 v[78:81], v[142:145], v[214:217], 0
	v_mfma_f32_16x16x32_bf16 v[78:81], v[162:165], v[218:221], v[78:81]
	v_mfma_f32_16x16x32_bf16 v[74:77], v[182:185], v[214:217], 0
	s_barrier
	v_mfma_f32_16x16x32_bf16 v[74:77], v[186:189], v[218:221], v[74:77]
	s_setprio 0
	s_add_i32 s51, 0, 0x14000
	s_add_i32 s24, vcc_hi, s86
	s_mov_b32 m0, s24
	ds_read_b128 v[222:225], v249 offset:16384
	ds_read_b128 v[226:229], v249 offset:17408
	ds_read_b128 v[230:233], v249 offset:18432
	ds_read_b128 v[234:237], v249 offset:19456
	global_load_lds_dwordx4 v134, s[48:49]
	s_add_i32 m0, s24, 0x2000
	s_nop 0
	global_load_lds_dwordx4 v130, s[48:49]
	s_barrier
	s_waitcnt lgkmcnt(0)
	s_setprio 1
	s_waitcnt lgkmcnt(0)
	v_mfma_f32_16x16x32_bf16 v[118:121], v[222:225], v[190:193], 0
	v_mfma_f32_16x16x32_bf16 v[118:121], v[226:229], v[194:197], v[118:121]
	v_mfma_f32_16x16x32_bf16 v[114:117], v[230:233], v[190:193], 0
	v_mfma_f32_16x16x32_bf16 v[114:117], v[234:237], v[194:197], v[114:117]
	v_mfma_f32_16x16x32_bf16 v[102:105], v[222:225], v[198:201], 0
	v_mfma_f32_16x16x32_bf16 v[102:105], v[226:229], v[202:205], v[102:105]
	v_mfma_f32_16x16x32_bf16 v[98:101], v[230:233], v[198:201], 0
	v_mfma_f32_16x16x32_bf16 v[98:101], v[234:237], v[202:205], v[98:101]
	v_mfma_f32_16x16x32_bf16 v[86:89], v[222:225], v[206:209], 0
	v_mfma_f32_16x16x32_bf16 v[86:89], v[226:229], v[210:213], v[86:89]
	v_mfma_f32_16x16x32_bf16 v[82:85], v[230:233], v[206:209], 0
	v_mfma_f32_16x16x32_bf16 v[82:85], v[234:237], v[210:213], v[82:85]
	v_mfma_f32_16x16x32_bf16 v[70:73], v[222:225], v[214:217], 0
	v_mfma_f32_16x16x32_bf16 v[70:73], v[226:229], v[218:221], v[70:73]
	v_mfma_f32_16x16x32_bf16 v[66:69], v[230:233], v[214:217], 0
	s_barrier
	v_mfma_f32_16x16x32_bf16 v[66:69], v[234:237], v[218:221], v[66:69]
	s_setprio 0
	s_mov_b32 m0, s93
	s_mov_b64 s[100:101], s[60:61]
	ds_read_b128 v[190:193], v169 offset:16384
	ds_read_b128 v[194:197], v169 offset:17408
	ds_read_b128 v[198:201], v169 offset:18432
	ds_read_b128 v[202:205], v169 offset:19456
	ds_read_b128 v[206:209], v169 offset:20480
	ds_read_b128 v[210:213], v169 offset:21504
	ds_read_b128 v[214:217], v169 offset:22528
	ds_read_b128 v[218:221], v169 offset:23552
	global_load_lds_dwordx4 v136, s[60:61]
	s_mov_b64 s[100:101], s[60:61]
	s_mov_b32 m0, s98
	s_nop 0
	global_load_lds_dwordx4 v132, s[60:61]
	s_waitcnt vmcnt(8)
	s_barrier
	s_waitcnt lgkmcnt(0)
	s_setprio 1
	s_waitcnt lgkmcnt(0)
	v_mfma_f32_16x16x32_bf16 v[62:65], v[142:145], v[190:193], 0
	v_mfma_f32_16x16x32_bf16 v[62:65], v[162:165], v[194:197], v[62:65]
	v_mfma_f32_16x16x32_bf16 v[58:61], v[182:185], v[190:193], 0
	v_mfma_f32_16x16x32_bf16 v[58:61], v[186:189], v[194:197], v[58:61]
	v_mfma_f32_16x16x32_bf16 v[46:49], v[142:145], v[198:201], 0
	v_mfma_f32_16x16x32_bf16 v[46:49], v[162:165], v[202:205], v[46:49]
	v_mfma_f32_16x16x32_bf16 v[42:45], v[182:185], v[198:201], 0
	v_mfma_f32_16x16x32_bf16 v[42:45], v[186:189], v[202:205], v[42:45]
	v_mfma_f32_16x16x32_bf16 v[30:33], v[142:145], v[206:209], 0
	v_mfma_f32_16x16x32_bf16 v[30:33], v[162:165], v[210:213], v[30:33]
	v_mfma_f32_16x16x32_bf16 v[26:29], v[182:185], v[206:209], 0
	v_mfma_f32_16x16x32_bf16 v[26:29], v[186:189], v[210:213], v[26:29]
	v_mfma_f32_16x16x32_bf16 v[14:17], v[142:145], v[214:217], 0
	v_mfma_f32_16x16x32_bf16 v[14:17], v[162:165], v[218:221], v[14:17]
	v_mfma_f32_16x16x32_bf16 v[10:13], v[182:185], v[214:217], 0
	s_barrier
; #define PG8_STAGE(bufoff, gbase, voff) do { _Pragma("unroll") for (int _i = 0; _i < 2; ++_i) \
;         __builtin_amdgcn_global_load_lds((const unsigned*)((const char*)(gbase) + (voff)[_i]), (LAS unsigned*)(lds + (bufoff) + ldsw + _i * 8192), 16, 0, 0); } while (0)
; #define PG8_LDA(dst, b, h) do { _Pragma("unroll") for (int m = 0; m < 4; ++m) _Pragma("unroll") for (int k = 0; k < 2; ++k) dst[m][k] = *(const LAS bf16x8*)(lds + PG8_SA(b, h) + aoff + m * 2048 + k * 1024); } while (0)
; #define PG8_LDB(dst, b, h) do { _Pragma("unroll") for (int n = 0; n < 2; ++n) _Pragma("unroll") for (int k = 0; k < 2; ++k) dst[n][k] = *(const LAS bf16x8*)(lds + PG8_SB(b, h) + boff + n * 2048 + k * 1024); } while (0)
; #define PG8_MMA(ai, bj, At, Bt) do { __builtin_amdgcn_s_setprio(1); _Pragma("unroll") for (int m = 0; m < 4; ++m) _Pragma("unroll") for (int n = 0; n < 2; ++n) _Pragma("unroll") for (int k = 0; k < 2; ++k) \
;         acc[ai][bj][m][n] = __builtin_amdgcn_mfma_f32_16x16x32_bf16(Bt[n][k], At[m][k], acc[ai][bj][m][n], 0, 0, 0); __builtin_amdgcn_s_setprio(0); } while (0)
; #define PG8_WAIT_V(n) asm volatile("s_waitcnt vmcnt(" #n ")" ::: "memory")
; #define PG8_WAIT_L(n) asm volatile("s_waitcnt lgkmcnt(" #n ")" ::: "memory")
; #define PG8_BAR __builtin_amdgcn_s_barrier()
; #define PG8_SCHED __builtin_amdgcn_sched_barrier(0)
; template <class Epi, class Sched>
; __device__ __forceinline__ void gemm_phase(LAS unsigned char* lds, const Gemm g, const Sched& S, const Epi& E) {
;     ...
;             PG8_BAR; PG8_WAIT_L(0); PG8_MMA(1, 0, At, B0); PG8_BAR; PG8_SCHED;
;             PG8_STAGE(PG8_SB(0, 1), b2 + hstep, voffB);
;             PG8_WAIT_V(6); PG8_BAR; PG8_MMA(1, 1, At, B1); PG8_BAR;
;             PG8_LDB(B0, 1, 0); PG8_SCHED; PG8_LDA(At, 1, 0); PG8_STAGE(PG8_SA(0, 1), a2 + hstep, voffA);
;             PG8_WAIT_L(8); PG8_BAR; PG8_WAIT_L(0); PG8_MMA(0, 0, At, B0); PG8_BAR; PG8_SCHED;
;             PG8_LDB(B1, 1, 1); PG8_STAGE(PG8_SB(1, 0), b3, voffB);
;             PG8_BAR; PG8_WAIT_L(0); PG8_MMA(0, 1, At, B1); PG8_BAR;
;             PG8_LDA(At, 1, 1); PG8_STAGE(PG8_SA(1, 0), a3, voffA);
	v_mfma_f32_16x16x32_bf16 v[10:13], v[186:189], v[218:221], v[10:13]
	s_setprio 0
	s_add_u32 s24, s48, 0x40000
	s_addc_u32 s25, s49, 0
	s_add_i32 s51, s51, s86
	s_mov_b32 m0, s51
	s_nop 0
	global_load_lds_dwordx4 v134, s[24:25]
	s_add_i32 m0, s51, 0x2000
	s_nop 0
	global_load_lds_dwordx4 v130, s[24:25]
	ds_read_b128 v[142:145], v249 offset:32768
	ds_read_b128 v[162:165], v249 offset:33792
	ds_read_b128 v[182:185], v249 offset:34816
	ds_read_b128 v[186:189], v249 offset:35840
	s_waitcnt vmcnt(6)
	s_barrier
	s_setprio 1
	v_mfma_f32_16x16x32_bf16 v[54:57], v[222:225], v[190:193], 0
	v_mfma_f32_16x16x32_bf16 v[54:57], v[226:229], v[194:197], v[54:57]
	v_mfma_f32_16x16x32_bf16 v[50:53], v[230:233], v[190:193], 0
	ds_read_b128 v[190:193], v169 offset:32768
	v_mfma_f32_16x16x32_bf16 v[50:53], v[234:237], v[194:197], v[50:53]
	ds_read_b128 v[194:197], v169 offset:33792
	v_mfma_f32_16x16x32_bf16 v[38:41], v[222:225], v[198:201], 0
	v_mfma_f32_16x16x32_bf16 v[38:41], v[226:229], v[202:205], v[38:41]
	v_mfma_f32_16x16x32_bf16 v[34:37], v[230:233], v[198:201], 0
	ds_read_b128 v[198:201], v169 offset:34816
	v_mfma_f32_16x16x32_bf16 v[34:37], v[234:237], v[202:205], v[34:37]
	ds_read_b128 v[202:205], v169 offset:35840
	v_mfma_f32_16x16x32_bf16 v[22:25], v[222:225], v[206:209], 0
	v_mfma_f32_16x16x32_bf16 v[22:25], v[226:229], v[210:213], v[22:25]
	v_mfma_f32_16x16x32_bf16 v[18:21], v[230:233], v[206:209], 0
	ds_read_b128 v[206:209], v169 offset:36864
	v_mfma_f32_16x16x32_bf16 v[18:21], v[234:237], v[210:213], v[18:21]
	ds_read_b128 v[210:213], v169 offset:37888
	v_mfma_f32_16x16x32_bf16 v[6:9], v[222:225], v[214:217], 0
	v_mfma_f32_16x16x32_bf16 v[6:9], v[226:229], v[218:221], v[6:9]
	v_mfma_f32_16x16x32_bf16 v[2:5], v[230:233], v[214:217], 0
	s_barrier
	v_mfma_f32_16x16x32_bf16 v[2:5], v[234:237], v[218:221], v[2:5]
	s_setprio 0
	s_add_i32 s51, 0, 0x18000
	s_add_u32 s24, s60, 0x40000
	s_addc_u32 s25, s61, 0
	s_mov_b32 m0, s99
	ds_read_b128 v[214:217], v169 offset:38912
	ds_read_b128 v[218:221], v169 offset:39936
	global_load_lds_dwordx4 v136, s[24:25]
	s_mov_b32 m0, s94
	s_nop 0
	global_load_lds_dwordx4 v132, s[24:25]
	s_waitcnt lgkmcnt(8)
	s_barrier
	s_waitcnt lgkmcnt(0)
	s_setprio 1
	s_waitcnt lgkmcnt(0)
	v_mfma_f32_16x16x32_bf16 v[126:129], v[142:145], v[190:193], v[126:129]
	v_mfma_f32_16x16x32_bf16 v[126:129], v[162:165], v[194:197], v[126:129]
	v_mfma_f32_16x16x32_bf16 v[122:125], v[182:185], v[190:193], v[122:125]
	v_mfma_f32_16x16x32_bf16 v[122:125], v[186:189], v[194:197], v[122:125]
	v_mfma_f32_16x16x32_bf16 v[110:113], v[142:145], v[198:201], v[110:113]
	v_mfma_f32_16x16x32_bf16 v[110:113], v[162:165], v[202:205], v[110:113]
	v_mfma_f32_16x16x32_bf16 v[106:109], v[182:185], v[198:201], v[106:109]
	v_mfma_f32_16x16x32_bf16 v[106:109], v[186:189], v[202:205], v[106:109]
	v_mfma_f32_16x16x32_bf16 v[94:97], v[142:145], v[206:209], v[94:97]
	v_mfma_f32_16x16x32_bf16 v[94:97], v[162:165], v[210:213], v[94:97]
	v_mfma_f32_16x16x32_bf16 v[90:93], v[182:185], v[206:209], v[90:93]
	v_mfma_f32_16x16x32_bf16 v[90:93], v[186:189], v[210:213], v[90:93]
	v_mfma_f32_16x16x32_bf16 v[78:81], v[142:145], v[214:217], v[78:81]
	v_mfma_f32_16x16x32_bf16 v[78:81], v[162:165], v[218:221], v[78:81]
	v_mfma_f32_16x16x32_bf16 v[74:77], v[182:185], v[214:217], v[74:77]
	s_barrier
	v_mfma_f32_16x16x32_bf16 v[74:77], v[186:189], v[218:221], v[74:77]
	s_setprio 0
	s_add_i32 s60, 0, 0x1c000
	s_add_i32 s24, s51, s86
	s_add_i32 m0, s24, 0xffffff80
	ds_read_b128 v[222:225], v249 offset:49152
	ds_read_b128 v[226:229], v249 offset:50176
	ds_read_b128 v[230:233], v249 offset:51200
	ds_read_b128 v[234:237], v249 offset:52224
	global_load_lds_dwordx4 v134, s[48:49] offset:128
	s_add_i32 m0, s24, 0x1f80
	s_nop 0
	global_load_lds_dwordx4 v130, s[48:49] offset:128
	s_barrier
	s_waitcnt lgkmcnt(0)
	s_setprio 1
	s_waitcnt lgkmcnt(0)
	v_mfma_f32_16x16x32_bf16 v[118:121], v[222:225], v[190:193], v[118:121]
	v_mfma_f32_16x16x32_bf16 v[118:121], v[226:229], v[194:197], v[118:121]
	v_mfma_f32_16x16x32_bf16 v[114:117], v[230:233], v[190:193], v[114:117]
	v_mfma_f32_16x16x32_bf16 v[114:117], v[234:237], v[194:197], v[114:117]
	v_mfma_f32_16x16x32_bf16 v[102:105], v[222:225], v[198:201], v[102:105]
	v_mfma_f32_16x16x32_bf16 v[102:105], v[226:229], v[202:205], v[102:105]
	v_mfma_f32_16x16x32_bf16 v[98:101], v[230:233], v[198:201], v[98:101]
	v_mfma_f32_16x16x32_bf16 v[98:101], v[234:237], v[202:205], v[98:101]
	v_mfma_f32_16x16x32_bf16 v[86:89], v[222:225], v[206:209], v[86:89]
	v_mfma_f32_16x16x32_bf16 v[86:89], v[226:229], v[210:213], v[86:89]
	v_mfma_f32_16x16x32_bf16 v[82:85], v[230:233], v[206:209], v[82:85]
	v_mfma_f32_16x16x32_bf16 v[82:85], v[234:237], v[210:213], v[82:85]
	v_mfma_f32_16x16x32_bf16 v[70:73], v[222:225], v[214:217], v[70:73]
	v_mfma_f32_16x16x32_bf16 v[70:73], v[226:229], v[218:221], v[70:73]
	v_mfma_f32_16x16x32_bf16 v[66:69], v[230:233], v[214:217], v[66:69]
	s_barrier
	v_mfma_f32_16x16x32_bf16 v[66:69], v[234:237], v[218:221], v[66:69]
	s_setprio 0
	s_add_i32 m0, s95, 0xffffff80
	ds_read_b128 v[190:193], v169 offset:49152
	ds_read_b128 v[194:197], v169 offset:50176
	ds_read_b128 v[198:201], v169 offset:51200
	ds_read_b128 v[202:205], v169 offset:52224
	ds_read_b128 v[206:209], v169 offset:53248
	ds_read_b128 v[210:213], v169 offset:54272
	ds_read_b128 v[214:217], v169 offset:55296
	ds_read_b128 v[218:221], v169 offset:56320
	global_load_lds_dwordx4 v136, s[100:101] offset:128
	s_add_i32 m0, s96, 0xffffff80
	s_nop 0
	global_load_lds_dwordx4 v132, s[100:101] offset:128
	s_waitcnt vmcnt(8)
	s_barrier
; #define PG8_STAGE(bufoff, gbase, voff) do { _Pragma("unroll") for (int _i = 0; _i < 2; ++_i) \
;         __builtin_amdgcn_global_load_lds((const unsigned*)((const char*)(gbase) + (voff)[_i]), (LAS unsigned*)(lds + (bufoff) + ldsw + _i * 8192), 16, 0, 0); } while (0)
; #define PG8_LDA(dst, b, h) do { _Pragma("unroll") for (int m = 0; m < 4; ++m) _Pragma("unroll") for (int k = 0; k < 2; ++k) dst[m][k] = *(const LAS bf16x8*)(lds + PG8_SA(b, h) + aoff + m * 2048 + k * 1024); } while (0)
; #define PG8_LDB(dst, b, h) do { _Pragma("unroll") for (int n = 0; n < 2; ++n) _Pragma("unroll") for (int k = 0; k < 2; ++k) dst[n][k] = *(const LAS bf16x8*)(lds + PG8_SB(b, h) + boff + n * 2048 + k * 1024); } while (0)
; #define PG8_WAIT_V(n) asm volatile("s_waitcnt vmcnt(" #n ")" ::: "memory")
; #define PG8_WAIT_L(n) asm volatile("s_waitcnt lgkmcnt(" #n ")" ::: "memory")
; #define PG8_BAR __builtin_amdgcn_s_barrier()
; #define PG8_SCHED __builtin_amdgcn_sched_barrier(0)
; template <class Epi, class Sched>
; __device__ __forceinline__ void gemm_phase(LAS unsigned char* lds, const Gemm g, const Sched& S, const Epi& E) {
;     ...
;             PG8_LDB(B0, 0, 0); PG8_SCHED; PG8_LDA(At, 0, 0); PG8_STAGE(PG8_SA(1, 1), a1 + hstep, voffA);
;             PG8_WAIT_L(8); PG8_BAR; PG8_WAIT_L(0); PG8_MMA(0, 0, At, B0); PG8_BAR; PG8_SCHED;
;             PG8_LDB(B1, 0, 1); PG8_STAGE(PG8_SB(0, 0), b2, voffB);
;             PG8_BAR; PG8_WAIT_L(0); PG8_MMA(0, 1, At, B1); PG8_BAR;
;             PG8_LDA(At, 0, 1); PG8_STAGE(PG8_SA(0, 0), a2, voffA);
;             PG8_BAR; PG8_WAIT_L(0); PG8_MMA(1, 0, At, B0); PG8_BAR; PG8_SCHED;
;             PG8_STAGE(PG8_SB(0, 1), b2 + hstep, voffB);
;             PG8_WAIT_V(6); PG8_BAR; PG8_MMA(1, 1, At, B1); PG8_BAR;
;             PG8_LDB(B0, 1, 0); PG8_SCHED; PG8_LDA(At, 1, 0); PG8_STAGE(PG8_SA(0, 1), a2 + hstep, voffA);
;             PG8_WAIT_L(8); PG8_BAR; PG8_WAIT_L(0); PG8_MMA(0, 0, At, B0); PG8_BAR; PG8_SCHED;
;             PG8_LDB(B1, 1, 1); PG8_STAGE(PG8_SB(1, 0), b3, voffB);
;             PG8_BAR; PG8_WAIT_L(0); PG8_MMA(0, 1, At, B1); PG8_BAR;
;             PG8_LDA(At, 1, 1); PG8_STAGE(PG8_SA(1, 0), a3, voffA);
;             PG8_BAR; PG8_WAIT_L(0); PG8_MMA(1, 0, At, B0); PG8_BAR; PG8_SCHED;
;             PG8_STAGE(PG8_SB(1, 1), b3 + hstep, voffB);
;             PG8_WAIT_V(6); PG8_BAR; PG8_MMA(1, 1, At, B1); PG8_BAR;
	s_waitcnt lgkmcnt(0)
	s_setprio 1
	s_waitcnt lgkmcnt(0)
	v_mfma_f32_16x16x32_bf16 v[62:65], v[142:145], v[190:193], v[62:65]
	v_mfma_f32_16x16x32_bf16 v[62:65], v[162:165], v[194:197], v[62:65]
	v_mfma_f32_16x16x32_bf16 v[58:61], v[182:185], v[190:193], v[58:61]
	v_mfma_f32_16x16x32_bf16 v[58:61], v[186:189], v[194:197], v[58:61]
	v_mfma_f32_16x16x32_bf16 v[46:49], v[142:145], v[198:201], v[46:49]
	v_mfma_f32_16x16x32_bf16 v[46:49], v[162:165], v[202:205], v[46:49]
	v_mfma_f32_16x16x32_bf16 v[42:45], v[182:185], v[198:201], v[42:45]
	v_mfma_f32_16x16x32_bf16 v[42:45], v[186:189], v[202:205], v[42:45]
	v_mfma_f32_16x16x32_bf16 v[30:33], v[142:145], v[206:209], v[30:33]
	v_mfma_f32_16x16x32_bf16 v[30:33], v[162:165], v[210:213], v[30:33]
	v_mfma_f32_16x16x32_bf16 v[26:29], v[182:185], v[206:209], v[26:29]
	v_mfma_f32_16x16x32_bf16 v[26:29], v[186:189], v[210:213], v[26:29]
	v_mfma_f32_16x16x32_bf16 v[14:17], v[142:145], v[214:217], v[14:17]
	v_mfma_f32_16x16x32_bf16 v[14:17], v[162:165], v[218:221], v[14:17]
	v_mfma_f32_16x16x32_bf16 v[10:13], v[182:185], v[214:217], v[10:13]
	s_barrier
	v_mfma_f32_16x16x32_bf16 v[10:13], v[186:189], v[218:221], v[10:13]
	s_setprio 0
	s_add_u32 s24, s48, 0x40080
	s_addc_u32 s25, s49, 0
	s_add_i32 s48, s60, s86
	s_mov_b32 m0, s48
	s_nop 0
	global_load_lds_dwordx4 v134, s[24:25]
	s_add_i32 m0, s48, 0x2000
	s_nop 0
	global_load_lds_dwordx4 v130, s[24:25]
	ds_read_b128 v[142:145], v249
	ds_read_b128 v[162:165], v249 offset:1024
	ds_read_b128 v[182:185], v249 offset:2048
	ds_read_b128 v[186:189], v249 offset:3072
	s_waitcnt vmcnt(6)
	s_barrier
	s_setprio 1
	v_mfma_f32_16x16x32_bf16 v[54:57], v[222:225], v[190:193], v[54:57]
	v_mfma_f32_16x16x32_bf16 v[54:57], v[226:229], v[194:197], v[54:57]
	v_mfma_f32_16x16x32_bf16 v[50:53], v[230:233], v[190:193], v[50:53]
	ds_read_b128 v[190:193], v169
	v_mfma_f32_16x16x32_bf16 v[50:53], v[234:237], v[194:197], v[50:53]
	ds_read_b128 v[194:197], v169 offset:1024
	v_mfma_f32_16x16x32_bf16 v[38:41], v[222:225], v[198:201], v[38:41]
	v_mfma_f32_16x16x32_bf16 v[38:41], v[226:229], v[202:205], v[38:41]
	v_mfma_f32_16x16x32_bf16 v[34:37], v[230:233], v[198:201], v[34:37]
	ds_read_b128 v[198:201], v169 offset:2048
	v_mfma_f32_16x16x32_bf16 v[34:37], v[234:237], v[202:205], v[34:37]
	ds_read_b128 v[202:205], v169 offset:3072
	v_mfma_f32_16x16x32_bf16 v[22:25], v[222:225], v[206:209], v[22:25]
	v_mfma_f32_16x16x32_bf16 v[22:25], v[226:229], v[210:213], v[22:25]
	v_mfma_f32_16x16x32_bf16 v[18:21], v[230:233], v[206:209], v[18:21]
	ds_read_b128 v[206:209], v169 offset:4096
	v_mfma_f32_16x16x32_bf16 v[18:21], v[234:237], v[210:213], v[18:21]
	ds_read_b128 v[210:213], v169 offset:5120
	v_mfma_f32_16x16x32_bf16 v[6:9], v[222:225], v[214:217], v[6:9]
	v_mfma_f32_16x16x32_bf16 v[6:9], v[226:229], v[218:221], v[6:9]
	v_mfma_f32_16x16x32_bf16 v[2:5], v[230:233], v[214:217], v[2:5]
	s_barrier
	v_mfma_f32_16x16x32_bf16 v[2:5], v[234:237], v[218:221], v[2:5]
	s_setprio 0
	s_add_i32 s50, s50, 2
	s_add_u32 vcc_lo, vcc_lo, 0x100
	s_addc_u32 s35, s35, 0
	s_add_u32 s38, s38, 0x100
	s_addc_u32 s39, s39, 0
	s_cmp_gt_u32 s50, 13
.LBB0_165:
	s_add_u32 s24, s38, 0xfffc0080
	s_addc_u32 s25, s39, -1
	s_add_i32 vcc_hi, 0, 0x10000
	s_cmp_eq_u32 s50, 12
	s_cselect_b32 s61, s34, s25
	s_cselect_b32 s60, s45, s24
	s_cselect_b32 s49, s43, s35
	s_cselect_b32 s48, s79, vcc_lo
	s_add_i32 m0, s93, 0xc000
	ds_read_b128 v[214:217], v169 offset:6144
	ds_read_b128 v[218:221], v169 offset:7168
	global_load_lds_dwordx4 v140, s[38:39]
	s_add_i32 m0, s93, 0xe000
	s_nop 0
	global_load_lds_dwordx4 v138, s[38:39]
	s_waitcnt lgkmcnt(8)
	s_barrier
	s_waitcnt lgkmcnt(0)
	s_setprio 1
	s_waitcnt lgkmcnt(0)
	v_mfma_f32_16x16x32_bf16 v[126:129], v[142:145], v[190:193], v[126:129]
	v_mfma_f32_16x16x32_bf16 v[126:129], v[162:165], v[194:197], v[126:129]
	v_mfma_f32_16x16x32_bf16 v[122:125], v[182:185], v[190:193], v[122:125]
	v_mfma_f32_16x16x32_bf16 v[122:125], v[186:189], v[194:197], v[122:125]
	v_mfma_f32_16x16x32_bf16 v[110:113], v[142:145], v[198:201], v[110:113]
	v_mfma_f32_16x16x32_bf16 v[110:113], v[162:165], v[202:205], v[110:113]
	v_mfma_f32_16x16x32_bf16 v[106:109], v[182:185], v[198:201], v[106:109]
	v_mfma_f32_16x16x32_bf16 v[106:109], v[186:189], v[202:205], v[106:109]
	v_mfma_f32_16x16x32_bf16 v[94:97], v[142:145], v[206:209], v[94:97]
	v_mfma_f32_16x16x32_bf16 v[94:97], v[162:165], v[210:213], v[94:97]
	v_mfma_f32_16x16x32_bf16 v[90:93], v[182:185], v[206:209], v[90:93]
	v_mfma_f32_16x16x32_bf16 v[90:93], v[186:189], v[210:213], v[90:93]
	v_mfma_f32_16x16x32_bf16 v[78:81], v[142:145], v[214:217], v[78:81]
	v_mfma_f32_16x16x32_bf16 v[78:81], v[162:165], v[218:221], v[78:81]
	v_mfma_f32_16x16x32_bf16 v[74:77], v[182:185], v[214:217], v[74:77]
	s_barrier
	v_mfma_f32_16x16x32_bf16 v[74:77], v[186:189], v[218:221], v[74:77]
	s_setprio 0
	s_add_i32 s51, 0, 0x14000
	s_add_i32 s24, vcc_hi, s86
	s_mov_b32 m0, s24
	ds_read_b128 v[222:225], v249 offset:16384
	ds_read_b128 v[226:229], v249 offset:17408
	ds_read_b128 v[230:233], v249 offset:18432
	ds_read_b128 v[234:237], v249 offset:19456
	global_load_lds_dwordx4 v134, s[48:49]
	s_add_i32 m0, s24, 0x2000
	s_nop 0
	global_load_lds_dwordx4 v130, s[48:49]
	s_barrier
; #define PG8_STAGE(bufoff, gbase, voff) do { _Pragma("unroll") for (int _i = 0; _i < 2; ++_i) \
;         __builtin_amdgcn_global_load_lds((const unsigned*)((const char*)(gbase) + (voff)[_i]), (LAS unsigned*)(lds + (bufoff) + ldsw + _i * 8192), 16, 0, 0); } while (0)
; #define PG8_LDA(dst, b, h) do { _Pragma("unroll") for (int m = 0; m < 4; ++m) _Pragma("unroll") for (int k = 0; k < 2; ++k) dst[m][k] = *(const LAS bf16x8*)(lds + PG8_SA(b, h) + aoff + m * 2048 + k * 1024); } while (0)
; #define PG8_LDB(dst, b, h) do { _Pragma("unroll") for (int n = 0; n < 2; ++n) _Pragma("unroll") for (int k = 0; k < 2; ++k) dst[n][k] = *(const LAS bf16x8*)(lds + PG8_SB(b, h) + boff + n * 2048 + k * 1024); } while (0)
; #define PG8_MMA(ai, bj, At, Bt) do { __builtin_amdgcn_s_setprio(1); _Pragma("unroll") for (int m = 0; m < 4; ++m) _Pragma("unroll") for (int n = 0; n < 2; ++n) _Pragma("unroll") for (int k = 0; k < 2; ++k) \
;         acc[ai][bj][m][n] = __builtin_amdgcn_mfma_f32_16x16x32_bf16(Bt[n][k], At[m][k], acc[ai][bj][m][n], 0, 0, 0); __builtin_amdgcn_s_setprio(0); } while (0)
; #define PG8_WAIT_V(n) asm volatile("s_waitcnt vmcnt(" #n ")" ::: "memory")
; #define PG8_WAIT_L(n) asm volatile("s_waitcnt lgkmcnt(" #n ")" ::: "memory")
; #define PG8_BAR __builtin_amdgcn_s_barrier()
; #define PG8_SCHED __builtin_amdgcn_sched_barrier(0)
; template <class Epi, class Sched>
; __device__ __forceinline__ void gemm_phase(LAS unsigned char* lds, const Gemm g, const Sched& S, const Epi& E) {
;     ...
;             PG8_BAR; PG8_WAIT_L(0); PG8_MMA(0, 1, At, B1); PG8_BAR;
;             PG8_LDA(At, 0, 1); PG8_STAGE(PG8_SA(0, 0), a2, voffA);
;             PG8_BAR; PG8_WAIT_L(0); PG8_MMA(1, 0, At, B0); PG8_BAR; PG8_SCHED;
;             PG8_STAGE(PG8_SB(0, 1), b2 + hstep, voffB);
;             PG8_WAIT_V(6); PG8_BAR; PG8_MMA(1, 1, At, B1); PG8_BAR;
;             PG8_LDB(B0, 1, 0); PG8_SCHED; PG8_LDA(At, 1, 0); PG8_STAGE(PG8_SA(0, 1), a2 + hstep, voffA);
;             PG8_WAIT_L(8); PG8_BAR; PG8_WAIT_L(0); PG8_MMA(0, 0, At, B0); PG8_BAR; PG8_SCHED;
	s_waitcnt lgkmcnt(0)
	s_setprio 1
	s_waitcnt lgkmcnt(0)
	v_mfma_f32_16x16x32_bf16 v[118:121], v[222:225], v[190:193], v[118:121]
	v_mfma_f32_16x16x32_bf16 v[118:121], v[226:229], v[194:197], v[118:121]
	v_mfma_f32_16x16x32_bf16 v[114:117], v[230:233], v[190:193], v[114:117]
	v_mfma_f32_16x16x32_bf16 v[114:117], v[234:237], v[194:197], v[114:117]
	v_mfma_f32_16x16x32_bf16 v[102:105], v[222:225], v[198:201], v[102:105]
	v_mfma_f32_16x16x32_bf16 v[102:105], v[226:229], v[202:205], v[102:105]
	v_mfma_f32_16x16x32_bf16 v[98:101], v[230:233], v[198:201], v[98:101]
	v_mfma_f32_16x16x32_bf16 v[98:101], v[234:237], v[202:205], v[98:101]
	v_mfma_f32_16x16x32_bf16 v[86:89], v[222:225], v[206:209], v[86:89]
	v_mfma_f32_16x16x32_bf16 v[86:89], v[226:229], v[210:213], v[86:89]
	v_mfma_f32_16x16x32_bf16 v[82:85], v[230:233], v[206:209], v[82:85]
	v_mfma_f32_16x16x32_bf16 v[82:85], v[234:237], v[210:213], v[82:85]
	v_mfma_f32_16x16x32_bf16 v[70:73], v[222:225], v[214:217], v[70:73]
	v_mfma_f32_16x16x32_bf16 v[70:73], v[226:229], v[218:221], v[70:73]
	v_mfma_f32_16x16x32_bf16 v[66:69], v[230:233], v[214:217], v[66:69]
	s_barrier
	v_mfma_f32_16x16x32_bf16 v[66:69], v[234:237], v[218:221], v[66:69]
	s_setprio 0
	s_mov_b32 m0, s93
	s_mov_b64 s[100:101], s[60:61]
	ds_read_b128 v[190:193], v169 offset:16384
	ds_read_b128 v[194:197], v169 offset:17408
	ds_read_b128 v[198:201], v169 offset:18432
	ds_read_b128 v[202:205], v169 offset:19456
	ds_read_b128 v[206:209], v169 offset:20480
	ds_read_b128 v[210:213], v169 offset:21504
	ds_read_b128 v[214:217], v169 offset:22528
	ds_read_b128 v[218:221], v169 offset:23552
	global_load_lds_dwordx4 v136, s[60:61]
	s_mov_b64 s[100:101], s[60:61]
	s_mov_b32 m0, s98
	s_nop 0
	global_load_lds_dwordx4 v132, s[60:61]
	s_waitcnt vmcnt(8)
	s_barrier
	s_waitcnt lgkmcnt(0)
	s_setprio 1
	s_waitcnt lgkmcnt(0)
	v_mfma_f32_16x16x32_bf16 v[62:65], v[142:145], v[190:193], v[62:65]
	v_mfma_f32_16x16x32_bf16 v[62:65], v[162:165], v[194:197], v[62:65]
	v_mfma_f32_16x16x32_bf16 v[58:61], v[182:185], v[190:193], v[58:61]
	v_mfma_f32_16x16x32_bf16 v[58:61], v[186:189], v[194:197], v[58:61]
	v_mfma_f32_16x16x32_bf16 v[46:49], v[142:145], v[198:201], v[46:49]
	v_mfma_f32_16x16x32_bf16 v[46:49], v[162:165], v[202:205], v[46:49]
	v_mfma_f32_16x16x32_bf16 v[42:45], v[182:185], v[198:201], v[42:45]
	v_mfma_f32_16x16x32_bf16 v[42:45], v[186:189], v[202:205], v[42:45]
	v_mfma_f32_16x16x32_bf16 v[30:33], v[142:145], v[206:209], v[30:33]
	v_mfma_f32_16x16x32_bf16 v[30:33], v[162:165], v[210:213], v[30:33]
	v_mfma_f32_16x16x32_bf16 v[26:29], v[182:185], v[206:209], v[26:29]
	v_mfma_f32_16x16x32_bf16 v[26:29], v[186:189], v[210:213], v[26:29]
	v_mfma_f32_16x16x32_bf16 v[14:17], v[142:145], v[214:217], v[14:17]
	v_mfma_f32_16x16x32_bf16 v[14:17], v[162:165], v[218:221], v[14:17]
	v_mfma_f32_16x16x32_bf16 v[10:13], v[182:185], v[214:217], v[10:13]
	s_barrier
	v_mfma_f32_16x16x32_bf16 v[10:13], v[186:189], v[218:221], v[10:13]
	s_setprio 0
	s_add_u32 s24, s48, 0x40000
	s_addc_u32 s25, s49, 0
	s_add_i32 s51, s51, s86
	s_mov_b32 m0, s51
	s_nop 0
	global_load_lds_dwordx4 v134, s[24:25]
	s_add_i32 m0, s51, 0x2000
	s_nop 0
	global_load_lds_dwordx4 v130, s[24:25]
	ds_read_b128 v[142:145], v249 offset:32768
	ds_read_b128 v[162:165], v249 offset:33792
	ds_read_b128 v[182:185], v249 offset:34816
	ds_read_b128 v[186:189], v249 offset:35840
	s_waitcnt vmcnt(6)
	s_barrier
	s_setprio 1
	v_mfma_f32_16x16x32_bf16 v[54:57], v[222:225], v[190:193], v[54:57]
	v_mfma_f32_16x16x32_bf16 v[54:57], v[226:229], v[194:197], v[54:57]
	v_mfma_f32_16x16x32_bf16 v[50:53], v[230:233], v[190:193], v[50:53]
	ds_read_b128 v[190:193], v169 offset:32768
	v_mfma_f32_16x16x32_bf16 v[50:53], v[234:237], v[194:197], v[50:53]
	ds_read_b128 v[194:197], v169 offset:33792
	v_mfma_f32_16x16x32_bf16 v[38:41], v[222:225], v[198:201], v[38:41]
	v_mfma_f32_16x16x32_bf16 v[38:41], v[226:229], v[202:205], v[38:41]
	v_mfma_f32_16x16x32_bf16 v[34:37], v[230:233], v[198:201], v[34:37]
	ds_read_b128 v[198:201], v169 offset:34816
	v_mfma_f32_16x16x32_bf16 v[34:37], v[234:237], v[202:205], v[34:37]
	ds_read_b128 v[202:205], v169 offset:35840
	v_mfma_f32_16x16x32_bf16 v[22:25], v[222:225], v[206:209], v[22:25]
	v_mfma_f32_16x16x32_bf16 v[22:25], v[226:229], v[210:213], v[22:25]
	v_mfma_f32_16x16x32_bf16 v[18:21], v[230:233], v[206:209], v[18:21]
	ds_read_b128 v[206:209], v169 offset:36864
	v_mfma_f32_16x16x32_bf16 v[18:21], v[234:237], v[210:213], v[18:21]
	ds_read_b128 v[210:213], v169 offset:37888
	v_mfma_f32_16x16x32_bf16 v[6:9], v[222:225], v[214:217], v[6:9]
	v_mfma_f32_16x16x32_bf16 v[6:9], v[226:229], v[218:221], v[6:9]
	v_mfma_f32_16x16x32_bf16 v[2:5], v[230:233], v[214:217], v[2:5]
	s_barrier
	v_mfma_f32_16x16x32_bf16 v[2:5], v[234:237], v[218:221], v[2:5]
	s_setprio 0
	s_add_i32 s51, 0, 0x18000
	s_add_u32 s24, s60, 0x40000
	s_addc_u32 s25, s61, 0
	s_mov_b32 m0, s99
	ds_read_b128 v[214:217], v169 offset:38912
	ds_read_b128 v[218:221], v169 offset:39936
	global_load_lds_dwordx4 v136, s[24:25]
	s_mov_b32 m0, s94
	s_nop 0
	global_load_lds_dwordx4 v132, s[24:25]
	s_waitcnt lgkmcnt(8)
	s_barrier
; #define PG8_STAGE(bufoff, gbase, voff) do { _Pragma("unroll") for (int _i = 0; _i < 2; ++_i) \
;         __builtin_amdgcn_global_load_lds((const unsigned*)((const char*)(gbase) + (voff)[_i]), (LAS unsigned*)(lds + (bufoff) + ldsw + _i * 8192), 16, 0, 0); } while (0)
; #define PG8_LDA(dst, b, h) do { _Pragma("unroll") for (int m = 0; m < 4; ++m) _Pragma("unroll") for (int k = 0; k < 2; ++k) dst[m][k] = *(const LAS bf16x8*)(lds + PG8_SA(b, h) + aoff + m * 2048 + k * 1024); } while (0)
; #define PG8_LDB(dst, b, h) do { _Pragma("unroll") for (int n = 0; n < 2; ++n) _Pragma("unroll") for (int k = 0; k < 2; ++k) dst[n][k] = *(const LAS bf16x8*)(lds + PG8_SB(b, h) + boff + n * 2048 + k * 1024); } while (0)
; #define PG8_MMA(ai, bj, At, Bt) do { __builtin_amdgcn_s_setprio(1); _Pragma("unroll") for (int m = 0; m < 4; ++m) _Pragma("unroll") for (int n = 0; n < 2; ++n) _Pragma("unroll") for (int k = 0; k < 2; ++k) \
;         acc[ai][bj][m][n] = __builtin_amdgcn_mfma_f32_16x16x32_bf16(Bt[n][k], At[m][k], acc[ai][bj][m][n], 0, 0, 0); __builtin_amdgcn_s_setprio(0); } while (0)
; #define PG8_WAIT_V(n) asm volatile("s_waitcnt vmcnt(" #n ")" ::: "memory")
; #define PG8_WAIT_L(n) asm volatile("s_waitcnt lgkmcnt(" #n ")" ::: "memory")
; #define PG8_BAR __builtin_amdgcn_s_barrier()
; #define PG8_SCHED __builtin_amdgcn_sched_barrier(0)
; template <class Epi, class Sched>
; __device__ __forceinline__ void gemm_phase(LAS unsigned char* lds, const Gemm g, const Sched& S, const Epi& E) {
;     ...
;             PG8_WAIT_L(8); PG8_BAR; PG8_WAIT_L(0); PG8_MMA(0, 0, At, B0); PG8_BAR; PG8_SCHED;
;             PG8_LDB(B1, 1, 1); PG8_STAGE(PG8_SB(1, 0), b3, voffB);
;             PG8_BAR; PG8_WAIT_L(0); PG8_MMA(0, 1, At, B1); PG8_BAR;
;             PG8_LDA(At, 1, 1); PG8_STAGE(PG8_SA(1, 0), a3, voffA);
;             PG8_BAR; PG8_WAIT_L(0); PG8_MMA(1, 0, At, B0); PG8_BAR; PG8_SCHED;
;             PG8_STAGE(PG8_SB(1, 1), b3 + hstep, voffB);
;             PG8_WAIT_V(6); PG8_BAR; PG8_MMA(1, 1, At, B1); PG8_BAR;
;         }
;         if (wr == 0) PG8_BAR;
	s_waitcnt lgkmcnt(0)
	s_setprio 1
	s_waitcnt lgkmcnt(0)
	v_mfma_f32_16x16x32_bf16 v[126:129], v[142:145], v[190:193], v[126:129]
	v_mfma_f32_16x16x32_bf16 v[126:129], v[162:165], v[194:197], v[126:129]
	v_mfma_f32_16x16x32_bf16 v[122:125], v[182:185], v[190:193], v[122:125]
	v_mfma_f32_16x16x32_bf16 v[122:125], v[186:189], v[194:197], v[122:125]
	v_mfma_f32_16x16x32_bf16 v[110:113], v[142:145], v[198:201], v[110:113]
	v_mfma_f32_16x16x32_bf16 v[110:113], v[162:165], v[202:205], v[110:113]
	v_mfma_f32_16x16x32_bf16 v[106:109], v[182:185], v[198:201], v[106:109]
	v_mfma_f32_16x16x32_bf16 v[106:109], v[186:189], v[202:205], v[106:109]
	v_mfma_f32_16x16x32_bf16 v[94:97], v[142:145], v[206:209], v[94:97]
	v_mfma_f32_16x16x32_bf16 v[94:97], v[162:165], v[210:213], v[94:97]
	v_mfma_f32_16x16x32_bf16 v[90:93], v[182:185], v[206:209], v[90:93]
	v_mfma_f32_16x16x32_bf16 v[90:93], v[186:189], v[210:213], v[90:93]
	v_mfma_f32_16x16x32_bf16 v[78:81], v[142:145], v[214:217], v[78:81]
	v_mfma_f32_16x16x32_bf16 v[78:81], v[162:165], v[218:221], v[78:81]
	v_mfma_f32_16x16x32_bf16 v[74:77], v[182:185], v[214:217], v[74:77]
	s_barrier
	v_mfma_f32_16x16x32_bf16 v[74:77], v[186:189], v[218:221], v[74:77]
	s_setprio 0
	s_add_i32 s60, 0, 0x1c000
	s_add_i32 s24, s51, s86
	s_add_i32 m0, s24, 0xffffff80
	ds_read_b128 v[222:225], v249 offset:49152
	ds_read_b128 v[226:229], v249 offset:50176
	ds_read_b128 v[230:233], v249 offset:51200
	ds_read_b128 v[234:237], v249 offset:52224
	global_load_lds_dwordx4 v134, s[48:49] offset:128
	s_add_i32 m0, s24, 0x1f80
	s_nop 0
	global_load_lds_dwordx4 v130, s[48:49] offset:128
	s_barrier
	s_waitcnt lgkmcnt(0)
	s_setprio 1
	s_waitcnt lgkmcnt(0)
	v_mfma_f32_16x16x32_bf16 v[118:121], v[222:225], v[190:193], v[118:121]
	v_mfma_f32_16x16x32_bf16 v[118:121], v[226:229], v[194:197], v[118:121]
	v_mfma_f32_16x16x32_bf16 v[114:117], v[230:233], v[190:193], v[114:117]
	v_mfma_f32_16x16x32_bf16 v[114:117], v[234:237], v[194:197], v[114:117]
	v_mfma_f32_16x16x32_bf16 v[102:105], v[222:225], v[198:201], v[102:105]
	v_mfma_f32_16x16x32_bf16 v[102:105], v[226:229], v[202:205], v[102:105]
	v_mfma_f32_16x16x32_bf16 v[98:101], v[230:233], v[198:201], v[98:101]
	v_mfma_f32_16x16x32_bf16 v[98:101], v[234:237], v[202:205], v[98:101]
	v_mfma_f32_16x16x32_bf16 v[86:89], v[222:225], v[206:209], v[86:89]
	v_mfma_f32_16x16x32_bf16 v[86:89], v[226:229], v[210:213], v[86:89]
	v_mfma_f32_16x16x32_bf16 v[82:85], v[230:233], v[206:209], v[82:85]
	v_mfma_f32_16x16x32_bf16 v[82:85], v[234:237], v[210:213], v[82:85]
	v_mfma_f32_16x16x32_bf16 v[70:73], v[222:225], v[214:217], v[70:73]
	v_mfma_f32_16x16x32_bf16 v[70:73], v[226:229], v[218:221], v[70:73]
	v_mfma_f32_16x16x32_bf16 v[66:69], v[230:233], v[214:217], v[66:69]
	s_barrier
	v_mfma_f32_16x16x32_bf16 v[66:69], v[234:237], v[218:221], v[66:69]
	s_setprio 0
	s_add_i32 m0, s95, 0xffffff80
	ds_read_b128 v[190:193], v169 offset:49152
	ds_read_b128 v[194:197], v169 offset:50176
	ds_read_b128 v[198:201], v169 offset:51200
	ds_read_b128 v[202:205], v169 offset:52224
	ds_read_b128 v[206:209], v169 offset:53248
	ds_read_b128 v[210:213], v169 offset:54272
	ds_read_b128 v[214:217], v169 offset:55296
	ds_read_b128 v[218:221], v169 offset:56320
	global_load_lds_dwordx4 v136, s[100:101] offset:128
	s_add_i32 m0, s96, 0xffffff80
	s_nop 0
	global_load_lds_dwordx4 v132, s[100:101] offset:128
	s_waitcnt vmcnt(8)
	s_barrier
	s_waitcnt lgkmcnt(0)
	s_setprio 1
	s_waitcnt lgkmcnt(0)
	v_mfma_f32_16x16x32_bf16 v[62:65], v[142:145], v[190:193], v[62:65]
	v_mfma_f32_16x16x32_bf16 v[62:65], v[162:165], v[194:197], v[62:65]
	v_mfma_f32_16x16x32_bf16 v[58:61], v[182:185], v[190:193], v[58:61]
	v_mfma_f32_16x16x32_bf16 v[58:61], v[186:189], v[194:197], v[58:61]
	v_mfma_f32_16x16x32_bf16 v[46:49], v[142:145], v[198:201], v[46:49]
	v_mfma_f32_16x16x32_bf16 v[46:49], v[162:165], v[202:205], v[46:49]
	v_mfma_f32_16x16x32_bf16 v[42:45], v[182:185], v[198:201], v[42:45]
	v_mfma_f32_16x16x32_bf16 v[42:45], v[186:189], v[202:205], v[42:45]
	v_mfma_f32_16x16x32_bf16 v[30:33], v[142:145], v[206:209], v[30:33]
	v_mfma_f32_16x16x32_bf16 v[30:33], v[162:165], v[210:213], v[30:33]
	v_mfma_f32_16x16x32_bf16 v[26:29], v[182:185], v[206:209], v[26:29]
	v_mfma_f32_16x16x32_bf16 v[26:29], v[186:189], v[210:213], v[26:29]
	v_mfma_f32_16x16x32_bf16 v[14:17], v[142:145], v[214:217], v[14:17]
	v_mfma_f32_16x16x32_bf16 v[14:17], v[162:165], v[218:221], v[14:17]
	v_mfma_f32_16x16x32_bf16 v[10:13], v[182:185], v[214:217], v[10:13]
	s_barrier
	v_mfma_f32_16x16x32_bf16 v[10:13], v[186:189], v[218:221], v[10:13]
	s_setprio 0
	s_add_u32 s24, s48, 0x40080
	s_addc_u32 s25, s49, 0
	s_add_i32 s48, s60, s86
	s_mov_b32 m0, s48
	s_nop 0
	global_load_lds_dwordx4 v134, s[24:25]
	s_add_i32 m0, s48, 0x2000
	s_nop 0
	global_load_lds_dwordx4 v130, s[24:25]
	ds_read_b128 v[142:145], v249
	ds_read_b128 v[162:165], v249 offset:1024
	ds_read_b128 v[182:185], v249 offset:2048
	ds_read_b128 v[186:189], v249 offset:3072
	s_waitcnt vmcnt(6)
	s_barrier
	s_setprio 1
	v_mfma_f32_16x16x32_bf16 v[54:57], v[222:225], v[190:193], v[54:57]
	v_mfma_f32_16x16x32_bf16 v[54:57], v[226:229], v[194:197], v[54:57]
	v_mfma_f32_16x16x32_bf16 v[50:53], v[230:233], v[190:193], v[50:53]
	ds_read_b128 v[190:193], v169
	v_mfma_f32_16x16x32_bf16 v[50:53], v[234:237], v[194:197], v[50:53]
	ds_read_b128 v[194:197], v169 offset:1024
	v_mfma_f32_16x16x32_bf16 v[38:41], v[222:225], v[198:201], v[38:41]
	v_mfma_f32_16x16x32_bf16 v[38:41], v[226:229], v[202:205], v[38:41]
	v_mfma_f32_16x16x32_bf16 v[34:37], v[230:233], v[198:201], v[34:37]
	ds_read_b128 v[198:201], v169 offset:2048
	v_mfma_f32_16x16x32_bf16 v[34:37], v[234:237], v[202:205], v[34:37]
	ds_read_b128 v[202:205], v169 offset:3072
	v_mfma_f32_16x16x32_bf16 v[22:25], v[222:225], v[206:209], v[22:25]
	v_mfma_f32_16x16x32_bf16 v[22:25], v[226:229], v[210:213], v[22:25]
	v_mfma_f32_16x16x32_bf16 v[18:21], v[230:233], v[206:209], v[18:21]
	ds_read_b128 v[206:209], v169 offset:4096
	v_mfma_f32_16x16x32_bf16 v[18:21], v[234:237], v[210:213], v[18:21]
	ds_read_b128 v[210:213], v169 offset:5120
	v_mfma_f32_16x16x32_bf16 v[6:9], v[222:225], v[214:217], v[6:9]
	v_mfma_f32_16x16x32_bf16 v[6:9], v[226:229], v[218:221], v[6:9]
	v_mfma_f32_16x16x32_bf16 v[2:5], v[230:233], v[214:217], v[2:5]
	s_barrier
	v_mfma_f32_16x16x32_bf16 v[2:5], v[234:237], v[218:221], v[2:5]
	s_setprio 0
	s_add_i32 s50, s50, 2
	s_add_u32 vcc_lo, vcc_lo, 0x100
	s_addc_u32 s35, s35, 0
	s_add_u32 s38, s38, 0x100
	s_addc_u32 s39, s39, 0
	s_cmp_gt_u32 s50, 13
	s_cbranch_scc0 .LBB0_165
	s_waitcnt lgkmcnt(0)
	s_and_b64 vcc, exec, s[40:41]
	s_cbranch_vccz .LBB0_168
	s_barrier

; #define PG8_STAGE(bufoff, gbase, voff) do { _Pragma("unroll") for (int _i = 0; _i < 2; ++_i) \
;         __builtin_amdgcn_global_load_lds((const unsigned*)((const char*)(gbase) + (voff)[_i]), (LAS unsigned*)(lds + (bufoff) + ldsw + _i * 8192), 16, 0, 0); } while (0)
; #define PG8_LDA(dst, b, h) do { _Pragma("unroll") for (int m = 0; m < 4; ++m) _Pragma("unroll") for (int k = 0; k < 2; ++k) dst[m][k] = *(const LAS bf16x8*)(lds + PG8_SA(b, h) + aoff + m * 2048 + k * 1024); } while (0)
; #define PG8_LDB(dst, b, h) do { _Pragma("unroll") for (int n = 0; n < 2; ++n) _Pragma("unroll") for (int k = 0; k < 2; ++k) dst[n][k] = *(const LAS bf16x8*)(lds + PG8_SB(b, h) + boff + n * 2048 + k * 1024); } while (0)
; #define PG8_MMA(ai, bj, At, Bt) do { __builtin_amdgcn_s_setprio(1); _Pragma("unroll") for (int m = 0; m < 4; ++m) _Pragma("unroll") for (int n = 0; n < 2; ++n) _Pragma("unroll") for (int k = 0; k < 2; ++k) \
;         acc[ai][bj][m][n] = __builtin_amdgcn_mfma_f32_16x16x32_bf16(Bt[n][k], At[m][k], acc[ai][bj][m][n], 0, 0, 0); __builtin_amdgcn_s_setprio(0); } while (0)
; #define PG8_WAIT_L(n) asm volatile("s_waitcnt lgkmcnt(" #n ")" ::: "memory")
; template <class Epi, class Sched>
; __device__ __forceinline__ void gemm_phase(LAS unsigned char* lds, const Gemm g, const Sched& S, const Epi& E) {
;     ...
;         const bool has_next = S.next(ui + 1, nxt);
;         const char* nA = has_next ? PG8_APANEL(nxt.pm) : cA; const char* nB = has_next ? (const char*)g.Bt + (size_t)nxt.pn * tstep : cB;
;         for (int t = 0; t < nt; t += 2) {
;             const bool last = (t == nt - 2);
;             const char* a1 = cA + (size_t)(t + 1) * kstep;
;             const char* a2 = last ? nA : cA + (size_t)(t + 2) * kstep; const char* b2 = last ? nB : cB + (size_t)(t + 2) * kstep;
;             const char* a3 = a2 + kstep; const char* b3 = b2 + kstep;
;             PG8_LDB(B0, 0, 0); PG8_SCHED; PG8_LDA(At, 0, 0); PG8_STAGE(PG8_SA(1, 1), a1 + hstep, voffA);
;             PG8_WAIT_L(8); PG8_BAR; PG8_WAIT_L(0); PG8_MMA(0, 0, At, B0); PG8_BAR; PG8_SCHED;
;             PG8_LDB(B1, 0, 1); PG8_STAGE(PG8_SB(0, 0), b2, voffB);
;             PG8_BAR; PG8_WAIT_L(0); PG8_MMA(0, 1, At, B1); PG8_BAR;
;             PG8_LDA(At, 0, 1); PG8_STAGE(PG8_SA(0, 0), a2, voffA);
;             PG8_BAR; PG8_WAIT_L(0); PG8_MMA(1, 0, At, B0); PG8_BAR; PG8_SCHED;
.LBB0_415:
	s_ashr_i32 s47, s46, 31
	s_lshl_b64 s[24:25], s[46:47], 19
	s_add_u32 s48, s82, s24
	s_addc_u32 s49, s83, s25
	s_and_b64 s[0:1], s[0:1], exec
	s_cselect_b32 s47, s49, s37
	s_cselect_b32 s61, s48, s36
	s_add_u32 s35, s36, 0x100
	s_addc_u32 s50, s37, 0
	s_add_u32 s0, s38, 0x40080
	s_addc_u32 s1, s39, 0
	s_mov_b32 s38, -2
	v_add_u32_e32 v249, 0x10000, v144
	ds_read_b128 v[164:167], v249
	ds_read_b128 v[182:185], v249 offset:1024
	ds_read_b128 v[186:189], v249 offset:2048
	ds_read_b128 v[190:193], v249 offset:3072
	ds_read_b128 v[194:197], v162
	ds_read_b128 v[198:201], v162 offset:1024
	ds_read_b128 v[202:205], v162 offset:2048
	ds_read_b128 v[206:209], v162 offset:3072
	ds_read_b128 v[210:213], v162 offset:4096
	ds_read_b128 v[214:217], v162 offset:5120
	s_add_u32 s24, s0, 0xfffc0080
	s_addc_u32 s25, s1, -1
	s_add_i32 s39, 0, 0x10000
	s_cmp_eq_u32 s38, 12
	s_cselect_b32 vcc_hi, s77, s25
	s_cselect_b32 vcc_lo, s76, s24
	s_cselect_b32 s37, s47, s50
	s_cselect_b32 s36, s61, s35
	s_add_i32 m0, s93, 0xc000
	ds_read_b128 v[218:221], v162 offset:6144
	ds_read_b128 v[222:225], v162 offset:7168
	global_load_lds_dwordx4 v140, s[0:1]
	s_add_i32 m0, s93, 0xe000
	s_nop 0
	global_load_lds_dwordx4 v138, s[0:1]
	s_waitcnt lgkmcnt(8)
	s_barrier
	s_waitcnt lgkmcnt(0)
	s_setprio 1
	s_waitcnt lgkmcnt(0)
	v_mfma_f32_16x16x32_bf16 v[126:129], v[164:167], v[194:197], 0
	v_mfma_f32_16x16x32_bf16 v[126:129], v[182:185], v[198:201], v[126:129]
	v_mfma_f32_16x16x32_bf16 v[122:125], v[186:189], v[194:197], 0
	v_mfma_f32_16x16x32_bf16 v[122:125], v[190:193], v[198:201], v[122:125]
	v_mfma_f32_16x16x32_bf16 v[118:121], v[164:167], v[202:205], 0
	v_mfma_f32_16x16x32_bf16 v[118:121], v[182:185], v[206:209], v[118:121]
	v_mfma_f32_16x16x32_bf16 v[110:113], v[186:189], v[202:205], 0
	v_mfma_f32_16x16x32_bf16 v[110:113], v[190:193], v[206:209], v[110:113]
	v_mfma_f32_16x16x32_bf16 v[102:105], v[164:167], v[210:213], 0
	v_mfma_f32_16x16x32_bf16 v[102:105], v[182:185], v[214:217], v[102:105]
	v_mfma_f32_16x16x32_bf16 v[94:97], v[186:189], v[210:213], 0
	v_mfma_f32_16x16x32_bf16 v[94:97], v[190:193], v[214:217], v[94:97]
	v_mfma_f32_16x16x32_bf16 v[86:89], v[164:167], v[218:221], 0
	v_mfma_f32_16x16x32_bf16 v[86:89], v[182:185], v[222:225], v[86:89]
	v_mfma_f32_16x16x32_bf16 v[78:81], v[186:189], v[218:221], 0
	s_barrier
	v_mfma_f32_16x16x32_bf16 v[78:81], v[190:193], v[222:225], v[78:81]
	s_setprio 0
	s_add_i32 s51, 0, 0x14000
	s_add_i32 s24, s39, s86
	ds_read_b128 v[226:229], v249 offset:16384
	ds_read_b128 v[230:233], v249 offset:17408
	ds_read_b128 v[234:237], v249 offset:18432
	ds_read_b128 v[238:241], v249 offset:19456
	s_mov_b32 m0, s24
	global_load_lds_dwordx4 v134, s[36:37]
	s_add_i32 m0, s24, 0x2000
	s_nop 0
	global_load_lds_dwordx4 v130, s[36:37]
	s_barrier
	s_waitcnt lgkmcnt(0)
	s_setprio 1
	s_waitcnt lgkmcnt(0)
	v_mfma_f32_16x16x32_bf16 v[114:117], v[226:229], v[194:197], 0
	v_mfma_f32_16x16x32_bf16 v[114:117], v[230:233], v[198:201], v[114:117]
	v_mfma_f32_16x16x32_bf16 v[106:109], v[234:237], v[194:197], 0
	v_mfma_f32_16x16x32_bf16 v[106:109], v[238:241], v[198:201], v[106:109]
	v_mfma_f32_16x16x32_bf16 v[98:101], v[226:229], v[202:205], 0
	v_mfma_f32_16x16x32_bf16 v[98:101], v[230:233], v[206:209], v[98:101]
	v_mfma_f32_16x16x32_bf16 v[90:93], v[234:237], v[202:205], 0
	v_mfma_f32_16x16x32_bf16 v[90:93], v[238:241], v[206:209], v[90:93]
	v_mfma_f32_16x16x32_bf16 v[82:85], v[226:229], v[210:213], 0
	v_mfma_f32_16x16x32_bf16 v[82:85], v[230:233], v[214:217], v[82:85]
	v_mfma_f32_16x16x32_bf16 v[74:77], v[234:237], v[210:213], 0
	v_mfma_f32_16x16x32_bf16 v[74:77], v[238:241], v[214:217], v[74:77]
	v_mfma_f32_16x16x32_bf16 v[70:73], v[226:229], v[218:221], 0
	v_mfma_f32_16x16x32_bf16 v[70:73], v[230:233], v[222:225], v[70:73]
	v_mfma_f32_16x16x32_bf16 v[66:69], v[234:237], v[218:221], 0
	s_barrier
	v_mfma_f32_16x16x32_bf16 v[66:69], v[238:241], v[222:225], v[66:69]
	s_setprio 0
	s_mov_b32 m0, s93
	ds_read_b128 v[194:197], v162 offset:16384
	ds_read_b128 v[198:201], v162 offset:17408
	ds_read_b128 v[202:205], v162 offset:18432
	ds_read_b128 v[206:209], v162 offset:19456
	ds_read_b128 v[210:213], v162 offset:20480
	ds_read_b128 v[214:217], v162 offset:21504
	ds_read_b128 v[218:221], v162 offset:22528
	ds_read_b128 v[222:225], v162 offset:23552
	global_load_lds_dwordx4 v136, vcc
	s_mov_b32 m0, s94
	s_nop 0
	global_load_lds_dwordx4 v132, vcc
	s_waitcnt vmcnt(8)
	s_barrier
	s_waitcnt lgkmcnt(0)
	s_setprio 1
	s_waitcnt lgkmcnt(0)
	v_mfma_f32_16x16x32_bf16 v[62:65], v[164:167], v[194:197], 0
	v_mfma_f32_16x16x32_bf16 v[62:65], v[182:185], v[198:201], v[62:65]
	v_mfma_f32_16x16x32_bf16 v[58:61], v[186:189], v[194:197], 0
	v_mfma_f32_16x16x32_bf16 v[58:61], v[190:193], v[198:201], v[58:61]
	v_mfma_f32_16x16x32_bf16 v[54:57], v[164:167], v[202:205], 0
	v_mfma_f32_16x16x32_bf16 v[54:57], v[182:185], v[206:209], v[54:57]
	v_mfma_f32_16x16x32_bf16 v[46:49], v[186:189], v[202:205], 0
	v_mfma_f32_16x16x32_bf16 v[46:49], v[190:193], v[206:209], v[46:49]
	v_mfma_f32_16x16x32_bf16 v[38:41], v[164:167], v[210:213], 0
	v_mfma_f32_16x16x32_bf16 v[38:41], v[182:185], v[214:217], v[38:41]
	v_mfma_f32_16x16x32_bf16 v[30:33], v[186:189], v[210:213], 0
	v_mfma_f32_16x16x32_bf16 v[30:33], v[190:193], v[214:217], v[30:33]
	v_mfma_f32_16x16x32_bf16 v[22:25], v[164:167], v[218:221], 0
	v_mfma_f32_16x16x32_bf16 v[22:25], v[182:185], v[222:225], v[22:25]
	v_mfma_f32_16x16x32_bf16 v[14:17], v[186:189], v[218:221], 0
	s_barrier
; #define PG8_STAGE(bufoff, gbase, voff) do { _Pragma("unroll") for (int _i = 0; _i < 2; ++_i) \
;         __builtin_amdgcn_global_load_lds((const unsigned*)((const char*)(gbase) + (voff)[_i]), (LAS unsigned*)(lds + (bufoff) + ldsw + _i * 8192), 16, 0, 0); } while (0)
; #define PG8_LDA(dst, b, h) do { _Pragma("unroll") for (int m = 0; m < 4; ++m) _Pragma("unroll") for (int k = 0; k < 2; ++k) dst[m][k] = *(const LAS bf16x8*)(lds + PG8_SA(b, h) + aoff + m * 2048 + k * 1024); } while (0)
; #define PG8_LDB(dst, b, h) do { _Pragma("unroll") for (int n = 0; n < 2; ++n) _Pragma("unroll") for (int k = 0; k < 2; ++k) dst[n][k] = *(const LAS bf16x8*)(lds + PG8_SB(b, h) + boff + n * 2048 + k * 1024); } while (0)
; #define PG8_MMA(ai, bj, At, Bt) do { __builtin_amdgcn_s_setprio(1); _Pragma("unroll") for (int m = 0; m < 4; ++m) _Pragma("unroll") for (int n = 0; n < 2; ++n) _Pragma("unroll") for (int k = 0; k < 2; ++k) \
;         acc[ai][bj][m][n] = __builtin_amdgcn_mfma_f32_16x16x32_bf16(Bt[n][k], At[m][k], acc[ai][bj][m][n], 0, 0, 0); __builtin_amdgcn_s_setprio(0); } while (0)
; #define PG8_WAIT_V(n) asm volatile("s_waitcnt vmcnt(" #n ")" ::: "memory")
; #define PG8_WAIT_L(n) asm volatile("s_waitcnt lgkmcnt(" #n ")" ::: "memory")
; #define PG8_BAR __builtin_amdgcn_s_barrier()
; #define PG8_SCHED __builtin_amdgcn_sched_barrier(0)
; template <class Epi, class Sched>
; __device__ __forceinline__ void gemm_phase(LAS unsigned char* lds, const Gemm g, const Sched& S, const Epi& E) {
;     ...
;             PG8_STAGE(PG8_SB(0, 1), b2 + hstep, voffB);
;             PG8_WAIT_V(6); PG8_BAR; PG8_MMA(1, 1, At, B1); PG8_BAR;
;             PG8_LDB(B0, 1, 0); PG8_SCHED; PG8_LDA(At, 1, 0); PG8_STAGE(PG8_SA(0, 1), a2 + hstep, voffA);
;             PG8_WAIT_L(8); PG8_BAR; PG8_WAIT_L(0); PG8_MMA(0, 0, At, B0); PG8_BAR; PG8_SCHED;
;             PG8_LDB(B1, 1, 1); PG8_STAGE(PG8_SB(1, 0), b3, voffB);
;             PG8_BAR; PG8_WAIT_L(0); PG8_MMA(0, 1, At, B1); PG8_BAR;
;             PG8_LDA(At, 1, 1); PG8_STAGE(PG8_SA(1, 0), a3, voffA);
;             PG8_BAR; PG8_WAIT_L(0); PG8_MMA(1, 0, At, B0); PG8_BAR; PG8_SCHED;
	v_mfma_f32_16x16x32_bf16 v[14:17], v[190:193], v[222:225], v[14:17]
	s_setprio 0
	s_add_u32 s24, s36, 0x40000
	s_addc_u32 s25, s37, 0
	s_add_i32 s39, s51, s86
	s_mov_b32 m0, s39
	s_nop 0
	global_load_lds_dwordx4 v134, s[24:25]
	s_add_i32 m0, s39, 0x2000
	s_nop 0
	global_load_lds_dwordx4 v130, s[24:25]
	ds_read_b128 v[164:167], v249 offset:32768
	ds_read_b128 v[182:185], v249 offset:33792
	ds_read_b128 v[186:189], v249 offset:34816
	ds_read_b128 v[190:193], v249 offset:35840
	s_waitcnt vmcnt(6)
	s_barrier
	s_setprio 1
	v_mfma_f32_16x16x32_bf16 v[50:53], v[226:229], v[194:197], 0
	v_mfma_f32_16x16x32_bf16 v[50:53], v[230:233], v[198:201], v[50:53]
	v_mfma_f32_16x16x32_bf16 v[42:45], v[234:237], v[194:197], 0
	ds_read_b128 v[194:197], v162 offset:32768
	v_mfma_f32_16x16x32_bf16 v[42:45], v[238:241], v[198:201], v[42:45]
	ds_read_b128 v[198:201], v162 offset:33792
	v_mfma_f32_16x16x32_bf16 v[34:37], v[226:229], v[202:205], 0
	v_mfma_f32_16x16x32_bf16 v[34:37], v[230:233], v[206:209], v[34:37]
	v_mfma_f32_16x16x32_bf16 v[26:29], v[234:237], v[202:205], 0
	ds_read_b128 v[202:205], v162 offset:34816
	v_mfma_f32_16x16x32_bf16 v[26:29], v[238:241], v[206:209], v[26:29]
	ds_read_b128 v[206:209], v162 offset:35840
	v_mfma_f32_16x16x32_bf16 v[18:21], v[226:229], v[210:213], 0
	v_mfma_f32_16x16x32_bf16 v[18:21], v[230:233], v[214:217], v[18:21]
	v_mfma_f32_16x16x32_bf16 v[10:13], v[234:237], v[210:213], 0
	ds_read_b128 v[210:213], v162 offset:36864
	v_mfma_f32_16x16x32_bf16 v[10:13], v[238:241], v[214:217], v[10:13]
	ds_read_b128 v[214:217], v162 offset:37888
	v_mfma_f32_16x16x32_bf16 v[6:9], v[226:229], v[218:221], 0
	v_mfma_f32_16x16x32_bf16 v[6:9], v[230:233], v[222:225], v[6:9]
	v_mfma_f32_16x16x32_bf16 v[2:5], v[234:237], v[218:221], 0
	s_barrier
	v_mfma_f32_16x16x32_bf16 v[2:5], v[238:241], v[222:225], v[2:5]
	s_setprio 0
	s_add_i32 s39, 0, 0x18000
	s_add_u32 s24, vcc_lo, 0x40000
	s_addc_u32 s25, vcc_hi, 0
	s_mov_b32 m0, s95
	ds_read_b128 v[218:221], v162 offset:38912
	ds_read_b128 v[222:225], v162 offset:39936
	global_load_lds_dwordx4 v136, s[24:25]
	s_mov_b32 m0, s96
	s_nop 0
	global_load_lds_dwordx4 v132, s[24:25]
	s_waitcnt lgkmcnt(8)
	s_barrier
	s_waitcnt lgkmcnt(0)
	s_setprio 1
	s_waitcnt lgkmcnt(0)
	v_mfma_f32_16x16x32_bf16 v[126:129], v[164:167], v[194:197], v[126:129]
	v_mfma_f32_16x16x32_bf16 v[126:129], v[182:185], v[198:201], v[126:129]
	v_mfma_f32_16x16x32_bf16 v[122:125], v[186:189], v[194:197], v[122:125]
	v_mfma_f32_16x16x32_bf16 v[122:125], v[190:193], v[198:201], v[122:125]
	v_mfma_f32_16x16x32_bf16 v[118:121], v[164:167], v[202:205], v[118:121]
	v_mfma_f32_16x16x32_bf16 v[118:121], v[182:185], v[206:209], v[118:121]
	v_mfma_f32_16x16x32_bf16 v[110:113], v[186:189], v[202:205], v[110:113]
	v_mfma_f32_16x16x32_bf16 v[110:113], v[190:193], v[206:209], v[110:113]
	v_mfma_f32_16x16x32_bf16 v[102:105], v[164:167], v[210:213], v[102:105]
	v_mfma_f32_16x16x32_bf16 v[102:105], v[182:185], v[214:217], v[102:105]
	v_mfma_f32_16x16x32_bf16 v[94:97], v[186:189], v[210:213], v[94:97]
	v_mfma_f32_16x16x32_bf16 v[94:97], v[190:193], v[214:217], v[94:97]
	v_mfma_f32_16x16x32_bf16 v[86:89], v[164:167], v[218:221], v[86:89]
	v_mfma_f32_16x16x32_bf16 v[86:89], v[182:185], v[222:225], v[86:89]
	v_mfma_f32_16x16x32_bf16 v[78:81], v[186:189], v[218:221], v[78:81]
	s_barrier
	v_mfma_f32_16x16x32_bf16 v[78:81], v[190:193], v[222:225], v[78:81]
	s_setprio 0
	s_add_i32 s51, 0, 0x1c000
	s_add_i32 s24, s39, s86
	s_add_i32 m0, s24, 0xffffff80
	ds_read_b128 v[226:229], v249 offset:49152
	ds_read_b128 v[230:233], v249 offset:50176
	ds_read_b128 v[234:237], v249 offset:51200
	ds_read_b128 v[238:241], v249 offset:52224
	global_load_lds_dwordx4 v134, s[36:37] offset:128
	s_add_i32 m0, s24, 0x1f80
	s_nop 0
	global_load_lds_dwordx4 v130, s[36:37] offset:128
	s_barrier
	s_waitcnt lgkmcnt(0)
	s_setprio 1
	s_waitcnt lgkmcnt(0)
	v_mfma_f32_16x16x32_bf16 v[114:117], v[226:229], v[194:197], v[114:117]
	v_mfma_f32_16x16x32_bf16 v[114:117], v[230:233], v[198:201], v[114:117]
	v_mfma_f32_16x16x32_bf16 v[106:109], v[234:237], v[194:197], v[106:109]
	v_mfma_f32_16x16x32_bf16 v[106:109], v[238:241], v[198:201], v[106:109]
	v_mfma_f32_16x16x32_bf16 v[98:101], v[226:229], v[202:205], v[98:101]
	v_mfma_f32_16x16x32_bf16 v[98:101], v[230:233], v[206:209], v[98:101]
	v_mfma_f32_16x16x32_bf16 v[90:93], v[234:237], v[202:205], v[90:93]
	v_mfma_f32_16x16x32_bf16 v[90:93], v[238:241], v[206:209], v[90:93]
	v_mfma_f32_16x16x32_bf16 v[82:85], v[226:229], v[210:213], v[82:85]
	v_mfma_f32_16x16x32_bf16 v[82:85], v[230:233], v[214:217], v[82:85]
	v_mfma_f32_16x16x32_bf16 v[74:77], v[234:237], v[210:213], v[74:77]
	v_mfma_f32_16x16x32_bf16 v[74:77], v[238:241], v[214:217], v[74:77]
	v_mfma_f32_16x16x32_bf16 v[70:73], v[226:229], v[218:221], v[70:73]
	v_mfma_f32_16x16x32_bf16 v[70:73], v[230:233], v[222:225], v[70:73]
	v_mfma_f32_16x16x32_bf16 v[66:69], v[234:237], v[218:221], v[66:69]
	s_barrier
	v_mfma_f32_16x16x32_bf16 v[66:69], v[238:241], v[222:225], v[66:69]
	s_setprio 0
	s_add_i32 m0, s97, 0xffffff80
	ds_read_b128 v[194:197], v162 offset:49152
	ds_read_b128 v[198:201], v162 offset:50176
	ds_read_b128 v[202:205], v162 offset:51200
	ds_read_b128 v[206:209], v162 offset:52224
	ds_read_b128 v[210:213], v162 offset:53248
	ds_read_b128 v[214:217], v162 offset:54272
	ds_read_b128 v[218:221], v162 offset:55296
	ds_read_b128 v[222:225], v162 offset:56320
	global_load_lds_dwordx4 v136, vcc offset:128
	s_add_i32 m0, s98, 0xffffff80
	s_nop 0
	global_load_lds_dwordx4 v132, vcc offset:128
	s_waitcnt vmcnt(8)
	s_barrier
; #define PG8_STAGE(bufoff, gbase, voff) do { _Pragma("unroll") for (int _i = 0; _i < 2; ++_i) \
;         __builtin_amdgcn_global_load_lds((const unsigned*)((const char*)(gbase) + (voff)[_i]), (LAS unsigned*)(lds + (bufoff) + ldsw + _i * 8192), 16, 0, 0); } while (0)
; #define PG8_LDA(dst, b, h) do { _Pragma("unroll") for (int m = 0; m < 4; ++m) _Pragma("unroll") for (int k = 0; k < 2; ++k) dst[m][k] = *(const LAS bf16x8*)(lds + PG8_SA(b, h) + aoff + m * 2048 + k * 1024); } while (0)
; #define PG8_LDB(dst, b, h) do { _Pragma("unroll") for (int n = 0; n < 2; ++n) _Pragma("unroll") for (int k = 0; k < 2; ++k) dst[n][k] = *(const LAS bf16x8*)(lds + PG8_SB(b, h) + boff + n * 2048 + k * 1024); } while (0)
; #define PG8_MMA(ai, bj, At, Bt) do { __builtin_amdgcn_s_setprio(1); _Pragma("unroll") for (int m = 0; m < 4; ++m) _Pragma("unroll") for (int n = 0; n < 2; ++n) _Pragma("unroll") for (int k = 0; k < 2; ++k) \
;         acc[ai][bj][m][n] = __builtin_amdgcn_mfma_f32_16x16x32_bf16(Bt[n][k], At[m][k], acc[ai][bj][m][n], 0, 0, 0); __builtin_amdgcn_s_setprio(0); } while (0)
; #define PG8_WAIT_V(n) asm volatile("s_waitcnt vmcnt(" #n ")" ::: "memory")
; #define PG8_WAIT_L(n) asm volatile("s_waitcnt lgkmcnt(" #n ")" ::: "memory")
; #define PG8_BAR __builtin_amdgcn_s_barrier()
; #define PG8_SCHED __builtin_amdgcn_sched_barrier(0)
; template <class Epi, class Sched>
; __device__ __forceinline__ void gemm_phase(LAS unsigned char* lds, const Gemm g, const Sched& S, const Epi& E) {
;     ...
;         for (int t = 0; t < nt; t += 2) {
;             const bool last = (t == nt - 2);
;             const char* a1 = cA + (size_t)(t + 1) * kstep;
;             const char* a2 = last ? nA : cA + (size_t)(t + 2) * kstep; const char* b2 = last ? nB : cB + (size_t)(t + 2) * kstep;
;             const char* a3 = a2 + kstep; const char* b3 = b2 + kstep;
;             PG8_LDB(B0, 0, 0); PG8_SCHED; PG8_LDA(At, 0, 0); PG8_STAGE(PG8_SA(1, 1), a1 + hstep, voffA);
;             PG8_WAIT_L(8); PG8_BAR; PG8_WAIT_L(0); PG8_MMA(0, 0, At, B0); PG8_BAR; PG8_SCHED;
;             PG8_LDB(B1, 0, 1); PG8_STAGE(PG8_SB(0, 0), b2, voffB);
;             PG8_BAR; PG8_WAIT_L(0); PG8_MMA(0, 1, At, B1); PG8_BAR;
;     ...
;             PG8_BAR; PG8_WAIT_L(0); PG8_MMA(1, 0, At, B0); PG8_BAR; PG8_SCHED;
;             PG8_STAGE(PG8_SB(1, 1), b3 + hstep, voffB);
;             PG8_WAIT_V(6); PG8_BAR; PG8_MMA(1, 1, At, B1); PG8_BAR;
	s_waitcnt lgkmcnt(0)
	s_setprio 1
	s_waitcnt lgkmcnt(0)
	v_mfma_f32_16x16x32_bf16 v[62:65], v[164:167], v[194:197], v[62:65]
	v_mfma_f32_16x16x32_bf16 v[62:65], v[182:185], v[198:201], v[62:65]
	v_mfma_f32_16x16x32_bf16 v[58:61], v[186:189], v[194:197], v[58:61]
	v_mfma_f32_16x16x32_bf16 v[58:61], v[190:193], v[198:201], v[58:61]
	v_mfma_f32_16x16x32_bf16 v[54:57], v[164:167], v[202:205], v[54:57]
	v_mfma_f32_16x16x32_bf16 v[54:57], v[182:185], v[206:209], v[54:57]
	v_mfma_f32_16x16x32_bf16 v[46:49], v[186:189], v[202:205], v[46:49]
	v_mfma_f32_16x16x32_bf16 v[46:49], v[190:193], v[206:209], v[46:49]
	v_mfma_f32_16x16x32_bf16 v[38:41], v[164:167], v[210:213], v[38:41]
	v_mfma_f32_16x16x32_bf16 v[38:41], v[182:185], v[214:217], v[38:41]
	v_mfma_f32_16x16x32_bf16 v[30:33], v[186:189], v[210:213], v[30:33]
	v_mfma_f32_16x16x32_bf16 v[30:33], v[190:193], v[214:217], v[30:33]
	v_mfma_f32_16x16x32_bf16 v[22:25], v[164:167], v[218:221], v[22:25]
	v_mfma_f32_16x16x32_bf16 v[22:25], v[182:185], v[222:225], v[22:25]
	v_mfma_f32_16x16x32_bf16 v[14:17], v[186:189], v[218:221], v[14:17]
	s_barrier
	v_mfma_f32_16x16x32_bf16 v[14:17], v[190:193], v[222:225], v[14:17]
	s_setprio 0
	s_add_u32 s24, s36, 0x40080
	s_addc_u32 s25, s37, 0
	s_add_i32 s36, s51, s86
	s_mov_b32 m0, s36
	s_nop 0
	global_load_lds_dwordx4 v134, s[24:25]
	s_add_i32 m0, s36, 0x2000
	s_nop 0
	global_load_lds_dwordx4 v130, s[24:25]
	ds_read_b128 v[164:167], v249
	ds_read_b128 v[182:185], v249 offset:1024
	ds_read_b128 v[186:189], v249 offset:2048
	ds_read_b128 v[190:193], v249 offset:3072
	s_waitcnt vmcnt(6)
	s_barrier
	s_setprio 1
	v_mfma_f32_16x16x32_bf16 v[50:53], v[226:229], v[194:197], v[50:53]
	v_mfma_f32_16x16x32_bf16 v[50:53], v[230:233], v[198:201], v[50:53]
	v_mfma_f32_16x16x32_bf16 v[42:45], v[234:237], v[194:197], v[42:45]
	ds_read_b128 v[194:197], v162
	v_mfma_f32_16x16x32_bf16 v[42:45], v[238:241], v[198:201], v[42:45]
	ds_read_b128 v[198:201], v162 offset:1024
	v_mfma_f32_16x16x32_bf16 v[34:37], v[226:229], v[202:205], v[34:37]
	v_mfma_f32_16x16x32_bf16 v[34:37], v[230:233], v[206:209], v[34:37]
	v_mfma_f32_16x16x32_bf16 v[26:29], v[234:237], v[202:205], v[26:29]
	ds_read_b128 v[202:205], v162 offset:2048
	v_mfma_f32_16x16x32_bf16 v[26:29], v[238:241], v[206:209], v[26:29]
	ds_read_b128 v[206:209], v162 offset:3072
	v_mfma_f32_16x16x32_bf16 v[18:21], v[226:229], v[210:213], v[18:21]
	v_mfma_f32_16x16x32_bf16 v[18:21], v[230:233], v[214:217], v[18:21]
	v_mfma_f32_16x16x32_bf16 v[10:13], v[234:237], v[210:213], v[10:13]
	ds_read_b128 v[210:213], v162 offset:4096
	v_mfma_f32_16x16x32_bf16 v[10:13], v[238:241], v[214:217], v[10:13]
	ds_read_b128 v[214:217], v162 offset:5120
	v_mfma_f32_16x16x32_bf16 v[6:9], v[226:229], v[218:221], v[6:9]
	v_mfma_f32_16x16x32_bf16 v[6:9], v[230:233], v[222:225], v[6:9]
	v_mfma_f32_16x16x32_bf16 v[2:5], v[234:237], v[218:221], v[2:5]
	s_barrier
	v_mfma_f32_16x16x32_bf16 v[2:5], v[238:241], v[222:225], v[2:5]
	s_setprio 0
	s_add_i32 s38, s38, 2
	s_add_u32 s35, s35, 0x100
	s_addc_u32 s50, s50, 0
	s_add_u32 s0, s0, 0x100
	s_addc_u32 s1, s1, 0
	s_cmp_gt_u32 s38, 13
.LBB0_416:
	s_add_u32 s24, s0, 0xfffc0080
	s_addc_u32 s25, s1, -1
	s_add_i32 s39, 0, 0x10000
	s_cmp_eq_u32 s38, 12
	s_cselect_b32 vcc_hi, s77, s25
	s_cselect_b32 vcc_lo, s76, s24
	s_cselect_b32 s37, s47, s50
	s_cselect_b32 s36, s61, s35
	s_add_i32 m0, s93, 0xc000
	ds_read_b128 v[218:221], v162 offset:6144
	ds_read_b128 v[222:225], v162 offset:7168
	global_load_lds_dwordx4 v140, s[0:1]
	s_add_i32 m0, s93, 0xe000
	s_nop 0
	global_load_lds_dwordx4 v138, s[0:1]
	s_waitcnt lgkmcnt(8)
	s_barrier
	s_waitcnt lgkmcnt(0)
	s_setprio 1
	s_waitcnt lgkmcnt(0)
	v_mfma_f32_16x16x32_bf16 v[126:129], v[164:167], v[194:197], v[126:129]
	v_mfma_f32_16x16x32_bf16 v[126:129], v[182:185], v[198:201], v[126:129]
	v_mfma_f32_16x16x32_bf16 v[122:125], v[186:189], v[194:197], v[122:125]
	v_mfma_f32_16x16x32_bf16 v[122:125], v[190:193], v[198:201], v[122:125]
	v_mfma_f32_16x16x32_bf16 v[118:121], v[164:167], v[202:205], v[118:121]
	v_mfma_f32_16x16x32_bf16 v[118:121], v[182:185], v[206:209], v[118:121]
	v_mfma_f32_16x16x32_bf16 v[110:113], v[186:189], v[202:205], v[110:113]
	v_mfma_f32_16x16x32_bf16 v[110:113], v[190:193], v[206:209], v[110:113]
	v_mfma_f32_16x16x32_bf16 v[102:105], v[164:167], v[210:213], v[102:105]
	v_mfma_f32_16x16x32_bf16 v[102:105], v[182:185], v[214:217], v[102:105]
	v_mfma_f32_16x16x32_bf16 v[94:97], v[186:189], v[210:213], v[94:97]
	v_mfma_f32_16x16x32_bf16 v[94:97], v[190:193], v[214:217], v[94:97]
	v_mfma_f32_16x16x32_bf16 v[86:89], v[164:167], v[218:221], v[86:89]
	v_mfma_f32_16x16x32_bf16 v[86:89], v[182:185], v[222:225], v[86:89]
	v_mfma_f32_16x16x32_bf16 v[78:81], v[186:189], v[218:221], v[78:81]
	s_barrier
	v_mfma_f32_16x16x32_bf16 v[78:81], v[190:193], v[222:225], v[78:81]
	s_setprio 0
	s_add_i32 s51, 0, 0x14000
	s_add_i32 s24, s39, s86
	ds_read_b128 v[226:229], v249 offset:16384
	ds_read_b128 v[230:233], v249 offset:17408
	ds_read_b128 v[234:237], v249 offset:18432
	ds_read_b128 v[238:241], v249 offset:19456
	s_mov_b32 m0, s24
	global_load_lds_dwordx4 v134, s[36:37]
	s_add_i32 m0, s24, 0x2000
	s_nop 0
	global_load_lds_dwordx4 v130, s[36:37]
	s_barrier
; #define PG8_STAGE(bufoff, gbase, voff) do { _Pragma("unroll") for (int _i = 0; _i < 2; ++_i) \
;         __builtin_amdgcn_global_load_lds((const unsigned*)((const char*)(gbase) + (voff)[_i]), (LAS unsigned*)(lds + (bufoff) + ldsw + _i * 8192), 16, 0, 0); } while (0)
; #define PG8_LDA(dst, b, h) do { _Pragma("unroll") for (int m = 0; m < 4; ++m) _Pragma("unroll") for (int k = 0; k < 2; ++k) dst[m][k] = *(const LAS bf16x8*)(lds + PG8_SA(b, h) + aoff + m * 2048 + k * 1024); } while (0)
; #define PG8_LDB(dst, b, h) do { _Pragma("unroll") for (int n = 0; n < 2; ++n) _Pragma("unroll") for (int k = 0; k < 2; ++k) dst[n][k] = *(const LAS bf16x8*)(lds + PG8_SB(b, h) + boff + n * 2048 + k * 1024); } while (0)
; #define PG8_MMA(ai, bj, At, Bt) do { __builtin_amdgcn_s_setprio(1); _Pragma("unroll") for (int m = 0; m < 4; ++m) _Pragma("unroll") for (int n = 0; n < 2; ++n) _Pragma("unroll") for (int k = 0; k < 2; ++k) \
;         acc[ai][bj][m][n] = __builtin_amdgcn_mfma_f32_16x16x32_bf16(Bt[n][k], At[m][k], acc[ai][bj][m][n], 0, 0, 0); __builtin_amdgcn_s_setprio(0); } while (0)
; #define PG8_WAIT_V(n) asm volatile("s_waitcnt vmcnt(" #n ")" ::: "memory")
; #define PG8_WAIT_L(n) asm volatile("s_waitcnt lgkmcnt(" #n ")" ::: "memory")
; #define PG8_BAR __builtin_amdgcn_s_barrier()
; #define PG8_SCHED __builtin_amdgcn_sched_barrier(0)
; template <class Epi, class Sched>
; __device__ __forceinline__ void gemm_phase(LAS unsigned char* lds, const Gemm g, const Sched& S, const Epi& E) {
;     ...
;             PG8_BAR; PG8_WAIT_L(0); PG8_MMA(0, 1, At, B1); PG8_BAR;
;             PG8_LDA(At, 0, 1); PG8_STAGE(PG8_SA(0, 0), a2, voffA);
;             PG8_BAR; PG8_WAIT_L(0); PG8_MMA(1, 0, At, B0); PG8_BAR; PG8_SCHED;
;             PG8_STAGE(PG8_SB(0, 1), b2 + hstep, voffB);
;             PG8_WAIT_V(6); PG8_BAR; PG8_MMA(1, 1, At, B1); PG8_BAR;
;             PG8_LDB(B0, 1, 0); PG8_SCHED; PG8_LDA(At, 1, 0); PG8_STAGE(PG8_SA(0, 1), a2 + hstep, voffA);
;             PG8_WAIT_L(8); PG8_BAR; PG8_WAIT_L(0); PG8_MMA(0, 0, At, B0); PG8_BAR; PG8_SCHED;
	s_waitcnt lgkmcnt(0)
	s_setprio 1
	s_waitcnt lgkmcnt(0)
	v_mfma_f32_16x16x32_bf16 v[114:117], v[226:229], v[194:197], v[114:117]
	v_mfma_f32_16x16x32_bf16 v[114:117], v[230:233], v[198:201], v[114:117]
	v_mfma_f32_16x16x32_bf16 v[106:109], v[234:237], v[194:197], v[106:109]
	v_mfma_f32_16x16x32_bf16 v[106:109], v[238:241], v[198:201], v[106:109]
	v_mfma_f32_16x16x32_bf16 v[98:101], v[226:229], v[202:205], v[98:101]
	v_mfma_f32_16x16x32_bf16 v[98:101], v[230:233], v[206:209], v[98:101]
	v_mfma_f32_16x16x32_bf16 v[90:93], v[234:237], v[202:205], v[90:93]
	v_mfma_f32_16x16x32_bf16 v[90:93], v[238:241], v[206:209], v[90:93]
	v_mfma_f32_16x16x32_bf16 v[82:85], v[226:229], v[210:213], v[82:85]
	v_mfma_f32_16x16x32_bf16 v[82:85], v[230:233], v[214:217], v[82:85]
	v_mfma_f32_16x16x32_bf16 v[74:77], v[234:237], v[210:213], v[74:77]
	v_mfma_f32_16x16x32_bf16 v[74:77], v[238:241], v[214:217], v[74:77]
	v_mfma_f32_16x16x32_bf16 v[70:73], v[226:229], v[218:221], v[70:73]
	v_mfma_f32_16x16x32_bf16 v[70:73], v[230:233], v[222:225], v[70:73]
	v_mfma_f32_16x16x32_bf16 v[66:69], v[234:237], v[218:221], v[66:69]
	s_barrier
	v_mfma_f32_16x16x32_bf16 v[66:69], v[238:241], v[222:225], v[66:69]
	s_setprio 0
	s_mov_b32 m0, s93
	ds_read_b128 v[194:197], v162 offset:16384
	ds_read_b128 v[198:201], v162 offset:17408
	ds_read_b128 v[202:205], v162 offset:18432
	ds_read_b128 v[206:209], v162 offset:19456
	ds_read_b128 v[210:213], v162 offset:20480
	ds_read_b128 v[214:217], v162 offset:21504
	ds_read_b128 v[218:221], v162 offset:22528
	ds_read_b128 v[222:225], v162 offset:23552
	global_load_lds_dwordx4 v136, vcc
	s_mov_b32 m0, s94
	s_nop 0
	global_load_lds_dwordx4 v132, vcc
	s_waitcnt vmcnt(8)
	s_barrier
	s_waitcnt lgkmcnt(0)
	s_setprio 1
	s_waitcnt lgkmcnt(0)
	v_mfma_f32_16x16x32_bf16 v[62:65], v[164:167], v[194:197], v[62:65]
	v_mfma_f32_16x16x32_bf16 v[62:65], v[182:185], v[198:201], v[62:65]
	v_mfma_f32_16x16x32_bf16 v[58:61], v[186:189], v[194:197], v[58:61]
	v_mfma_f32_16x16x32_bf16 v[58:61], v[190:193], v[198:201], v[58:61]
	v_mfma_f32_16x16x32_bf16 v[54:57], v[164:167], v[202:205], v[54:57]
	v_mfma_f32_16x16x32_bf16 v[54:57], v[182:185], v[206:209], v[54:57]
	v_mfma_f32_16x16x32_bf16 v[46:49], v[186:189], v[202:205], v[46:49]
	v_mfma_f32_16x16x32_bf16 v[46:49], v[190:193], v[206:209], v[46:49]
	v_mfma_f32_16x16x32_bf16 v[38:41], v[164:167], v[210:213], v[38:41]
	v_mfma_f32_16x16x32_bf16 v[38:41], v[182:185], v[214:217], v[38:41]
	v_mfma_f32_16x16x32_bf16 v[30:33], v[186:189], v[210:213], v[30:33]
	v_mfma_f32_16x16x32_bf16 v[30:33], v[190:193], v[214:217], v[30:33]
	v_mfma_f32_16x16x32_bf16 v[22:25], v[164:167], v[218:221], v[22:25]
	v_mfma_f32_16x16x32_bf16 v[22:25], v[182:185], v[222:225], v[22:25]
	v_mfma_f32_16x16x32_bf16 v[14:17], v[186:189], v[218:221], v[14:17]
	s_barrier
	v_mfma_f32_16x16x32_bf16 v[14:17], v[190:193], v[222:225], v[14:17]
	s_setprio 0
	s_add_u32 s24, s36, 0x40000
	s_addc_u32 s25, s37, 0
	s_add_i32 s39, s51, s86
	s_mov_b32 m0, s39
	s_nop 0
	global_load_lds_dwordx4 v134, s[24:25]
	s_add_i32 m0, s39, 0x2000
	s_nop 0
	global_load_lds_dwordx4 v130, s[24:25]
	ds_read_b128 v[164:167], v249 offset:32768
	ds_read_b128 v[182:185], v249 offset:33792
	ds_read_b128 v[186:189], v249 offset:34816
	ds_read_b128 v[190:193], v249 offset:35840
	s_waitcnt vmcnt(6)
	s_barrier
	s_setprio 1
	v_mfma_f32_16x16x32_bf16 v[50:53], v[226:229], v[194:197], v[50:53]
	v_mfma_f32_16x16x32_bf16 v[50:53], v[230:233], v[198:201], v[50:53]
	v_mfma_f32_16x16x32_bf16 v[42:45], v[234:237], v[194:197], v[42:45]
	ds_read_b128 v[194:197], v162 offset:32768
	v_mfma_f32_16x16x32_bf16 v[42:45], v[238:241], v[198:201], v[42:45]
	ds_read_b128 v[198:201], v162 offset:33792
	v_mfma_f32_16x16x32_bf16 v[34:37], v[226:229], v[202:205], v[34:37]
	v_mfma_f32_16x16x32_bf16 v[34:37], v[230:233], v[206:209], v[34:37]
	v_mfma_f32_16x16x32_bf16 v[26:29], v[234:237], v[202:205], v[26:29]
	ds_read_b128 v[202:205], v162 offset:34816
	v_mfma_f32_16x16x32_bf16 v[26:29], v[238:241], v[206:209], v[26:29]
	ds_read_b128 v[206:209], v162 offset:35840
	v_mfma_f32_16x16x32_bf16 v[18:21], v[226:229], v[210:213], v[18:21]
	v_mfma_f32_16x16x32_bf16 v[18:21], v[230:233], v[214:217], v[18:21]
	v_mfma_f32_16x16x32_bf16 v[10:13], v[234:237], v[210:213], v[10:13]
	ds_read_b128 v[210:213], v162 offset:36864
	v_mfma_f32_16x16x32_bf16 v[10:13], v[238:241], v[214:217], v[10:13]
	ds_read_b128 v[214:217], v162 offset:37888
	v_mfma_f32_16x16x32_bf16 v[6:9], v[226:229], v[218:221], v[6:9]
	v_mfma_f32_16x16x32_bf16 v[6:9], v[230:233], v[222:225], v[6:9]
	v_mfma_f32_16x16x32_bf16 v[2:5], v[234:237], v[218:221], v[2:5]
	s_barrier
	v_mfma_f32_16x16x32_bf16 v[2:5], v[238:241], v[222:225], v[2:5]
	s_setprio 0
	s_add_i32 s39, 0, 0x18000
	s_add_u32 s24, vcc_lo, 0x40000
	s_addc_u32 s25, vcc_hi, 0
	s_mov_b32 m0, s95
	ds_read_b128 v[218:221], v162 offset:38912
	ds_read_b128 v[222:225], v162 offset:39936
	global_load_lds_dwordx4 v136, s[24:25]
	s_mov_b32 m0, s96
	s_nop 0
	global_load_lds_dwordx4 v132, s[24:25]
	s_waitcnt lgkmcnt(8)
	s_barrier
	s_waitcnt lgkmcnt(0)
	s_setprio 1
	s_waitcnt lgkmcnt(0)
	v_mfma_f32_16x16x32_bf16 v[126:129], v[164:167], v[194:197], v[126:129]
	v_mfma_f32_16x16x32_bf16 v[126:129], v[182:185], v[198:201], v[126:129]
	v_mfma_f32_16x16x32_bf16 v[122:125], v[186:189], v[194:197], v[122:125]
	v_mfma_f32_16x16x32_bf16 v[122:125], v[190:193], v[198:201], v[122:125]
	v_mfma_f32_16x16x32_bf16 v[118:121], v[164:167], v[202:205], v[118:121]
	v_mfma_f32_16x16x32_bf16 v[118:121], v[182:185], v[206:209], v[118:121]
	v_mfma_f32_16x16x32_bf16 v[110:113], v[186:189], v[202:205], v[110:113]
	v_mfma_f32_16x16x32_bf16 v[110:113], v[190:193], v[206:209], v[110:113]
	v_mfma_f32_16x16x32_bf16 v[102:105], v[164:167], v[210:213], v[102:105]
	v_mfma_f32_16x16x32_bf16 v[102:105], v[182:185], v[214:217], v[102:105]
	v_mfma_f32_16x16x32_bf16 v[94:97], v[186:189], v[210:213], v[94:97]
	v_mfma_f32_16x16x32_bf16 v[94:97], v[190:193], v[214:217], v[94:97]
	v_mfma_f32_16x16x32_bf16 v[86:89], v[164:167], v[218:221], v[86:89]
	v_mfma_f32_16x16x32_bf16 v[86:89], v[182:185], v[222:225], v[86:89]
	v_mfma_f32_16x16x32_bf16 v[78:81], v[186:189], v[218:221], v[78:81]
	s_barrier
; #define PG8_STAGE(bufoff, gbase, voff) do { _Pragma("unroll") for (int _i = 0; _i < 2; ++_i) \
;         __builtin_amdgcn_global_load_lds((const unsigned*)((const char*)(gbase) + (voff)[_i]), (LAS unsigned*)(lds + (bufoff) + ldsw + _i * 8192), 16, 0, 0); } while (0)
; #define PG8_LDA(dst, b, h) do { _Pragma("unroll") for (int m = 0; m < 4; ++m) _Pragma("unroll") for (int k = 0; k < 2; ++k) dst[m][k] = *(const LAS bf16x8*)(lds + PG8_SA(b, h) + aoff + m * 2048 + k * 1024); } while (0)
; #define PG8_LDB(dst, b, h) do { _Pragma("unroll") for (int n = 0; n < 2; ++n) _Pragma("unroll") for (int k = 0; k < 2; ++k) dst[n][k] = *(const LAS bf16x8*)(lds + PG8_SB(b, h) + boff + n * 2048 + k * 1024); } while (0)
; #define PG8_MMA(ai, bj, At, Bt) do { __builtin_amdgcn_s_setprio(1); _Pragma("unroll") for (int m = 0; m < 4; ++m) _Pragma("unroll") for (int n = 0; n < 2; ++n) _Pragma("unroll") for (int k = 0; k < 2; ++k) \
;         acc[ai][bj][m][n] = __builtin_amdgcn_mfma_f32_16x16x32_bf16(Bt[n][k], At[m][k], acc[ai][bj][m][n], 0, 0, 0); __builtin_amdgcn_s_setprio(0); } while (0)
; #define PG8_WAIT_V(n) asm volatile("s_waitcnt vmcnt(" #n ")" ::: "memory")
; #define PG8_WAIT_L(n) asm volatile("s_waitcnt lgkmcnt(" #n ")" ::: "memory")
; #define PG8_BAR __builtin_amdgcn_s_barrier()
; #define PG8_SCHED __builtin_amdgcn_sched_barrier(0)
; template <class Epi, class Sched>
; __device__ __forceinline__ void gemm_phase(LAS unsigned char* lds, const Gemm g, const Sched& S, const Epi& E) {
;     ...
;             PG8_LDB(B1, 1, 1); PG8_STAGE(PG8_SB(1, 0), b3, voffB);
;             PG8_BAR; PG8_WAIT_L(0); PG8_MMA(0, 1, At, B1); PG8_BAR;
;             PG8_LDA(At, 1, 1); PG8_STAGE(PG8_SA(1, 0), a3, voffA);
;             PG8_BAR; PG8_WAIT_L(0); PG8_MMA(1, 0, At, B0); PG8_BAR; PG8_SCHED;
;             PG8_STAGE(PG8_SB(1, 1), b3 + hstep, voffB);
;             PG8_WAIT_V(6); PG8_BAR; PG8_MMA(1, 1, At, B1); PG8_BAR;
;         }
;         if (wr == 0) PG8_BAR;
	v_mfma_f32_16x16x32_bf16 v[78:81], v[190:193], v[222:225], v[78:81]
	s_setprio 0
	s_add_i32 s51, 0, 0x1c000
	s_add_i32 s24, s39, s86
	s_add_i32 m0, s24, 0xffffff80
	ds_read_b128 v[226:229], v249 offset:49152
	ds_read_b128 v[230:233], v249 offset:50176
	ds_read_b128 v[234:237], v249 offset:51200
	ds_read_b128 v[238:241], v249 offset:52224
	global_load_lds_dwordx4 v134, s[36:37] offset:128
	s_add_i32 m0, s24, 0x1f80
	s_nop 0
	global_load_lds_dwordx4 v130, s[36:37] offset:128
	s_barrier
	s_waitcnt lgkmcnt(0)
	s_setprio 1
	s_waitcnt lgkmcnt(0)
	v_mfma_f32_16x16x32_bf16 v[114:117], v[226:229], v[194:197], v[114:117]
	v_mfma_f32_16x16x32_bf16 v[114:117], v[230:233], v[198:201], v[114:117]
	v_mfma_f32_16x16x32_bf16 v[106:109], v[234:237], v[194:197], v[106:109]
	v_mfma_f32_16x16x32_bf16 v[106:109], v[238:241], v[198:201], v[106:109]
	v_mfma_f32_16x16x32_bf16 v[98:101], v[226:229], v[202:205], v[98:101]
	v_mfma_f32_16x16x32_bf16 v[98:101], v[230:233], v[206:209], v[98:101]
	v_mfma_f32_16x16x32_bf16 v[90:93], v[234:237], v[202:205], v[90:93]
	v_mfma_f32_16x16x32_bf16 v[90:93], v[238:241], v[206:209], v[90:93]
	v_mfma_f32_16x16x32_bf16 v[82:85], v[226:229], v[210:213], v[82:85]
	v_mfma_f32_16x16x32_bf16 v[82:85], v[230:233], v[214:217], v[82:85]
	v_mfma_f32_16x16x32_bf16 v[74:77], v[234:237], v[210:213], v[74:77]
	v_mfma_f32_16x16x32_bf16 v[74:77], v[238:241], v[214:217], v[74:77]
	v_mfma_f32_16x16x32_bf16 v[70:73], v[226:229], v[218:221], v[70:73]
	v_mfma_f32_16x16x32_bf16 v[70:73], v[230:233], v[222:225], v[70:73]
	v_mfma_f32_16x16x32_bf16 v[66:69], v[234:237], v[218:221], v[66:69]
	s_barrier
	v_mfma_f32_16x16x32_bf16 v[66:69], v[238:241], v[222:225], v[66:69]
	s_setprio 0
	s_add_i32 m0, s97, 0xffffff80
	ds_read_b128 v[194:197], v162 offset:49152
	ds_read_b128 v[198:201], v162 offset:50176
	ds_read_b128 v[202:205], v162 offset:51200
	ds_read_b128 v[206:209], v162 offset:52224
	ds_read_b128 v[210:213], v162 offset:53248
	ds_read_b128 v[214:217], v162 offset:54272
	ds_read_b128 v[218:221], v162 offset:55296
	ds_read_b128 v[222:225], v162 offset:56320
	global_load_lds_dwordx4 v136, vcc offset:128
	s_add_i32 m0, s98, 0xffffff80
	s_nop 0
	global_load_lds_dwordx4 v132, vcc offset:128
	s_waitcnt vmcnt(8)
	s_barrier
	s_waitcnt lgkmcnt(0)
	s_setprio 1
	s_waitcnt lgkmcnt(0)
	v_mfma_f32_16x16x32_bf16 v[62:65], v[164:167], v[194:197], v[62:65]
	v_mfma_f32_16x16x32_bf16 v[62:65], v[182:185], v[198:201], v[62:65]
	v_mfma_f32_16x16x32_bf16 v[58:61], v[186:189], v[194:197], v[58:61]
	v_mfma_f32_16x16x32_bf16 v[58:61], v[190:193], v[198:201], v[58:61]
	v_mfma_f32_16x16x32_bf16 v[54:57], v[164:167], v[202:205], v[54:57]
	v_mfma_f32_16x16x32_bf16 v[54:57], v[182:185], v[206:209], v[54:57]
	v_mfma_f32_16x16x32_bf16 v[46:49], v[186:189], v[202:205], v[46:49]
	v_mfma_f32_16x16x32_bf16 v[46:49], v[190:193], v[206:209], v[46:49]
	v_mfma_f32_16x16x32_bf16 v[38:41], v[164:167], v[210:213], v[38:41]
	v_mfma_f32_16x16x32_bf16 v[38:41], v[182:185], v[214:217], v[38:41]
	v_mfma_f32_16x16x32_bf16 v[30:33], v[186:189], v[210:213], v[30:33]
	v_mfma_f32_16x16x32_bf16 v[30:33], v[190:193], v[214:217], v[30:33]
	v_mfma_f32_16x16x32_bf16 v[22:25], v[164:167], v[218:221], v[22:25]
	v_mfma_f32_16x16x32_bf16 v[22:25], v[182:185], v[222:225], v[22:25]
	v_mfma_f32_16x16x32_bf16 v[14:17], v[186:189], v[218:221], v[14:17]
	s_barrier
	v_mfma_f32_16x16x32_bf16 v[14:17], v[190:193], v[222:225], v[14:17]
	s_setprio 0
	s_add_u32 s24, s36, 0x40080
	s_addc_u32 s25, s37, 0
	s_add_i32 s36, s51, s86
	s_mov_b32 m0, s36
	s_nop 0
	global_load_lds_dwordx4 v134, s[24:25]
	s_add_i32 m0, s36, 0x2000
	s_nop 0
	global_load_lds_dwordx4 v130, s[24:25]
	ds_read_b128 v[164:167], v249
	ds_read_b128 v[182:185], v249 offset:1024
	ds_read_b128 v[186:189], v249 offset:2048
	ds_read_b128 v[190:193], v249 offset:3072
	s_waitcnt vmcnt(6)
	s_barrier
	s_setprio 1
	v_mfma_f32_16x16x32_bf16 v[50:53], v[226:229], v[194:197], v[50:53]
	v_mfma_f32_16x16x32_bf16 v[50:53], v[230:233], v[198:201], v[50:53]
	v_mfma_f32_16x16x32_bf16 v[42:45], v[234:237], v[194:197], v[42:45]
	ds_read_b128 v[194:197], v162
	v_mfma_f32_16x16x32_bf16 v[42:45], v[238:241], v[198:201], v[42:45]
	ds_read_b128 v[198:201], v162 offset:1024
	v_mfma_f32_16x16x32_bf16 v[34:37], v[226:229], v[202:205], v[34:37]
	v_mfma_f32_16x16x32_bf16 v[34:37], v[230:233], v[206:209], v[34:37]
	v_mfma_f32_16x16x32_bf16 v[26:29], v[234:237], v[202:205], v[26:29]
	ds_read_b128 v[202:205], v162 offset:2048
	v_mfma_f32_16x16x32_bf16 v[26:29], v[238:241], v[206:209], v[26:29]
	ds_read_b128 v[206:209], v162 offset:3072
	v_mfma_f32_16x16x32_bf16 v[18:21], v[226:229], v[210:213], v[18:21]
	v_mfma_f32_16x16x32_bf16 v[18:21], v[230:233], v[214:217], v[18:21]
	v_mfma_f32_16x16x32_bf16 v[10:13], v[234:237], v[210:213], v[10:13]
	ds_read_b128 v[210:213], v162 offset:4096
	v_mfma_f32_16x16x32_bf16 v[10:13], v[238:241], v[214:217], v[10:13]
	ds_read_b128 v[214:217], v162 offset:5120
	v_mfma_f32_16x16x32_bf16 v[6:9], v[226:229], v[218:221], v[6:9]
	v_mfma_f32_16x16x32_bf16 v[6:9], v[230:233], v[222:225], v[6:9]
	v_mfma_f32_16x16x32_bf16 v[2:5], v[234:237], v[218:221], v[2:5]
	s_barrier
	v_mfma_f32_16x16x32_bf16 v[2:5], v[238:241], v[222:225], v[2:5]
	s_setprio 0
	s_add_i32 s38, s38, 2
	s_add_u32 s35, s35, 0x100
	s_addc_u32 s50, s50, 0
	s_add_u32 s0, s0, 0x100
	s_addc_u32 s1, s1, 0
	s_cmp_gt_u32 s38, 13
	s_cbranch_scc0 .LBB0_416
	s_waitcnt lgkmcnt(0)
	s_and_b64 vcc, exec, s[44:45]
	s_cbranch_vccz .LBB0_419
	s_barrier

; #define PG8_STAGE(bufoff, gbase, voff) do { _Pragma("unroll") for (int _i = 0; _i < 2; ++_i) \
;         __builtin_amdgcn_global_load_lds((const unsigned*)((const char*)(gbase) + (voff)[_i]), (LAS unsigned*)(lds + (bufoff) + ldsw + _i * 8192), 16, 0, 0); } while (0)
; #define PG8_LDA(dst, b, h) do { _Pragma("unroll") for (int m = 0; m < 4; ++m) _Pragma("unroll") for (int k = 0; k < 2; ++k) dst[m][k] = *(const LAS bf16x8*)(lds + PG8_SA(b, h) + aoff + m * 2048 + k * 1024); } while (0)
; #define PG8_LDB(dst, b, h) do { _Pragma("unroll") for (int n = 0; n < 2; ++n) _Pragma("unroll") for (int k = 0; k < 2; ++k) dst[n][k] = *(const LAS bf16x8*)(lds + PG8_SB(b, h) + boff + n * 2048 + k * 1024); } while (0)
; #define PG8_MMA(ai, bj, At, Bt) do { __builtin_amdgcn_s_setprio(1); _Pragma("unroll") for (int m = 0; m < 4; ++m) _Pragma("unroll") for (int n = 0; n < 2; ++n) _Pragma("unroll") for (int k = 0; k < 2; ++k) \
;         acc[ai][bj][m][n] = __builtin_amdgcn_mfma_f32_16x16x32_bf16(Bt[n][k], At[m][k], acc[ai][bj][m][n], 0, 0, 0); __builtin_amdgcn_s_setprio(0); } while (0)
; #define PG8_WAIT_L(n) asm volatile("s_waitcnt lgkmcnt(" #n ")" ::: "memory")
; template <class Epi, class Sched>
; __device__ __forceinline__ void gemm_phase(LAS unsigned char* lds, const Gemm g, const Sched& S, const Epi& E) {
;     ...
;         const bool has_next = S.next(ui + 1, nxt);
;         const char* nA = has_next ? PG8_APANEL(nxt.pm) : cA; const char* nB = has_next ? (const char*)g.Bt + (size_t)nxt.pn * tstep : cB;
;         for (int t = 0; t < nt; t += 2) {
;             const bool last = (t == nt - 2);
;             const char* a1 = cA + (size_t)(t + 1) * kstep;
;             const char* a2 = last ? nA : cA + (size_t)(t + 2) * kstep; const char* b2 = last ? nB : cB + (size_t)(t + 2) * kstep;
;             const char* a3 = a2 + kstep; const char* b3 = b2 + kstep;
;             PG8_LDB(B0, 0, 0); PG8_SCHED; PG8_LDA(At, 0, 0); PG8_STAGE(PG8_SA(1, 1), a1 + hstep, voffA);
;             PG8_WAIT_L(8); PG8_BAR; PG8_WAIT_L(0); PG8_MMA(0, 0, At, B0); PG8_BAR; PG8_SCHED;
;             PG8_LDB(B1, 0, 1); PG8_STAGE(PG8_SB(0, 0), b2, voffB);
;             PG8_BAR; PG8_WAIT_L(0); PG8_MMA(0, 1, At, B1); PG8_BAR;
;             PG8_LDA(At, 0, 1); PG8_STAGE(PG8_SA(0, 0), a2, voffA);
;             PG8_BAR; PG8_WAIT_L(0); PG8_MMA(1, 0, At, B0); PG8_BAR; PG8_SCHED;
.LBB0_556:
	s_ashr_i32 s45, s44, 31
	s_lshl_b64 s[24:25], s[44:45], 19
	s_add_u32 s60, s86, s24
	s_addc_u32 s61, s93, s25
	s_and_b64 s[0:1], s[0:1], exec
	s_cselect_b32 s45, s61, s49
	s_cselect_b32 s47, s60, s48
	s_add_u32 s35, s48, 0x100
	s_addc_u32 s50, s49, 0
	s_add_u32 s0, s38, 0x40080
	s_addc_u32 s1, s39, 0
	s_mov_b32 s38, -2
	v_add_u32_e32 v249, 0x10000, v164
	ds_read_b128 v[142:145], v249
	ds_read_b128 v[182:185], v249 offset:1024
	ds_read_b128 v[186:189], v249 offset:2048
	ds_read_b128 v[190:193], v249 offset:3072
	ds_read_b128 v[194:197], v166
	ds_read_b128 v[198:201], v166 offset:1024
	ds_read_b128 v[202:205], v166 offset:2048
	ds_read_b128 v[206:209], v166 offset:3072
	ds_read_b128 v[210:213], v166 offset:4096
	ds_read_b128 v[214:217], v166 offset:5120
	s_add_u32 s24, s0, 0xfffc0080
	s_addc_u32 s25, s1, -1
	s_add_i32 s39, 0, 0x10000
	s_cmp_eq_u32 s38, 12
	s_cselect_b32 vcc_hi, s77, s25
	s_cselect_b32 vcc_lo, s76, s24
	s_cselect_b32 s49, s45, s50
	s_cselect_b32 s48, s47, s35
	s_add_i32 m0, s95, 0xc000
	ds_read_b128 v[218:221], v166 offset:6144
	ds_read_b128 v[222:225], v166 offset:7168
	global_load_lds_dwordx4 v140, s[0:1]
	s_add_i32 m0, s95, 0xe000
	s_nop 0
	global_load_lds_dwordx4 v138, s[0:1]
	s_waitcnt lgkmcnt(8)
	s_barrier
	s_waitcnt lgkmcnt(0)
	s_setprio 1
	s_waitcnt lgkmcnt(0)
	v_mfma_f32_16x16x32_bf16 v[126:129], v[142:145], v[194:197], 0
	v_mfma_f32_16x16x32_bf16 v[126:129], v[182:185], v[198:201], v[126:129]
	v_mfma_f32_16x16x32_bf16 v[122:125], v[186:189], v[194:197], 0
	v_mfma_f32_16x16x32_bf16 v[122:125], v[190:193], v[198:201], v[122:125]
	v_mfma_f32_16x16x32_bf16 v[110:113], v[142:145], v[202:205], 0
	v_mfma_f32_16x16x32_bf16 v[110:113], v[182:185], v[206:209], v[110:113]
	v_mfma_f32_16x16x32_bf16 v[106:109], v[186:189], v[202:205], 0
	v_mfma_f32_16x16x32_bf16 v[106:109], v[190:193], v[206:209], v[106:109]
	v_mfma_f32_16x16x32_bf16 v[94:97], v[142:145], v[210:213], 0
	v_mfma_f32_16x16x32_bf16 v[94:97], v[182:185], v[214:217], v[94:97]
	v_mfma_f32_16x16x32_bf16 v[90:93], v[186:189], v[210:213], 0
	v_mfma_f32_16x16x32_bf16 v[90:93], v[190:193], v[214:217], v[90:93]
	v_mfma_f32_16x16x32_bf16 v[78:81], v[142:145], v[218:221], 0
	v_mfma_f32_16x16x32_bf16 v[78:81], v[182:185], v[222:225], v[78:81]
	v_mfma_f32_16x16x32_bf16 v[74:77], v[186:189], v[218:221], 0
	s_barrier
	v_mfma_f32_16x16x32_bf16 v[74:77], v[190:193], v[222:225], v[74:77]
	s_setprio 0
	s_add_i32 s51, 0, 0x14000
	s_add_i32 s24, s39, s94
	ds_read_b128 v[226:229], v249 offset:16384
	ds_read_b128 v[230:233], v249 offset:17408
	ds_read_b128 v[234:237], v249 offset:18432
	ds_read_b128 v[238:241], v249 offset:19456
	s_mov_b32 m0, s24
	global_load_lds_dwordx4 v134, s[48:49]
	s_add_i32 m0, s24, 0x2000
	s_nop 0
	global_load_lds_dwordx4 v130, s[48:49]
	s_barrier
	s_waitcnt lgkmcnt(0)
	s_setprio 1
	s_waitcnt lgkmcnt(0)
	v_mfma_f32_16x16x32_bf16 v[118:121], v[226:229], v[194:197], 0
	v_mfma_f32_16x16x32_bf16 v[118:121], v[230:233], v[198:201], v[118:121]
	v_mfma_f32_16x16x32_bf16 v[114:117], v[234:237], v[194:197], 0
	v_mfma_f32_16x16x32_bf16 v[114:117], v[238:241], v[198:201], v[114:117]
	v_mfma_f32_16x16x32_bf16 v[102:105], v[226:229], v[202:205], 0
	v_mfma_f32_16x16x32_bf16 v[102:105], v[230:233], v[206:209], v[102:105]
	v_mfma_f32_16x16x32_bf16 v[98:101], v[234:237], v[202:205], 0
	v_mfma_f32_16x16x32_bf16 v[98:101], v[238:241], v[206:209], v[98:101]
	v_mfma_f32_16x16x32_bf16 v[86:89], v[226:229], v[210:213], 0
	v_mfma_f32_16x16x32_bf16 v[86:89], v[230:233], v[214:217], v[86:89]
	v_mfma_f32_16x16x32_bf16 v[82:85], v[234:237], v[210:213], 0
	v_mfma_f32_16x16x32_bf16 v[82:85], v[238:241], v[214:217], v[82:85]
	v_mfma_f32_16x16x32_bf16 v[70:73], v[226:229], v[218:221], 0
	v_mfma_f32_16x16x32_bf16 v[70:73], v[230:233], v[222:225], v[70:73]
	v_mfma_f32_16x16x32_bf16 v[66:69], v[234:237], v[218:221], 0
	s_barrier
	v_mfma_f32_16x16x32_bf16 v[66:69], v[238:241], v[222:225], v[66:69]
	s_setprio 0
	s_mov_b32 m0, s95
	ds_read_b128 v[194:197], v166 offset:16384
	ds_read_b128 v[198:201], v166 offset:17408
	ds_read_b128 v[202:205], v166 offset:18432
	ds_read_b128 v[206:209], v166 offset:19456
	ds_read_b128 v[210:213], v166 offset:20480
	ds_read_b128 v[214:217], v166 offset:21504
	ds_read_b128 v[218:221], v166 offset:22528
	ds_read_b128 v[222:225], v166 offset:23552
	global_load_lds_dwordx4 v136, vcc
	s_mov_b32 m0, s96
	s_nop 0
	global_load_lds_dwordx4 v132, vcc
	s_waitcnt vmcnt(8)
	s_barrier
	s_waitcnt lgkmcnt(0)
	s_setprio 1
	s_waitcnt lgkmcnt(0)
	v_mfma_f32_16x16x32_bf16 v[62:65], v[142:145], v[194:197], 0
	v_mfma_f32_16x16x32_bf16 v[62:65], v[182:185], v[198:201], v[62:65]
	v_mfma_f32_16x16x32_bf16 v[58:61], v[186:189], v[194:197], 0
	v_mfma_f32_16x16x32_bf16 v[58:61], v[190:193], v[198:201], v[58:61]
	v_mfma_f32_16x16x32_bf16 v[46:49], v[142:145], v[202:205], 0
	v_mfma_f32_16x16x32_bf16 v[46:49], v[182:185], v[206:209], v[46:49]
	v_mfma_f32_16x16x32_bf16 v[42:45], v[186:189], v[202:205], 0
	v_mfma_f32_16x16x32_bf16 v[42:45], v[190:193], v[206:209], v[42:45]
	v_mfma_f32_16x16x32_bf16 v[30:33], v[142:145], v[210:213], 0
	v_mfma_f32_16x16x32_bf16 v[30:33], v[182:185], v[214:217], v[30:33]
	v_mfma_f32_16x16x32_bf16 v[26:29], v[186:189], v[210:213], 0
	v_mfma_f32_16x16x32_bf16 v[26:29], v[190:193], v[214:217], v[26:29]
	v_mfma_f32_16x16x32_bf16 v[14:17], v[142:145], v[218:221], 0
	v_mfma_f32_16x16x32_bf16 v[14:17], v[182:185], v[222:225], v[14:17]
	v_mfma_f32_16x16x32_bf16 v[10:13], v[186:189], v[218:221], 0
	s_barrier
; #define PG8_STAGE(bufoff, gbase, voff) do { _Pragma("unroll") for (int _i = 0; _i < 2; ++_i) \
;         __builtin_amdgcn_global_load_lds((const unsigned*)((const char*)(gbase) + (voff)[_i]), (LAS unsigned*)(lds + (bufoff) + ldsw + _i * 8192), 16, 0, 0); } while (0)
; #define PG8_LDA(dst, b, h) do { _Pragma("unroll") for (int m = 0; m < 4; ++m) _Pragma("unroll") for (int k = 0; k < 2; ++k) dst[m][k] = *(const LAS bf16x8*)(lds + PG8_SA(b, h) + aoff + m * 2048 + k * 1024); } while (0)
; #define PG8_LDB(dst, b, h) do { _Pragma("unroll") for (int n = 0; n < 2; ++n) _Pragma("unroll") for (int k = 0; k < 2; ++k) dst[n][k] = *(const LAS bf16x8*)(lds + PG8_SB(b, h) + boff + n * 2048 + k * 1024); } while (0)
; #define PG8_MMA(ai, bj, At, Bt) do { __builtin_amdgcn_s_setprio(1); _Pragma("unroll") for (int m = 0; m < 4; ++m) _Pragma("unroll") for (int n = 0; n < 2; ++n) _Pragma("unroll") for (int k = 0; k < 2; ++k) \
;         acc[ai][bj][m][n] = __builtin_amdgcn_mfma_f32_16x16x32_bf16(Bt[n][k], At[m][k], acc[ai][bj][m][n], 0, 0, 0); __builtin_amdgcn_s_setprio(0); } while (0)
; #define PG8_WAIT_V(n) asm volatile("s_waitcnt vmcnt(" #n ")" ::: "memory")
; #define PG8_WAIT_L(n) asm volatile("s_waitcnt lgkmcnt(" #n ")" ::: "memory")
; #define PG8_BAR __builtin_amdgcn_s_barrier()
; #define PG8_SCHED __builtin_amdgcn_sched_barrier(0)
; template <class Epi, class Sched>
; __device__ __forceinline__ void gemm_phase(LAS unsigned char* lds, const Gemm g, const Sched& S, const Epi& E) {
;     ...
;             PG8_STAGE(PG8_SB(0, 1), b2 + hstep, voffB);
;             PG8_WAIT_V(6); PG8_BAR; PG8_MMA(1, 1, At, B1); PG8_BAR;
;             PG8_LDB(B0, 1, 0); PG8_SCHED; PG8_LDA(At, 1, 0); PG8_STAGE(PG8_SA(0, 1), a2 + hstep, voffA);
;             PG8_WAIT_L(8); PG8_BAR; PG8_WAIT_L(0); PG8_MMA(0, 0, At, B0); PG8_BAR; PG8_SCHED;
;             PG8_LDB(B1, 1, 1); PG8_STAGE(PG8_SB(1, 0), b3, voffB);
;             PG8_BAR; PG8_WAIT_L(0); PG8_MMA(0, 1, At, B1); PG8_BAR;
;             PG8_LDA(At, 1, 1); PG8_STAGE(PG8_SA(1, 0), a3, voffA);
;             PG8_BAR; PG8_WAIT_L(0); PG8_MMA(1, 0, At, B0); PG8_BAR; PG8_SCHED;
	v_mfma_f32_16x16x32_bf16 v[10:13], v[190:193], v[222:225], v[10:13]
	s_setprio 0
	s_add_u32 s24, s48, 0x40000
	s_addc_u32 s25, s49, 0
	s_add_i32 s39, s51, s94
	s_mov_b32 m0, s39
	s_nop 0
	global_load_lds_dwordx4 v134, s[24:25]
	s_add_i32 m0, s39, 0x2000
	s_nop 0
	global_load_lds_dwordx4 v130, s[24:25]
	ds_read_b128 v[142:145], v249 offset:32768
	ds_read_b128 v[182:185], v249 offset:33792
	ds_read_b128 v[186:189], v249 offset:34816
	ds_read_b128 v[190:193], v249 offset:35840
	s_waitcnt vmcnt(6)
	s_barrier
	s_setprio 1
	v_mfma_f32_16x16x32_bf16 v[54:57], v[226:229], v[194:197], 0
	v_mfma_f32_16x16x32_bf16 v[54:57], v[230:233], v[198:201], v[54:57]
	v_mfma_f32_16x16x32_bf16 v[50:53], v[234:237], v[194:197], 0
	ds_read_b128 v[194:197], v166 offset:32768
	v_mfma_f32_16x16x32_bf16 v[50:53], v[238:241], v[198:201], v[50:53]
	ds_read_b128 v[198:201], v166 offset:33792
	v_mfma_f32_16x16x32_bf16 v[38:41], v[226:229], v[202:205], 0
	v_mfma_f32_16x16x32_bf16 v[38:41], v[230:233], v[206:209], v[38:41]
	v_mfma_f32_16x16x32_bf16 v[34:37], v[234:237], v[202:205], 0
	ds_read_b128 v[202:205], v166 offset:34816
	v_mfma_f32_16x16x32_bf16 v[34:37], v[238:241], v[206:209], v[34:37]
	ds_read_b128 v[206:209], v166 offset:35840
	v_mfma_f32_16x16x32_bf16 v[22:25], v[226:229], v[210:213], 0
	v_mfma_f32_16x16x32_bf16 v[22:25], v[230:233], v[214:217], v[22:25]
	v_mfma_f32_16x16x32_bf16 v[18:21], v[234:237], v[210:213], 0
	ds_read_b128 v[210:213], v166 offset:36864
	v_mfma_f32_16x16x32_bf16 v[18:21], v[238:241], v[214:217], v[18:21]
	ds_read_b128 v[214:217], v166 offset:37888
	v_mfma_f32_16x16x32_bf16 v[6:9], v[226:229], v[218:221], 0
	v_mfma_f32_16x16x32_bf16 v[6:9], v[230:233], v[222:225], v[6:9]
	v_mfma_f32_16x16x32_bf16 v[2:5], v[234:237], v[218:221], 0
	s_barrier
	v_mfma_f32_16x16x32_bf16 v[2:5], v[238:241], v[222:225], v[2:5]
	s_setprio 0
	s_add_i32 s39, 0, 0x18000
	s_add_u32 s24, vcc_lo, 0x40000
	s_addc_u32 s25, vcc_hi, 0
	s_mov_b32 m0, s97
	ds_read_b128 v[218:221], v166 offset:38912
	ds_read_b128 v[222:225], v166 offset:39936
	global_load_lds_dwordx4 v136, s[24:25]
	s_mov_b32 m0, s98
	s_nop 0
	global_load_lds_dwordx4 v132, s[24:25]
	s_waitcnt lgkmcnt(8)
	s_barrier
	s_waitcnt lgkmcnt(0)
	s_setprio 1
	s_waitcnt lgkmcnt(0)
	v_mfma_f32_16x16x32_bf16 v[126:129], v[142:145], v[194:197], v[126:129]
	v_mfma_f32_16x16x32_bf16 v[126:129], v[182:185], v[198:201], v[126:129]
	v_mfma_f32_16x16x32_bf16 v[122:125], v[186:189], v[194:197], v[122:125]
	v_mfma_f32_16x16x32_bf16 v[122:125], v[190:193], v[198:201], v[122:125]
	v_mfma_f32_16x16x32_bf16 v[110:113], v[142:145], v[202:205], v[110:113]
	v_mfma_f32_16x16x32_bf16 v[110:113], v[182:185], v[206:209], v[110:113]
	v_mfma_f32_16x16x32_bf16 v[106:109], v[186:189], v[202:205], v[106:109]
	v_mfma_f32_16x16x32_bf16 v[106:109], v[190:193], v[206:209], v[106:109]
	v_mfma_f32_16x16x32_bf16 v[94:97], v[142:145], v[210:213], v[94:97]
	v_mfma_f32_16x16x32_bf16 v[94:97], v[182:185], v[214:217], v[94:97]
	v_mfma_f32_16x16x32_bf16 v[90:93], v[186:189], v[210:213], v[90:93]
	v_mfma_f32_16x16x32_bf16 v[90:93], v[190:193], v[214:217], v[90:93]
	v_mfma_f32_16x16x32_bf16 v[78:81], v[142:145], v[218:221], v[78:81]
	v_mfma_f32_16x16x32_bf16 v[78:81], v[182:185], v[222:225], v[78:81]
	v_mfma_f32_16x16x32_bf16 v[74:77], v[186:189], v[218:221], v[74:77]
	s_barrier
	v_mfma_f32_16x16x32_bf16 v[74:77], v[190:193], v[222:225], v[74:77]
	s_setprio 0
	s_add_i32 s51, 0, 0x1c000
	s_add_i32 s24, s39, s94
	s_add_i32 m0, s24, 0xffffff80
	ds_read_b128 v[226:229], v249 offset:49152
	ds_read_b128 v[230:233], v249 offset:50176
	ds_read_b128 v[234:237], v249 offset:51200
	ds_read_b128 v[238:241], v249 offset:52224
	global_load_lds_dwordx4 v134, s[48:49] offset:128
	s_add_i32 m0, s24, 0x1f80
	s_nop 0
	global_load_lds_dwordx4 v130, s[48:49] offset:128
	s_barrier
	s_waitcnt lgkmcnt(0)
	s_setprio 1
	s_waitcnt lgkmcnt(0)
	v_mfma_f32_16x16x32_bf16 v[118:121], v[226:229], v[194:197], v[118:121]
	v_mfma_f32_16x16x32_bf16 v[118:121], v[230:233], v[198:201], v[118:121]
	v_mfma_f32_16x16x32_bf16 v[114:117], v[234:237], v[194:197], v[114:117]
	v_mfma_f32_16x16x32_bf16 v[114:117], v[238:241], v[198:201], v[114:117]
	v_mfma_f32_16x16x32_bf16 v[102:105], v[226:229], v[202:205], v[102:105]
	v_mfma_f32_16x16x32_bf16 v[102:105], v[230:233], v[206:209], v[102:105]
	v_mfma_f32_16x16x32_bf16 v[98:101], v[234:237], v[202:205], v[98:101]
	v_mfma_f32_16x16x32_bf16 v[98:101], v[238:241], v[206:209], v[98:101]
	v_mfma_f32_16x16x32_bf16 v[86:89], v[226:229], v[210:213], v[86:89]
	v_mfma_f32_16x16x32_bf16 v[86:89], v[230:233], v[214:217], v[86:89]
	v_mfma_f32_16x16x32_bf16 v[82:85], v[234:237], v[210:213], v[82:85]
	v_mfma_f32_16x16x32_bf16 v[82:85], v[238:241], v[214:217], v[82:85]
	v_mfma_f32_16x16x32_bf16 v[70:73], v[226:229], v[218:221], v[70:73]
	v_mfma_f32_16x16x32_bf16 v[70:73], v[230:233], v[222:225], v[70:73]
	v_mfma_f32_16x16x32_bf16 v[66:69], v[234:237], v[218:221], v[66:69]
	s_barrier
	v_mfma_f32_16x16x32_bf16 v[66:69], v[238:241], v[222:225], v[66:69]
	s_setprio 0
	s_add_i32 m0, s99, 0xffffff80
	ds_read_b128 v[194:197], v166 offset:49152
	ds_read_b128 v[198:201], v166 offset:50176
	ds_read_b128 v[202:205], v166 offset:51200
	ds_read_b128 v[206:209], v166 offset:52224
	ds_read_b128 v[210:213], v166 offset:53248
	ds_read_b128 v[214:217], v166 offset:54272
	ds_read_b128 v[218:221], v166 offset:55296
	ds_read_b128 v[222:225], v166 offset:56320
	global_load_lds_dwordx4 v136, vcc offset:128
	s_add_i32 m0, s82, 0xffffff80
	s_nop 0
	global_load_lds_dwordx4 v132, vcc offset:128
	s_waitcnt vmcnt(8)
	s_barrier
; #define PG8_STAGE(bufoff, gbase, voff) do { _Pragma("unroll") for (int _i = 0; _i < 2; ++_i) \
;         __builtin_amdgcn_global_load_lds((const unsigned*)((const char*)(gbase) + (voff)[_i]), (LAS unsigned*)(lds + (bufoff) + ldsw + _i * 8192), 16, 0, 0); } while (0)
; #define PG8_LDA(dst, b, h) do { _Pragma("unroll") for (int m = 0; m < 4; ++m) _Pragma("unroll") for (int k = 0; k < 2; ++k) dst[m][k] = *(const LAS bf16x8*)(lds + PG8_SA(b, h) + aoff + m * 2048 + k * 1024); } while (0)
; #define PG8_LDB(dst, b, h) do { _Pragma("unroll") for (int n = 0; n < 2; ++n) _Pragma("unroll") for (int k = 0; k < 2; ++k) dst[n][k] = *(const LAS bf16x8*)(lds + PG8_SB(b, h) + boff + n * 2048 + k * 1024); } while (0)
; #define PG8_MMA(ai, bj, At, Bt) do { __builtin_amdgcn_s_setprio(1); _Pragma("unroll") for (int m = 0; m < 4; ++m) _Pragma("unroll") for (int n = 0; n < 2; ++n) _Pragma("unroll") for (int k = 0; k < 2; ++k) \
;         acc[ai][bj][m][n] = __builtin_amdgcn_mfma_f32_16x16x32_bf16(Bt[n][k], At[m][k], acc[ai][bj][m][n], 0, 0, 0); __builtin_amdgcn_s_setprio(0); } while (0)
; #define PG8_WAIT_V(n) asm volatile("s_waitcnt vmcnt(" #n ")" ::: "memory")
; #define PG8_WAIT_L(n) asm volatile("s_waitcnt lgkmcnt(" #n ")" ::: "memory")
; #define PG8_BAR __builtin_amdgcn_s_barrier()
; #define PG8_SCHED __builtin_amdgcn_sched_barrier(0)
; template <class Epi, class Sched>
; __device__ __forceinline__ void gemm_phase(LAS unsigned char* lds, const Gemm g, const Sched& S, const Epi& E) {
;     ...
;         for (int t = 0; t < nt; t += 2) {
;             const bool last = (t == nt - 2);
;             const char* a1 = cA + (size_t)(t + 1) * kstep;
;             const char* a2 = last ? nA : cA + (size_t)(t + 2) * kstep; const char* b2 = last ? nB : cB + (size_t)(t + 2) * kstep;
;             const char* a3 = a2 + kstep; const char* b3 = b2 + kstep;
;             PG8_LDB(B0, 0, 0); PG8_SCHED; PG8_LDA(At, 0, 0); PG8_STAGE(PG8_SA(1, 1), a1 + hstep, voffA);
;             PG8_WAIT_L(8); PG8_BAR; PG8_WAIT_L(0); PG8_MMA(0, 0, At, B0); PG8_BAR; PG8_SCHED;
;             PG8_LDB(B1, 0, 1); PG8_STAGE(PG8_SB(0, 0), b2, voffB);
;             PG8_BAR; PG8_WAIT_L(0); PG8_MMA(0, 1, At, B1); PG8_BAR;
;     ...
;             PG8_BAR; PG8_WAIT_L(0); PG8_MMA(1, 0, At, B0); PG8_BAR; PG8_SCHED;
;             PG8_STAGE(PG8_SB(1, 1), b3 + hstep, voffB);
;             PG8_WAIT_V(6); PG8_BAR; PG8_MMA(1, 1, At, B1); PG8_BAR;
	s_waitcnt lgkmcnt(0)
	s_setprio 1
	s_waitcnt lgkmcnt(0)
	v_mfma_f32_16x16x32_bf16 v[62:65], v[142:145], v[194:197], v[62:65]
	v_mfma_f32_16x16x32_bf16 v[62:65], v[182:185], v[198:201], v[62:65]
	v_mfma_f32_16x16x32_bf16 v[58:61], v[186:189], v[194:197], v[58:61]
	v_mfma_f32_16x16x32_bf16 v[58:61], v[190:193], v[198:201], v[58:61]
	v_mfma_f32_16x16x32_bf16 v[46:49], v[142:145], v[202:205], v[46:49]
	v_mfma_f32_16x16x32_bf16 v[46:49], v[182:185], v[206:209], v[46:49]
	v_mfma_f32_16x16x32_bf16 v[42:45], v[186:189], v[202:205], v[42:45]
	v_mfma_f32_16x16x32_bf16 v[42:45], v[190:193], v[206:209], v[42:45]
	v_mfma_f32_16x16x32_bf16 v[30:33], v[142:145], v[210:213], v[30:33]
	v_mfma_f32_16x16x32_bf16 v[30:33], v[182:185], v[214:217], v[30:33]
	v_mfma_f32_16x16x32_bf16 v[26:29], v[186:189], v[210:213], v[26:29]
	v_mfma_f32_16x16x32_bf16 v[26:29], v[190:193], v[214:217], v[26:29]
	v_mfma_f32_16x16x32_bf16 v[14:17], v[142:145], v[218:221], v[14:17]
	v_mfma_f32_16x16x32_bf16 v[14:17], v[182:185], v[222:225], v[14:17]
	v_mfma_f32_16x16x32_bf16 v[10:13], v[186:189], v[218:221], v[10:13]
	s_barrier
	v_mfma_f32_16x16x32_bf16 v[10:13], v[190:193], v[222:225], v[10:13]
	s_setprio 0
	s_add_u32 s24, s48, 0x40080
	s_addc_u32 s25, s49, 0
	s_add_i32 s39, s51, s94
	s_mov_b32 m0, s39
	s_nop 0
	global_load_lds_dwordx4 v134, s[24:25]
	s_add_i32 m0, s39, 0x2000
	s_nop 0
	global_load_lds_dwordx4 v130, s[24:25]
	ds_read_b128 v[142:145], v249
	ds_read_b128 v[182:185], v249 offset:1024
	ds_read_b128 v[186:189], v249 offset:2048
	ds_read_b128 v[190:193], v249 offset:3072
	s_waitcnt vmcnt(6)
	s_barrier
	s_setprio 1
	v_mfma_f32_16x16x32_bf16 v[54:57], v[226:229], v[194:197], v[54:57]
	v_mfma_f32_16x16x32_bf16 v[54:57], v[230:233], v[198:201], v[54:57]
	v_mfma_f32_16x16x32_bf16 v[50:53], v[234:237], v[194:197], v[50:53]
	ds_read_b128 v[194:197], v166
	v_mfma_f32_16x16x32_bf16 v[50:53], v[238:241], v[198:201], v[50:53]
	ds_read_b128 v[198:201], v166 offset:1024
	v_mfma_f32_16x16x32_bf16 v[38:41], v[226:229], v[202:205], v[38:41]
	v_mfma_f32_16x16x32_bf16 v[38:41], v[230:233], v[206:209], v[38:41]
	v_mfma_f32_16x16x32_bf16 v[34:37], v[234:237], v[202:205], v[34:37]
	ds_read_b128 v[202:205], v166 offset:2048
	v_mfma_f32_16x16x32_bf16 v[34:37], v[238:241], v[206:209], v[34:37]
	ds_read_b128 v[206:209], v166 offset:3072
	v_mfma_f32_16x16x32_bf16 v[22:25], v[226:229], v[210:213], v[22:25]
	v_mfma_f32_16x16x32_bf16 v[22:25], v[230:233], v[214:217], v[22:25]
	v_mfma_f32_16x16x32_bf16 v[18:21], v[234:237], v[210:213], v[18:21]
	ds_read_b128 v[210:213], v166 offset:4096
	v_mfma_f32_16x16x32_bf16 v[18:21], v[238:241], v[214:217], v[18:21]
	ds_read_b128 v[214:217], v166 offset:5120
	v_mfma_f32_16x16x32_bf16 v[6:9], v[226:229], v[218:221], v[6:9]
	v_mfma_f32_16x16x32_bf16 v[6:9], v[230:233], v[222:225], v[6:9]
	v_mfma_f32_16x16x32_bf16 v[2:5], v[234:237], v[218:221], v[2:5]
	s_barrier
	v_mfma_f32_16x16x32_bf16 v[2:5], v[238:241], v[222:225], v[2:5]
	s_setprio 0
	s_add_i32 s38, s38, 2
	s_add_u32 s35, s35, 0x100
	s_addc_u32 s50, s50, 0
	s_add_u32 s0, s0, 0x100
	s_addc_u32 s1, s1, 0
	s_cmp_gt_u32 s38, 13
.LBB0_557:
	s_add_u32 s24, s0, 0xfffc0080
	s_addc_u32 s25, s1, -1
	s_add_i32 s39, 0, 0x10000
	s_cmp_eq_u32 s38, 12
	s_cselect_b32 vcc_hi, s77, s25
	s_cselect_b32 vcc_lo, s76, s24
	s_cselect_b32 s49, s45, s50
	s_cselect_b32 s48, s47, s35
	s_add_i32 m0, s95, 0xc000
	ds_read_b128 v[218:221], v166 offset:6144
	ds_read_b128 v[222:225], v166 offset:7168
	global_load_lds_dwordx4 v140, s[0:1]
	s_add_i32 m0, s95, 0xe000
	s_nop 0
	global_load_lds_dwordx4 v138, s[0:1]
	s_waitcnt lgkmcnt(8)
	s_barrier
	s_waitcnt lgkmcnt(0)
	s_setprio 1
	s_waitcnt lgkmcnt(0)
	v_mfma_f32_16x16x32_bf16 v[126:129], v[142:145], v[194:197], v[126:129]
	v_mfma_f32_16x16x32_bf16 v[126:129], v[182:185], v[198:201], v[126:129]
	v_mfma_f32_16x16x32_bf16 v[122:125], v[186:189], v[194:197], v[122:125]
	v_mfma_f32_16x16x32_bf16 v[122:125], v[190:193], v[198:201], v[122:125]
	v_mfma_f32_16x16x32_bf16 v[110:113], v[142:145], v[202:205], v[110:113]
	v_mfma_f32_16x16x32_bf16 v[110:113], v[182:185], v[206:209], v[110:113]
	v_mfma_f32_16x16x32_bf16 v[106:109], v[186:189], v[202:205], v[106:109]
	v_mfma_f32_16x16x32_bf16 v[106:109], v[190:193], v[206:209], v[106:109]
	v_mfma_f32_16x16x32_bf16 v[94:97], v[142:145], v[210:213], v[94:97]
	v_mfma_f32_16x16x32_bf16 v[94:97], v[182:185], v[214:217], v[94:97]
	v_mfma_f32_16x16x32_bf16 v[90:93], v[186:189], v[210:213], v[90:93]
	v_mfma_f32_16x16x32_bf16 v[90:93], v[190:193], v[214:217], v[90:93]
	v_mfma_f32_16x16x32_bf16 v[78:81], v[142:145], v[218:221], v[78:81]
	v_mfma_f32_16x16x32_bf16 v[78:81], v[182:185], v[222:225], v[78:81]
	v_mfma_f32_16x16x32_bf16 v[74:77], v[186:189], v[218:221], v[74:77]
	s_barrier
	v_mfma_f32_16x16x32_bf16 v[74:77], v[190:193], v[222:225], v[74:77]
	s_setprio 0
	s_add_i32 s51, 0, 0x14000
	s_add_i32 s24, s39, s94
	ds_read_b128 v[226:229], v249 offset:16384
	ds_read_b128 v[230:233], v249 offset:17408
	ds_read_b128 v[234:237], v249 offset:18432
	ds_read_b128 v[238:241], v249 offset:19456
	s_mov_b32 m0, s24
	global_load_lds_dwordx4 v134, s[48:49]
	s_add_i32 m0, s24, 0x2000
	s_nop 0
	global_load_lds_dwordx4 v130, s[48:49]
	s_barrier
; #define PG8_STAGE(bufoff, gbase, voff) do { _Pragma("unroll") for (int _i = 0; _i < 2; ++_i) \
;         __builtin_amdgcn_global_load_lds((const unsigned*)((const char*)(gbase) + (voff)[_i]), (LAS unsigned*)(lds + (bufoff) + ldsw + _i * 8192), 16, 0, 0); } while (0)
; #define PG8_LDA(dst, b, h) do { _Pragma("unroll") for (int m = 0; m < 4; ++m) _Pragma("unroll") for (int k = 0; k < 2; ++k) dst[m][k] = *(const LAS bf16x8*)(lds + PG8_SA(b, h) + aoff + m * 2048 + k * 1024); } while (0)
; #define PG8_LDB(dst, b, h) do { _Pragma("unroll") for (int n = 0; n < 2; ++n) _Pragma("unroll") for (int k = 0; k < 2; ++k) dst[n][k] = *(const LAS bf16x8*)(lds + PG8_SB(b, h) + boff + n * 2048 + k * 1024); } while (0)
; #define PG8_MMA(ai, bj, At, Bt) do { __builtin_amdgcn_s_setprio(1); _Pragma("unroll") for (int m = 0; m < 4; ++m) _Pragma("unroll") for (int n = 0; n < 2; ++n) _Pragma("unroll") for (int k = 0; k < 2; ++k) \
;         acc[ai][bj][m][n] = __builtin_amdgcn_mfma_f32_16x16x32_bf16(Bt[n][k], At[m][k], acc[ai][bj][m][n], 0, 0, 0); __builtin_amdgcn_s_setprio(0); } while (0)
; #define PG8_WAIT_V(n) asm volatile("s_waitcnt vmcnt(" #n ")" ::: "memory")
; #define PG8_WAIT_L(n) asm volatile("s_waitcnt lgkmcnt(" #n ")" ::: "memory")
; #define PG8_BAR __builtin_amdgcn_s_barrier()
; #define PG8_SCHED __builtin_amdgcn_sched_barrier(0)
; template <class Epi, class Sched>
; __device__ __forceinline__ void gemm_phase(LAS unsigned char* lds, const Gemm g, const Sched& S, const Epi& E) {
;     ...
;             PG8_BAR; PG8_WAIT_L(0); PG8_MMA(0, 1, At, B1); PG8_BAR;
;             PG8_LDA(At, 0, 1); PG8_STAGE(PG8_SA(0, 0), a2, voffA);
;             PG8_BAR; PG8_WAIT_L(0); PG8_MMA(1, 0, At, B0); PG8_BAR; PG8_SCHED;
;             PG8_STAGE(PG8_SB(0, 1), b2 + hstep, voffB);
;             PG8_WAIT_V(6); PG8_BAR; PG8_MMA(1, 1, At, B1); PG8_BAR;
;             PG8_LDB(B0, 1, 0); PG8_SCHED; PG8_LDA(At, 1, 0); PG8_STAGE(PG8_SA(0, 1), a2 + hstep, voffA);
;             PG8_WAIT_L(8); PG8_BAR; PG8_WAIT_L(0); PG8_MMA(0, 0, At, B0); PG8_BAR; PG8_SCHED;
	s_waitcnt lgkmcnt(0)
	s_setprio 1
	s_waitcnt lgkmcnt(0)
	v_mfma_f32_16x16x32_bf16 v[118:121], v[226:229], v[194:197], v[118:121]
	v_mfma_f32_16x16x32_bf16 v[118:121], v[230:233], v[198:201], v[118:121]
	v_mfma_f32_16x16x32_bf16 v[114:117], v[234:237], v[194:197], v[114:117]
	v_mfma_f32_16x16x32_bf16 v[114:117], v[238:241], v[198:201], v[114:117]
	v_mfma_f32_16x16x32_bf16 v[102:105], v[226:229], v[202:205], v[102:105]
	v_mfma_f32_16x16x32_bf16 v[102:105], v[230:233], v[206:209], v[102:105]
	v_mfma_f32_16x16x32_bf16 v[98:101], v[234:237], v[202:205], v[98:101]
	v_mfma_f32_16x16x32_bf16 v[98:101], v[238:241], v[206:209], v[98:101]
	v_mfma_f32_16x16x32_bf16 v[86:89], v[226:229], v[210:213], v[86:89]
	v_mfma_f32_16x16x32_bf16 v[86:89], v[230:233], v[214:217], v[86:89]
	v_mfma_f32_16x16x32_bf16 v[82:85], v[234:237], v[210:213], v[82:85]
	v_mfma_f32_16x16x32_bf16 v[82:85], v[238:241], v[214:217], v[82:85]
	v_mfma_f32_16x16x32_bf16 v[70:73], v[226:229], v[218:221], v[70:73]
	v_mfma_f32_16x16x32_bf16 v[70:73], v[230:233], v[222:225], v[70:73]
	v_mfma_f32_16x16x32_bf16 v[66:69], v[234:237], v[218:221], v[66:69]
	s_barrier
	v_mfma_f32_16x16x32_bf16 v[66:69], v[238:241], v[222:225], v[66:69]
	s_setprio 0
	s_mov_b32 m0, s95
	ds_read_b128 v[194:197], v166 offset:16384
	ds_read_b128 v[198:201], v166 offset:17408
	ds_read_b128 v[202:205], v166 offset:18432
	ds_read_b128 v[206:209], v166 offset:19456
	ds_read_b128 v[210:213], v166 offset:20480
	ds_read_b128 v[214:217], v166 offset:21504
	ds_read_b128 v[218:221], v166 offset:22528
	ds_read_b128 v[222:225], v166 offset:23552
	global_load_lds_dwordx4 v136, vcc
	s_mov_b32 m0, s96
	s_nop 0
	global_load_lds_dwordx4 v132, vcc
	s_waitcnt vmcnt(8)
	s_barrier
	s_waitcnt lgkmcnt(0)
	s_setprio 1
	s_waitcnt lgkmcnt(0)
	v_mfma_f32_16x16x32_bf16 v[62:65], v[142:145], v[194:197], v[62:65]
	v_mfma_f32_16x16x32_bf16 v[62:65], v[182:185], v[198:201], v[62:65]
	v_mfma_f32_16x16x32_bf16 v[58:61], v[186:189], v[194:197], v[58:61]
	v_mfma_f32_16x16x32_bf16 v[58:61], v[190:193], v[198:201], v[58:61]
	v_mfma_f32_16x16x32_bf16 v[46:49], v[142:145], v[202:205], v[46:49]
	v_mfma_f32_16x16x32_bf16 v[46:49], v[182:185], v[206:209], v[46:49]
	v_mfma_f32_16x16x32_bf16 v[42:45], v[186:189], v[202:205], v[42:45]
	v_mfma_f32_16x16x32_bf16 v[42:45], v[190:193], v[206:209], v[42:45]
	v_mfma_f32_16x16x32_bf16 v[30:33], v[142:145], v[210:213], v[30:33]
	v_mfma_f32_16x16x32_bf16 v[30:33], v[182:185], v[214:217], v[30:33]
	v_mfma_f32_16x16x32_bf16 v[26:29], v[186:189], v[210:213], v[26:29]
	v_mfma_f32_16x16x32_bf16 v[26:29], v[190:193], v[214:217], v[26:29]
	v_mfma_f32_16x16x32_bf16 v[14:17], v[142:145], v[218:221], v[14:17]
	v_mfma_f32_16x16x32_bf16 v[14:17], v[182:185], v[222:225], v[14:17]
	v_mfma_f32_16x16x32_bf16 v[10:13], v[186:189], v[218:221], v[10:13]
	s_barrier
	v_mfma_f32_16x16x32_bf16 v[10:13], v[190:193], v[222:225], v[10:13]
	s_setprio 0
	s_add_u32 s24, s48, 0x40000
	s_addc_u32 s25, s49, 0
	s_add_i32 s39, s51, s94
	s_mov_b32 m0, s39
	s_nop 0
	global_load_lds_dwordx4 v134, s[24:25]
	s_add_i32 m0, s39, 0x2000
	s_nop 0
	global_load_lds_dwordx4 v130, s[24:25]
	ds_read_b128 v[142:145], v249 offset:32768
	ds_read_b128 v[182:185], v249 offset:33792
	ds_read_b128 v[186:189], v249 offset:34816
	ds_read_b128 v[190:193], v249 offset:35840
	s_waitcnt vmcnt(6)
	s_barrier
	s_setprio 1
	v_mfma_f32_16x16x32_bf16 v[54:57], v[226:229], v[194:197], v[54:57]
	v_mfma_f32_16x16x32_bf16 v[54:57], v[230:233], v[198:201], v[54:57]
	v_mfma_f32_16x16x32_bf16 v[50:53], v[234:237], v[194:197], v[50:53]
	ds_read_b128 v[194:197], v166 offset:32768
	v_mfma_f32_16x16x32_bf16 v[50:53], v[238:241], v[198:201], v[50:53]
	ds_read_b128 v[198:201], v166 offset:33792
	v_mfma_f32_16x16x32_bf16 v[38:41], v[226:229], v[202:205], v[38:41]
	v_mfma_f32_16x16x32_bf16 v[38:41], v[230:233], v[206:209], v[38:41]
	v_mfma_f32_16x16x32_bf16 v[34:37], v[234:237], v[202:205], v[34:37]
	ds_read_b128 v[202:205], v166 offset:34816
	v_mfma_f32_16x16x32_bf16 v[34:37], v[238:241], v[206:209], v[34:37]
	ds_read_b128 v[206:209], v166 offset:35840
	v_mfma_f32_16x16x32_bf16 v[22:25], v[226:229], v[210:213], v[22:25]
	v_mfma_f32_16x16x32_bf16 v[22:25], v[230:233], v[214:217], v[22:25]
	v_mfma_f32_16x16x32_bf16 v[18:21], v[234:237], v[210:213], v[18:21]
	ds_read_b128 v[210:213], v166 offset:36864
	v_mfma_f32_16x16x32_bf16 v[18:21], v[238:241], v[214:217], v[18:21]
	ds_read_b128 v[214:217], v166 offset:37888
	v_mfma_f32_16x16x32_bf16 v[6:9], v[226:229], v[218:221], v[6:9]
	v_mfma_f32_16x16x32_bf16 v[6:9], v[230:233], v[222:225], v[6:9]
	v_mfma_f32_16x16x32_bf16 v[2:5], v[234:237], v[218:221], v[2:5]
	s_barrier
	v_mfma_f32_16x16x32_bf16 v[2:5], v[238:241], v[222:225], v[2:5]
	s_setprio 0
	s_add_i32 s39, 0, 0x18000
	s_add_u32 s24, vcc_lo, 0x40000
	s_addc_u32 s25, vcc_hi, 0
	s_mov_b32 m0, s97
	ds_read_b128 v[218:221], v166 offset:38912
	ds_read_b128 v[222:225], v166 offset:39936
	global_load_lds_dwordx4 v136, s[24:25]
	s_mov_b32 m0, s98
	s_nop 0
	global_load_lds_dwordx4 v132, s[24:25]
	s_waitcnt lgkmcnt(8)
	s_barrier
	s_waitcnt lgkmcnt(0)
	s_setprio 1
	s_waitcnt lgkmcnt(0)
	v_mfma_f32_16x16x32_bf16 v[126:129], v[142:145], v[194:197], v[126:129]
	v_mfma_f32_16x16x32_bf16 v[126:129], v[182:185], v[198:201], v[126:129]
	v_mfma_f32_16x16x32_bf16 v[122:125], v[186:189], v[194:197], v[122:125]
	v_mfma_f32_16x16x32_bf16 v[122:125], v[190:193], v[198:201], v[122:125]
	v_mfma_f32_16x16x32_bf16 v[110:113], v[142:145], v[202:205], v[110:113]
	v_mfma_f32_16x16x32_bf16 v[110:113], v[182:185], v[206:209], v[110:113]
	v_mfma_f32_16x16x32_bf16 v[106:109], v[186:189], v[202:205], v[106:109]
	v_mfma_f32_16x16x32_bf16 v[106:109], v[190:193], v[206:209], v[106:109]
	v_mfma_f32_16x16x32_bf16 v[94:97], v[142:145], v[210:213], v[94:97]
	v_mfma_f32_16x16x32_bf16 v[94:97], v[182:185], v[214:217], v[94:97]
	v_mfma_f32_16x16x32_bf16 v[90:93], v[186:189], v[210:213], v[90:93]
	v_mfma_f32_16x16x32_bf16 v[90:93], v[190:193], v[214:217], v[90:93]
	v_mfma_f32_16x16x32_bf16 v[78:81], v[142:145], v[218:221], v[78:81]
	v_mfma_f32_16x16x32_bf16 v[78:81], v[182:185], v[222:225], v[78:81]
	v_mfma_f32_16x16x32_bf16 v[74:77], v[186:189], v[218:221], v[74:77]
	s_barrier
; #define PG8_STAGE(bufoff, gbase, voff) do { _Pragma("unroll") for (int _i = 0; _i < 2; ++_i) \
;         __builtin_amdgcn_global_load_lds((const unsigned*)((const char*)(gbase) + (voff)[_i]), (LAS unsigned*)(lds + (bufoff) + ldsw + _i * 8192), 16, 0, 0); } while (0)
; #define PG8_LDA(dst, b, h) do { _Pragma("unroll") for (int m = 0; m < 4; ++m) _Pragma("unroll") for (int k = 0; k < 2; ++k) dst[m][k] = *(const LAS bf16x8*)(lds + PG8_SA(b, h) + aoff + m * 2048 + k * 1024); } while (0)
; #define PG8_LDB(dst, b, h) do { _Pragma("unroll") for (int n = 0; n < 2; ++n) _Pragma("unroll") for (int k = 0; k < 2; ++k) dst[n][k] = *(const LAS bf16x8*)(lds + PG8_SB(b, h) + boff + n * 2048 + k * 1024); } while (0)
; #define PG8_MMA(ai, bj, At, Bt) do { __builtin_amdgcn_s_setprio(1); _Pragma("unroll") for (int m = 0; m < 4; ++m) _Pragma("unroll") for (int n = 0; n < 2; ++n) _Pragma("unroll") for (int k = 0; k < 2; ++k) \
;         acc[ai][bj][m][n] = __builtin_amdgcn_mfma_f32_16x16x32_bf16(Bt[n][k], At[m][k], acc[ai][bj][m][n], 0, 0, 0); __builtin_amdgcn_s_setprio(0); } while (0)
; #define PG8_WAIT_V(n) asm volatile("s_waitcnt vmcnt(" #n ")" ::: "memory")
; #define PG8_WAIT_L(n) asm volatile("s_waitcnt lgkmcnt(" #n ")" ::: "memory")
; #define PG8_BAR __builtin_amdgcn_s_barrier()
; #define PG8_SCHED __builtin_amdgcn_sched_barrier(0)
; template <class Epi, class Sched>
; __device__ __forceinline__ void gemm_phase(LAS unsigned char* lds, const Gemm g, const Sched& S, const Epi& E) {
;     ...
;             PG8_LDB(B1, 1, 1); PG8_STAGE(PG8_SB(1, 0), b3, voffB);
;             PG8_BAR; PG8_WAIT_L(0); PG8_MMA(0, 1, At, B1); PG8_BAR;
;             PG8_LDA(At, 1, 1); PG8_STAGE(PG8_SA(1, 0), a3, voffA);
;             PG8_BAR; PG8_WAIT_L(0); PG8_MMA(1, 0, At, B0); PG8_BAR; PG8_SCHED;
;             PG8_STAGE(PG8_SB(1, 1), b3 + hstep, voffB);
;             PG8_WAIT_V(6); PG8_BAR; PG8_MMA(1, 1, At, B1); PG8_BAR;
;         }
;         if (wr == 0) PG8_BAR;
	v_mfma_f32_16x16x32_bf16 v[74:77], v[190:193], v[222:225], v[74:77]
	s_setprio 0
	s_add_i32 s51, 0, 0x1c000
	s_add_i32 s24, s39, s94
	s_add_i32 m0, s24, 0xffffff80
	ds_read_b128 v[226:229], v249 offset:49152
	ds_read_b128 v[230:233], v249 offset:50176
	ds_read_b128 v[234:237], v249 offset:51200
	ds_read_b128 v[238:241], v249 offset:52224
	global_load_lds_dwordx4 v134, s[48:49] offset:128
	s_add_i32 m0, s24, 0x1f80
	s_nop 0
	global_load_lds_dwordx4 v130, s[48:49] offset:128
	s_barrier
	s_waitcnt lgkmcnt(0)
	s_setprio 1
	s_waitcnt lgkmcnt(0)
	v_mfma_f32_16x16x32_bf16 v[118:121], v[226:229], v[194:197], v[118:121]
	v_mfma_f32_16x16x32_bf16 v[118:121], v[230:233], v[198:201], v[118:121]
	v_mfma_f32_16x16x32_bf16 v[114:117], v[234:237], v[194:197], v[114:117]
	v_mfma_f32_16x16x32_bf16 v[114:117], v[238:241], v[198:201], v[114:117]
	v_mfma_f32_16x16x32_bf16 v[102:105], v[226:229], v[202:205], v[102:105]
	v_mfma_f32_16x16x32_bf16 v[102:105], v[230:233], v[206:209], v[102:105]
	v_mfma_f32_16x16x32_bf16 v[98:101], v[234:237], v[202:205], v[98:101]
	v_mfma_f32_16x16x32_bf16 v[98:101], v[238:241], v[206:209], v[98:101]
	v_mfma_f32_16x16x32_bf16 v[86:89], v[226:229], v[210:213], v[86:89]
	v_mfma_f32_16x16x32_bf16 v[86:89], v[230:233], v[214:217], v[86:89]
	v_mfma_f32_16x16x32_bf16 v[82:85], v[234:237], v[210:213], v[82:85]
	v_mfma_f32_16x16x32_bf16 v[82:85], v[238:241], v[214:217], v[82:85]
	v_mfma_f32_16x16x32_bf16 v[70:73], v[226:229], v[218:221], v[70:73]
	v_mfma_f32_16x16x32_bf16 v[70:73], v[230:233], v[222:225], v[70:73]
	v_mfma_f32_16x16x32_bf16 v[66:69], v[234:237], v[218:221], v[66:69]
	s_barrier
	v_mfma_f32_16x16x32_bf16 v[66:69], v[238:241], v[222:225], v[66:69]
	s_setprio 0
	s_add_i32 m0, s99, 0xffffff80
	ds_read_b128 v[194:197], v166 offset:49152
	ds_read_b128 v[198:201], v166 offset:50176
	ds_read_b128 v[202:205], v166 offset:51200
	ds_read_b128 v[206:209], v166 offset:52224
	ds_read_b128 v[210:213], v166 offset:53248
	ds_read_b128 v[214:217], v166 offset:54272
	ds_read_b128 v[218:221], v166 offset:55296
	ds_read_b128 v[222:225], v166 offset:56320
	global_load_lds_dwordx4 v136, vcc offset:128
	s_add_i32 m0, s82, 0xffffff80
	s_nop 0
	global_load_lds_dwordx4 v132, vcc offset:128
	s_waitcnt vmcnt(8)
	s_barrier
	s_waitcnt lgkmcnt(0)
	s_setprio 1
	s_waitcnt lgkmcnt(0)
	v_mfma_f32_16x16x32_bf16 v[62:65], v[142:145], v[194:197], v[62:65]
	v_mfma_f32_16x16x32_bf16 v[62:65], v[182:185], v[198:201], v[62:65]
	v_mfma_f32_16x16x32_bf16 v[58:61], v[186:189], v[194:197], v[58:61]
	v_mfma_f32_16x16x32_bf16 v[58:61], v[190:193], v[198:201], v[58:61]
	v_mfma_f32_16x16x32_bf16 v[46:49], v[142:145], v[202:205], v[46:49]
	v_mfma_f32_16x16x32_bf16 v[46:49], v[182:185], v[206:209], v[46:49]
	v_mfma_f32_16x16x32_bf16 v[42:45], v[186:189], v[202:205], v[42:45]
	v_mfma_f32_16x16x32_bf16 v[42:45], v[190:193], v[206:209], v[42:45]
	v_mfma_f32_16x16x32_bf16 v[30:33], v[142:145], v[210:213], v[30:33]
	v_mfma_f32_16x16x32_bf16 v[30:33], v[182:185], v[214:217], v[30:33]
	v_mfma_f32_16x16x32_bf16 v[26:29], v[186:189], v[210:213], v[26:29]
	v_mfma_f32_16x16x32_bf16 v[26:29], v[190:193], v[214:217], v[26:29]
	v_mfma_f32_16x16x32_bf16 v[14:17], v[142:145], v[218:221], v[14:17]
	v_mfma_f32_16x16x32_bf16 v[14:17], v[182:185], v[222:225], v[14:17]
	v_mfma_f32_16x16x32_bf16 v[10:13], v[186:189], v[218:221], v[10:13]
	s_barrier
	v_mfma_f32_16x16x32_bf16 v[10:13], v[190:193], v[222:225], v[10:13]
	s_setprio 0
	s_add_u32 s24, s48, 0x40080
	s_addc_u32 s25, s49, 0
	s_add_i32 s39, s51, s94
	s_mov_b32 m0, s39
	s_nop 0
	global_load_lds_dwordx4 v134, s[24:25]
	s_add_i32 m0, s39, 0x2000
	s_nop 0
	global_load_lds_dwordx4 v130, s[24:25]
	ds_read_b128 v[142:145], v249
	ds_read_b128 v[182:185], v249 offset:1024
	ds_read_b128 v[186:189], v249 offset:2048
	ds_read_b128 v[190:193], v249 offset:3072
	s_waitcnt vmcnt(6)
	s_barrier
	s_setprio 1
	v_mfma_f32_16x16x32_bf16 v[54:57], v[226:229], v[194:197], v[54:57]
	v_mfma_f32_16x16x32_bf16 v[54:57], v[230:233], v[198:201], v[54:57]
	v_mfma_f32_16x16x32_bf16 v[50:53], v[234:237], v[194:197], v[50:53]
	ds_read_b128 v[194:197], v166
	v_mfma_f32_16x16x32_bf16 v[50:53], v[238:241], v[198:201], v[50:53]
	ds_read_b128 v[198:201], v166 offset:1024
	v_mfma_f32_16x16x32_bf16 v[38:41], v[226:229], v[202:205], v[38:41]
	v_mfma_f32_16x16x32_bf16 v[38:41], v[230:233], v[206:209], v[38:41]
	v_mfma_f32_16x16x32_bf16 v[34:37], v[234:237], v[202:205], v[34:37]
	ds_read_b128 v[202:205], v166 offset:2048
	v_mfma_f32_16x16x32_bf16 v[34:37], v[238:241], v[206:209], v[34:37]
	ds_read_b128 v[206:209], v166 offset:3072
	v_mfma_f32_16x16x32_bf16 v[22:25], v[226:229], v[210:213], v[22:25]
	v_mfma_f32_16x16x32_bf16 v[22:25], v[230:233], v[214:217], v[22:25]
	v_mfma_f32_16x16x32_bf16 v[18:21], v[234:237], v[210:213], v[18:21]
	ds_read_b128 v[210:213], v166 offset:4096
	v_mfma_f32_16x16x32_bf16 v[18:21], v[238:241], v[214:217], v[18:21]
	ds_read_b128 v[214:217], v166 offset:5120
	v_mfma_f32_16x16x32_bf16 v[6:9], v[226:229], v[218:221], v[6:9]
	v_mfma_f32_16x16x32_bf16 v[6:9], v[230:233], v[222:225], v[6:9]
	v_mfma_f32_16x16x32_bf16 v[2:5], v[234:237], v[218:221], v[2:5]
	s_barrier
	v_mfma_f32_16x16x32_bf16 v[2:5], v[238:241], v[222:225], v[2:5]
	s_setprio 0
	s_add_i32 s38, s38, 2
	s_add_u32 s35, s35, 0x100
	s_addc_u32 s50, s50, 0
	s_add_u32 s0, s0, 0x100
	s_addc_u32 s1, s1, 0
	s_cmp_gt_u32 s38, 13
	s_cbranch_scc0 .LBB0_557
	s_waitcnt lgkmcnt(0)
	s_and_b64 vcc, exec, s[42:43]
	s_cbranch_vccz .LBB0_560
	s_barrier

; #define PG8_STAGE(bufoff, gbase, voff) do { _Pragma("unroll") for (int _i = 0; _i < 2; ++_i) \
;         __builtin_amdgcn_global_load_lds((const unsigned*)((const char*)(gbase) + (voff)[_i]), (LAS unsigned*)(lds + (bufoff) + ldsw + _i * 8192), 16, 0, 0); } while (0)
; #define PG8_LDA(dst, b, h) do { _Pragma("unroll") for (int m = 0; m < 4; ++m) _Pragma("unroll") for (int k = 0; k < 2; ++k) dst[m][k] = *(const LAS bf16x8*)(lds + PG8_SA(b, h) + aoff + m * 2048 + k * 1024); } while (0)
; #define PG8_LDB(dst, b, h) do { _Pragma("unroll") for (int n = 0; n < 2; ++n) _Pragma("unroll") for (int k = 0; k < 2; ++k) dst[n][k] = *(const LAS bf16x8*)(lds + PG8_SB(b, h) + boff + n * 2048 + k * 1024); } while (0)
; #define PG8_MMA(ai, bj, At, Bt) do { __builtin_amdgcn_s_setprio(1); _Pragma("unroll") for (int m = 0; m < 4; ++m) _Pragma("unroll") for (int n = 0; n < 2; ++n) _Pragma("unroll") for (int k = 0; k < 2; ++k) \
;         acc[ai][bj][m][n] = __builtin_amdgcn_mfma_f32_16x16x32_bf16(Bt[n][k], At[m][k], acc[ai][bj][m][n], 0, 0, 0); __builtin_amdgcn_s_setprio(0); } while (0)
; #define PG8_WAIT_L(n) asm volatile("s_waitcnt lgkmcnt(" #n ")" ::: "memory")
; template <class Epi, class Sched>
; __device__ __forceinline__ void gemm_phase(LAS unsigned char* lds, const Gemm g, const Sched& S, const Epi& E) {
;     ...
;         const bool has_next = S.next(ui + 1, nxt);
;         const char* nA = has_next ? PG8_APANEL(nxt.pm) : cA; const char* nB = has_next ? (const char*)g.Bt + (size_t)nxt.pn * tstep : cB;
;         for (int t = 0; t < nt; t += 2) {
;             const bool last = (t == nt - 2);
;             const char* a1 = cA + (size_t)(t + 1) * kstep;
;             const char* a2 = last ? nA : cA + (size_t)(t + 2) * kstep; const char* b2 = last ? nB : cB + (size_t)(t + 2) * kstep;
;             const char* a3 = a2 + kstep; const char* b3 = b2 + kstep;
;             PG8_LDB(B0, 0, 0); PG8_SCHED; PG8_LDA(At, 0, 0); PG8_STAGE(PG8_SA(1, 1), a1 + hstep, voffA);
;             PG8_WAIT_L(8); PG8_BAR; PG8_WAIT_L(0); PG8_MMA(0, 0, At, B0); PG8_BAR; PG8_SCHED;
;             PG8_LDB(B1, 0, 1); PG8_STAGE(PG8_SB(0, 0), b2, voffB);
;             PG8_BAR; PG8_WAIT_L(0); PG8_MMA(0, 1, At, B1); PG8_BAR;
;             PG8_LDA(At, 0, 1); PG8_STAGE(PG8_SA(0, 0), a2, voffA);
;             PG8_BAR; PG8_WAIT_L(0); PG8_MMA(1, 0, At, B0); PG8_BAR; PG8_SCHED;
.LBB0_626:
	s_ashr_i32 s43, s42, 31
	s_lshl_b64 s[24:25], s[42:43], 21
	s_add_u32 s60, s55, s24
	s_addc_u32 s61, s82, s25
	s_and_b64 s[0:1], s[0:1], exec
	s_cselect_b32 s43, s61, s49
	s_cselect_b32 s45, s60, s48
	s_add_u32 s35, s48, 0x100
	s_addc_u32 s50, s49, 0
	s_add_u32 s0, s76, 0x100080
	s_addc_u32 s1, s77, 0
	s_mov_b32 s98, -2
	v_add_u32_e32 v249, 0x10000, v144
	ds_read_b128 v[164:167], v249
	ds_read_b128 v[182:185], v249 offset:1024
	ds_read_b128 v[186:189], v249 offset:2048
	ds_read_b128 v[190:193], v249 offset:3072
	ds_read_b128 v[194:197], v162
	ds_read_b128 v[198:201], v162 offset:1024
	ds_read_b128 v[202:205], v162 offset:2048
	ds_read_b128 v[206:209], v162 offset:3072
	ds_read_b128 v[210:213], v162 offset:4096
	ds_read_b128 v[214:217], v162 offset:5120
	s_add_u32 s24, s0, 0xfff00080
	s_addc_u32 s25, s1, -1
	s_add_i32 s51, 0, 0x10000
	s_cmp_eq_u32 s98, 60
	s_cselect_b32 s77, s47, s25
	s_cselect_b32 s76, s46, s24
	s_cselect_b32 s49, s43, s50
	s_cselect_b32 s48, s45, s35
	s_add_i32 m0, s86, 0xc000
	ds_read_b128 v[218:221], v162 offset:6144
	ds_read_b128 v[222:225], v162 offset:7168
	global_load_lds_dwordx4 v140, s[0:1]
	s_add_i32 m0, s86, 0xe000
	s_nop 0
	global_load_lds_dwordx4 v138, s[0:1]
	s_waitcnt lgkmcnt(8)
	s_barrier
	s_waitcnt lgkmcnt(0)
	s_setprio 1
	s_waitcnt lgkmcnt(0)
	v_mfma_f32_16x16x32_bf16 v[126:129], v[164:167], v[194:197], 0
	v_mfma_f32_16x16x32_bf16 v[126:129], v[182:185], v[198:201], v[126:129]
	v_mfma_f32_16x16x32_bf16 v[122:125], v[186:189], v[194:197], 0
	v_mfma_f32_16x16x32_bf16 v[122:125], v[190:193], v[198:201], v[122:125]
	v_mfma_f32_16x16x32_bf16 v[118:121], v[164:167], v[202:205], 0
	v_mfma_f32_16x16x32_bf16 v[118:121], v[182:185], v[206:209], v[118:121]
	v_mfma_f32_16x16x32_bf16 v[110:113], v[186:189], v[202:205], 0
	v_mfma_f32_16x16x32_bf16 v[110:113], v[190:193], v[206:209], v[110:113]
	v_mfma_f32_16x16x32_bf16 v[102:105], v[164:167], v[210:213], 0
	v_mfma_f32_16x16x32_bf16 v[102:105], v[182:185], v[214:217], v[102:105]
	v_mfma_f32_16x16x32_bf16 v[94:97], v[186:189], v[210:213], 0
	v_mfma_f32_16x16x32_bf16 v[94:97], v[190:193], v[214:217], v[94:97]
	v_mfma_f32_16x16x32_bf16 v[86:89], v[164:167], v[218:221], 0
	v_mfma_f32_16x16x32_bf16 v[86:89], v[182:185], v[222:225], v[86:89]
	v_mfma_f32_16x16x32_bf16 v[78:81], v[186:189], v[218:221], 0
	s_barrier
	v_mfma_f32_16x16x32_bf16 v[78:81], v[190:193], v[222:225], v[78:81]
	s_setprio 0
	s_add_i32 s99, 0, 0x14000
	s_add_i32 s24, s51, s83
	ds_read_b128 v[226:229], v249 offset:16384
	ds_read_b128 v[230:233], v249 offset:17408
	ds_read_b128 v[234:237], v249 offset:18432
	ds_read_b128 v[238:241], v249 offset:19456
	s_mov_b32 m0, s24
	global_load_lds_dwordx4 v134, s[48:49]
	s_add_i32 m0, s24, 0x2000
	s_nop 0
	global_load_lds_dwordx4 v130, s[48:49]
	s_barrier
	s_waitcnt lgkmcnt(0)
	s_setprio 1
	s_waitcnt lgkmcnt(0)
	v_mfma_f32_16x16x32_bf16 v[114:117], v[226:229], v[194:197], 0
	v_mfma_f32_16x16x32_bf16 v[114:117], v[230:233], v[198:201], v[114:117]
	v_mfma_f32_16x16x32_bf16 v[106:109], v[234:237], v[194:197], 0
	v_mfma_f32_16x16x32_bf16 v[106:109], v[238:241], v[198:201], v[106:109]
	v_mfma_f32_16x16x32_bf16 v[98:101], v[226:229], v[202:205], 0
	v_mfma_f32_16x16x32_bf16 v[98:101], v[230:233], v[206:209], v[98:101]
	v_mfma_f32_16x16x32_bf16 v[90:93], v[234:237], v[202:205], 0
	v_mfma_f32_16x16x32_bf16 v[90:93], v[238:241], v[206:209], v[90:93]
	v_mfma_f32_16x16x32_bf16 v[82:85], v[226:229], v[210:213], 0
	v_mfma_f32_16x16x32_bf16 v[82:85], v[230:233], v[214:217], v[82:85]
	v_mfma_f32_16x16x32_bf16 v[74:77], v[234:237], v[210:213], 0
	v_mfma_f32_16x16x32_bf16 v[74:77], v[238:241], v[214:217], v[74:77]
	v_mfma_f32_16x16x32_bf16 v[70:73], v[226:229], v[218:221], 0
	v_mfma_f32_16x16x32_bf16 v[70:73], v[230:233], v[222:225], v[70:73]
	v_mfma_f32_16x16x32_bf16 v[66:69], v[234:237], v[218:221], 0
	s_barrier
	v_mfma_f32_16x16x32_bf16 v[66:69], v[238:241], v[222:225], v[66:69]
	s_setprio 0
	s_mov_b32 m0, s86
	s_mov_b64 s[100:101], s[76:77]
	ds_read_b128 v[194:197], v162 offset:16384
	ds_read_b128 v[198:201], v162 offset:17408
	ds_read_b128 v[202:205], v162 offset:18432
	ds_read_b128 v[206:209], v162 offset:19456
	ds_read_b128 v[210:213], v162 offset:20480
	ds_read_b128 v[214:217], v162 offset:21504
	ds_read_b128 v[218:221], v162 offset:22528
	ds_read_b128 v[222:225], v162 offset:23552
	global_load_lds_dwordx4 v136, s[76:77]
	s_mov_b64 s[100:101], s[76:77]
	s_mov_b32 m0, s92
	s_nop 0
	global_load_lds_dwordx4 v132, s[76:77]
	s_waitcnt vmcnt(8)
	s_barrier
	s_waitcnt lgkmcnt(0)
	s_setprio 1
	s_waitcnt lgkmcnt(0)
	v_mfma_f32_16x16x32_bf16 v[62:65], v[164:167], v[194:197], 0
	v_mfma_f32_16x16x32_bf16 v[62:65], v[182:185], v[198:201], v[62:65]
	v_mfma_f32_16x16x32_bf16 v[58:61], v[186:189], v[194:197], 0
	v_mfma_f32_16x16x32_bf16 v[58:61], v[190:193], v[198:201], v[58:61]
	v_mfma_f32_16x16x32_bf16 v[54:57], v[164:167], v[202:205], 0
	v_mfma_f32_16x16x32_bf16 v[54:57], v[182:185], v[206:209], v[54:57]
	v_mfma_f32_16x16x32_bf16 v[46:49], v[186:189], v[202:205], 0
	v_mfma_f32_16x16x32_bf16 v[46:49], v[190:193], v[206:209], v[46:49]
	v_mfma_f32_16x16x32_bf16 v[38:41], v[164:167], v[210:213], 0
	v_mfma_f32_16x16x32_bf16 v[38:41], v[182:185], v[214:217], v[38:41]
	v_mfma_f32_16x16x32_bf16 v[30:33], v[186:189], v[210:213], 0
	v_mfma_f32_16x16x32_bf16 v[30:33], v[190:193], v[214:217], v[30:33]
	v_mfma_f32_16x16x32_bf16 v[22:25], v[164:167], v[218:221], 0
	v_mfma_f32_16x16x32_bf16 v[22:25], v[182:185], v[222:225], v[22:25]
	v_mfma_f32_16x16x32_bf16 v[14:17], v[186:189], v[218:221], 0
	s_barrier
; #define PG8_STAGE(bufoff, gbase, voff) do { _Pragma("unroll") for (int _i = 0; _i < 2; ++_i) \
;         __builtin_amdgcn_global_load_lds((const unsigned*)((const char*)(gbase) + (voff)[_i]), (LAS unsigned*)(lds + (bufoff) + ldsw + _i * 8192), 16, 0, 0); } while (0)
; #define PG8_LDA(dst, b, h) do { _Pragma("unroll") for (int m = 0; m < 4; ++m) _Pragma("unroll") for (int k = 0; k < 2; ++k) dst[m][k] = *(const LAS bf16x8*)(lds + PG8_SA(b, h) + aoff + m * 2048 + k * 1024); } while (0)
; #define PG8_LDB(dst, b, h) do { _Pragma("unroll") for (int n = 0; n < 2; ++n) _Pragma("unroll") for (int k = 0; k < 2; ++k) dst[n][k] = *(const LAS bf16x8*)(lds + PG8_SB(b, h) + boff + n * 2048 + k * 1024); } while (0)
; #define PG8_MMA(ai, bj, At, Bt) do { __builtin_amdgcn_s_setprio(1); _Pragma("unroll") for (int m = 0; m < 4; ++m) _Pragma("unroll") for (int n = 0; n < 2; ++n) _Pragma("unroll") for (int k = 0; k < 2; ++k) \
;         acc[ai][bj][m][n] = __builtin_amdgcn_mfma_f32_16x16x32_bf16(Bt[n][k], At[m][k], acc[ai][bj][m][n], 0, 0, 0); __builtin_amdgcn_s_setprio(0); } while (0)
; #define PG8_WAIT_V(n) asm volatile("s_waitcnt vmcnt(" #n ")" ::: "memory")
; #define PG8_WAIT_L(n) asm volatile("s_waitcnt lgkmcnt(" #n ")" ::: "memory")
; #define PG8_BAR __builtin_amdgcn_s_barrier()
; #define PG8_SCHED __builtin_amdgcn_sched_barrier(0)
; template <class Epi, class Sched>
; __device__ __forceinline__ void gemm_phase(LAS unsigned char* lds, const Gemm g, const Sched& S, const Epi& E) {
;     ...
;             PG8_STAGE(PG8_SB(0, 1), b2 + hstep, voffB);
;             PG8_WAIT_V(6); PG8_BAR; PG8_MMA(1, 1, At, B1); PG8_BAR;
;             PG8_LDB(B0, 1, 0); PG8_SCHED; PG8_LDA(At, 1, 0); PG8_STAGE(PG8_SA(0, 1), a2 + hstep, voffA);
;             PG8_WAIT_L(8); PG8_BAR; PG8_WAIT_L(0); PG8_MMA(0, 0, At, B0); PG8_BAR; PG8_SCHED;
;             PG8_LDB(B1, 1, 1); PG8_STAGE(PG8_SB(1, 0), b3, voffB);
;             PG8_BAR; PG8_WAIT_L(0); PG8_MMA(0, 1, At, B1); PG8_BAR;
;             PG8_LDA(At, 1, 1); PG8_STAGE(PG8_SA(1, 0), a3, voffA);
;             PG8_BAR; PG8_WAIT_L(0); PG8_MMA(1, 0, At, B0); PG8_BAR; PG8_SCHED;
	v_mfma_f32_16x16x32_bf16 v[14:17], v[190:193], v[222:225], v[14:17]
	s_setprio 0
	s_add_u32 s24, s48, 0x100000
	s_addc_u32 s25, s49, 0
	s_add_i32 s51, s99, s83
	s_mov_b32 m0, s51
	s_nop 0
	global_load_lds_dwordx4 v134, s[24:25]
	s_add_i32 m0, s51, 0x2000
	s_nop 0
	global_load_lds_dwordx4 v130, s[24:25]
	ds_read_b128 v[164:167], v249 offset:32768
	ds_read_b128 v[182:185], v249 offset:33792
	ds_read_b128 v[186:189], v249 offset:34816
	ds_read_b128 v[190:193], v249 offset:35840
	s_waitcnt vmcnt(6)
	s_barrier
	s_setprio 1
	v_mfma_f32_16x16x32_bf16 v[50:53], v[226:229], v[194:197], 0
	v_mfma_f32_16x16x32_bf16 v[50:53], v[230:233], v[198:201], v[50:53]
	v_mfma_f32_16x16x32_bf16 v[42:45], v[234:237], v[194:197], 0
	ds_read_b128 v[194:197], v162 offset:32768
	v_mfma_f32_16x16x32_bf16 v[42:45], v[238:241], v[198:201], v[42:45]
	ds_read_b128 v[198:201], v162 offset:33792
	v_mfma_f32_16x16x32_bf16 v[34:37], v[226:229], v[202:205], 0
	v_mfma_f32_16x16x32_bf16 v[34:37], v[230:233], v[206:209], v[34:37]
	v_mfma_f32_16x16x32_bf16 v[26:29], v[234:237], v[202:205], 0
	ds_read_b128 v[202:205], v162 offset:34816
	v_mfma_f32_16x16x32_bf16 v[26:29], v[238:241], v[206:209], v[26:29]
	ds_read_b128 v[206:209], v162 offset:35840
	v_mfma_f32_16x16x32_bf16 v[18:21], v[226:229], v[210:213], 0
	v_mfma_f32_16x16x32_bf16 v[18:21], v[230:233], v[214:217], v[18:21]
	v_mfma_f32_16x16x32_bf16 v[10:13], v[234:237], v[210:213], 0
	ds_read_b128 v[210:213], v162 offset:36864
	v_mfma_f32_16x16x32_bf16 v[10:13], v[238:241], v[214:217], v[10:13]
	ds_read_b128 v[214:217], v162 offset:37888
	v_mfma_f32_16x16x32_bf16 v[6:9], v[226:229], v[218:221], 0
	v_mfma_f32_16x16x32_bf16 v[6:9], v[230:233], v[222:225], v[6:9]
	v_mfma_f32_16x16x32_bf16 v[2:5], v[234:237], v[218:221], 0
	s_barrier
	v_mfma_f32_16x16x32_bf16 v[2:5], v[238:241], v[222:225], v[2:5]
	s_setprio 0
	s_add_i32 s51, 0, 0x18000
	s_add_u32 s24, s76, 0x100000
	s_addc_u32 s25, s77, 0
	s_mov_b32 m0, s93
	ds_read_b128 v[218:221], v162 offset:38912
	ds_read_b128 v[222:225], v162 offset:39936
	global_load_lds_dwordx4 v136, s[24:25]
	s_mov_b32 m0, s94
	s_nop 0
	global_load_lds_dwordx4 v132, s[24:25]
	s_waitcnt lgkmcnt(8)
	s_barrier
	s_waitcnt lgkmcnt(0)
	s_setprio 1
	s_waitcnt lgkmcnt(0)
	v_mfma_f32_16x16x32_bf16 v[126:129], v[164:167], v[194:197], v[126:129]
	v_mfma_f32_16x16x32_bf16 v[126:129], v[182:185], v[198:201], v[126:129]
	v_mfma_f32_16x16x32_bf16 v[122:125], v[186:189], v[194:197], v[122:125]
	v_mfma_f32_16x16x32_bf16 v[122:125], v[190:193], v[198:201], v[122:125]
	v_mfma_f32_16x16x32_bf16 v[118:121], v[164:167], v[202:205], v[118:121]
	v_mfma_f32_16x16x32_bf16 v[118:121], v[182:185], v[206:209], v[118:121]
	v_mfma_f32_16x16x32_bf16 v[110:113], v[186:189], v[202:205], v[110:113]
	v_mfma_f32_16x16x32_bf16 v[110:113], v[190:193], v[206:209], v[110:113]
	v_mfma_f32_16x16x32_bf16 v[102:105], v[164:167], v[210:213], v[102:105]
	v_mfma_f32_16x16x32_bf16 v[102:105], v[182:185], v[214:217], v[102:105]
	v_mfma_f32_16x16x32_bf16 v[94:97], v[186:189], v[210:213], v[94:97]
	v_mfma_f32_16x16x32_bf16 v[94:97], v[190:193], v[214:217], v[94:97]
	v_mfma_f32_16x16x32_bf16 v[86:89], v[164:167], v[218:221], v[86:89]
	v_mfma_f32_16x16x32_bf16 v[86:89], v[182:185], v[222:225], v[86:89]
	v_mfma_f32_16x16x32_bf16 v[78:81], v[186:189], v[218:221], v[78:81]
	s_barrier
	v_mfma_f32_16x16x32_bf16 v[78:81], v[190:193], v[222:225], v[78:81]
	s_setprio 0
	s_add_i32 s76, 0, 0x1c000
	s_add_i32 s24, s51, s83
	s_add_i32 m0, s24, 0xffffff80
	ds_read_b128 v[226:229], v249 offset:49152
	ds_read_b128 v[230:233], v249 offset:50176
	ds_read_b128 v[234:237], v249 offset:51200
	ds_read_b128 v[238:241], v249 offset:52224
	global_load_lds_dwordx4 v134, s[48:49] offset:128
	s_add_i32 m0, s24, 0x1f80
	s_nop 0
	global_load_lds_dwordx4 v130, s[48:49] offset:128
	s_barrier
	s_waitcnt lgkmcnt(0)
	s_setprio 1
	s_waitcnt lgkmcnt(0)
	v_mfma_f32_16x16x32_bf16 v[114:117], v[226:229], v[194:197], v[114:117]
	v_mfma_f32_16x16x32_bf16 v[114:117], v[230:233], v[198:201], v[114:117]
	v_mfma_f32_16x16x32_bf16 v[106:109], v[234:237], v[194:197], v[106:109]
	v_mfma_f32_16x16x32_bf16 v[106:109], v[238:241], v[198:201], v[106:109]
	v_mfma_f32_16x16x32_bf16 v[98:101], v[226:229], v[202:205], v[98:101]
	v_mfma_f32_16x16x32_bf16 v[98:101], v[230:233], v[206:209], v[98:101]
	v_mfma_f32_16x16x32_bf16 v[90:93], v[234:237], v[202:205], v[90:93]
	v_mfma_f32_16x16x32_bf16 v[90:93], v[238:241], v[206:209], v[90:93]
	v_mfma_f32_16x16x32_bf16 v[82:85], v[226:229], v[210:213], v[82:85]
	v_mfma_f32_16x16x32_bf16 v[82:85], v[230:233], v[214:217], v[82:85]
	v_mfma_f32_16x16x32_bf16 v[74:77], v[234:237], v[210:213], v[74:77]
	v_mfma_f32_16x16x32_bf16 v[74:77], v[238:241], v[214:217], v[74:77]
	v_mfma_f32_16x16x32_bf16 v[70:73], v[226:229], v[218:221], v[70:73]
	v_mfma_f32_16x16x32_bf16 v[70:73], v[230:233], v[222:225], v[70:73]
	v_mfma_f32_16x16x32_bf16 v[66:69], v[234:237], v[218:221], v[66:69]
	s_barrier
	v_mfma_f32_16x16x32_bf16 v[66:69], v[238:241], v[222:225], v[66:69]
	s_setprio 0
	s_add_i32 m0, s95, 0xffffff80
	ds_read_b128 v[194:197], v162 offset:49152
	ds_read_b128 v[198:201], v162 offset:50176
	ds_read_b128 v[202:205], v162 offset:51200
	ds_read_b128 v[206:209], v162 offset:52224
	ds_read_b128 v[210:213], v162 offset:53248
	ds_read_b128 v[214:217], v162 offset:54272
	ds_read_b128 v[218:221], v162 offset:55296
	ds_read_b128 v[222:225], v162 offset:56320
	global_load_lds_dwordx4 v136, s[100:101] offset:128
	s_add_i32 m0, s96, 0xffffff80
	s_nop 0
	global_load_lds_dwordx4 v132, s[100:101] offset:128
	s_waitcnt vmcnt(8)
	s_barrier
; #define PG8_STAGE(bufoff, gbase, voff) do { _Pragma("unroll") for (int _i = 0; _i < 2; ++_i) \
;         __builtin_amdgcn_global_load_lds((const unsigned*)((const char*)(gbase) + (voff)[_i]), (LAS unsigned*)(lds + (bufoff) + ldsw + _i * 8192), 16, 0, 0); } while (0)
; #define PG8_LDA(dst, b, h) do { _Pragma("unroll") for (int m = 0; m < 4; ++m) _Pragma("unroll") for (int k = 0; k < 2; ++k) dst[m][k] = *(const LAS bf16x8*)(lds + PG8_SA(b, h) + aoff + m * 2048 + k * 1024); } while (0)
; #define PG8_LDB(dst, b, h) do { _Pragma("unroll") for (int n = 0; n < 2; ++n) _Pragma("unroll") for (int k = 0; k < 2; ++k) dst[n][k] = *(const LAS bf16x8*)(lds + PG8_SB(b, h) + boff + n * 2048 + k * 1024); } while (0)
; #define PG8_MMA(ai, bj, At, Bt) do { __builtin_amdgcn_s_setprio(1); _Pragma("unroll") for (int m = 0; m < 4; ++m) _Pragma("unroll") for (int n = 0; n < 2; ++n) _Pragma("unroll") for (int k = 0; k < 2; ++k) \
;         acc[ai][bj][m][n] = __builtin_amdgcn_mfma_f32_16x16x32_bf16(Bt[n][k], At[m][k], acc[ai][bj][m][n], 0, 0, 0); __builtin_amdgcn_s_setprio(0); } while (0)
; #define PG8_WAIT_V(n) asm volatile("s_waitcnt vmcnt(" #n ")" ::: "memory")
; #define PG8_WAIT_L(n) asm volatile("s_waitcnt lgkmcnt(" #n ")" ::: "memory")
; #define PG8_BAR __builtin_amdgcn_s_barrier()
; #define PG8_SCHED __builtin_amdgcn_sched_barrier(0)
; template <class Epi, class Sched>
; __device__ __forceinline__ void gemm_phase(LAS unsigned char* lds, const Gemm g, const Sched& S, const Epi& E) {
;     ...
;         for (int t = 0; t < nt; t += 2) {
;             const bool last = (t == nt - 2);
;             const char* a1 = cA + (size_t)(t + 1) * kstep;
;             const char* a2 = last ? nA : cA + (size_t)(t + 2) * kstep; const char* b2 = last ? nB : cB + (size_t)(t + 2) * kstep;
;             const char* a3 = a2 + kstep; const char* b3 = b2 + kstep;
;             PG8_LDB(B0, 0, 0); PG8_SCHED; PG8_LDA(At, 0, 0); PG8_STAGE(PG8_SA(1, 1), a1 + hstep, voffA);
;             PG8_WAIT_L(8); PG8_BAR; PG8_WAIT_L(0); PG8_MMA(0, 0, At, B0); PG8_BAR; PG8_SCHED;
;             PG8_LDB(B1, 0, 1); PG8_STAGE(PG8_SB(0, 0), b2, voffB);
;             PG8_BAR; PG8_WAIT_L(0); PG8_MMA(0, 1, At, B1); PG8_BAR;
;     ...
;             PG8_BAR; PG8_WAIT_L(0); PG8_MMA(1, 0, At, B0); PG8_BAR; PG8_SCHED;
;             PG8_STAGE(PG8_SB(1, 1), b3 + hstep, voffB);
;             PG8_WAIT_V(6); PG8_BAR; PG8_MMA(1, 1, At, B1); PG8_BAR;
	s_waitcnt lgkmcnt(0)
	s_setprio 1
	s_waitcnt lgkmcnt(0)
	v_mfma_f32_16x16x32_bf16 v[62:65], v[164:167], v[194:197], v[62:65]
	v_mfma_f32_16x16x32_bf16 v[62:65], v[182:185], v[198:201], v[62:65]
	v_mfma_f32_16x16x32_bf16 v[58:61], v[186:189], v[194:197], v[58:61]
	v_mfma_f32_16x16x32_bf16 v[58:61], v[190:193], v[198:201], v[58:61]
	v_mfma_f32_16x16x32_bf16 v[54:57], v[164:167], v[202:205], v[54:57]
	v_mfma_f32_16x16x32_bf16 v[54:57], v[182:185], v[206:209], v[54:57]
	v_mfma_f32_16x16x32_bf16 v[46:49], v[186:189], v[202:205], v[46:49]
	v_mfma_f32_16x16x32_bf16 v[46:49], v[190:193], v[206:209], v[46:49]
	v_mfma_f32_16x16x32_bf16 v[38:41], v[164:167], v[210:213], v[38:41]
	v_mfma_f32_16x16x32_bf16 v[38:41], v[182:185], v[214:217], v[38:41]
	v_mfma_f32_16x16x32_bf16 v[30:33], v[186:189], v[210:213], v[30:33]
	v_mfma_f32_16x16x32_bf16 v[30:33], v[190:193], v[214:217], v[30:33]
	v_mfma_f32_16x16x32_bf16 v[22:25], v[164:167], v[218:221], v[22:25]
	v_mfma_f32_16x16x32_bf16 v[22:25], v[182:185], v[222:225], v[22:25]
	v_mfma_f32_16x16x32_bf16 v[14:17], v[186:189], v[218:221], v[14:17]
	s_barrier
	v_mfma_f32_16x16x32_bf16 v[14:17], v[190:193], v[222:225], v[14:17]
	s_setprio 0
	s_add_u32 s24, s48, 0x100080
	s_addc_u32 s25, s49, 0
	s_add_i32 s48, s76, s83
	s_mov_b32 m0, s48
	s_nop 0
	global_load_lds_dwordx4 v134, s[24:25]
	s_add_i32 m0, s48, 0x2000
	s_nop 0
	global_load_lds_dwordx4 v130, s[24:25]
	ds_read_b128 v[164:167], v249
	ds_read_b128 v[182:185], v249 offset:1024
	ds_read_b128 v[186:189], v249 offset:2048
	ds_read_b128 v[190:193], v249 offset:3072
	s_waitcnt vmcnt(6)
	s_barrier
	s_setprio 1
	v_mfma_f32_16x16x32_bf16 v[50:53], v[226:229], v[194:197], v[50:53]
	v_mfma_f32_16x16x32_bf16 v[50:53], v[230:233], v[198:201], v[50:53]
	v_mfma_f32_16x16x32_bf16 v[42:45], v[234:237], v[194:197], v[42:45]
	ds_read_b128 v[194:197], v162
	v_mfma_f32_16x16x32_bf16 v[42:45], v[238:241], v[198:201], v[42:45]
	ds_read_b128 v[198:201], v162 offset:1024
	v_mfma_f32_16x16x32_bf16 v[34:37], v[226:229], v[202:205], v[34:37]
	v_mfma_f32_16x16x32_bf16 v[34:37], v[230:233], v[206:209], v[34:37]
	v_mfma_f32_16x16x32_bf16 v[26:29], v[234:237], v[202:205], v[26:29]
	ds_read_b128 v[202:205], v162 offset:2048
	v_mfma_f32_16x16x32_bf16 v[26:29], v[238:241], v[206:209], v[26:29]
	ds_read_b128 v[206:209], v162 offset:3072
	v_mfma_f32_16x16x32_bf16 v[18:21], v[226:229], v[210:213], v[18:21]
	v_mfma_f32_16x16x32_bf16 v[18:21], v[230:233], v[214:217], v[18:21]
	v_mfma_f32_16x16x32_bf16 v[10:13], v[234:237], v[210:213], v[10:13]
	ds_read_b128 v[210:213], v162 offset:4096
	v_mfma_f32_16x16x32_bf16 v[10:13], v[238:241], v[214:217], v[10:13]
	ds_read_b128 v[214:217], v162 offset:5120
	v_mfma_f32_16x16x32_bf16 v[6:9], v[226:229], v[218:221], v[6:9]
	v_mfma_f32_16x16x32_bf16 v[6:9], v[230:233], v[222:225], v[6:9]
	v_mfma_f32_16x16x32_bf16 v[2:5], v[234:237], v[218:221], v[2:5]
	s_barrier
	v_mfma_f32_16x16x32_bf16 v[2:5], v[238:241], v[222:225], v[2:5]
	s_setprio 0
	s_add_i32 s98, s98, 2
	s_add_u32 s35, s35, 0x100
	s_addc_u32 s50, s50, 0
	s_add_u32 s0, s0, 0x100
	s_addc_u32 s1, s1, 0
	s_cmp_gt_u32 s98, 61
.LBB0_627:
	s_add_u32 s24, s0, 0xfff00080
	s_addc_u32 s25, s1, -1
	s_add_i32 s51, 0, 0x10000
	s_cmp_eq_u32 s98, 60
	s_cselect_b32 s77, s47, s25
	s_cselect_b32 s76, s46, s24
	s_cselect_b32 s49, s43, s50
	s_cselect_b32 s48, s45, s35
	s_add_i32 m0, s86, 0xc000
	ds_read_b128 v[218:221], v162 offset:6144
	ds_read_b128 v[222:225], v162 offset:7168
	global_load_lds_dwordx4 v140, s[0:1]
	s_add_i32 m0, s86, 0xe000
	s_nop 0
	global_load_lds_dwordx4 v138, s[0:1]
	s_waitcnt lgkmcnt(8)
	s_barrier
	s_waitcnt lgkmcnt(0)
	s_setprio 1
	s_waitcnt lgkmcnt(0)
	v_mfma_f32_16x16x32_bf16 v[126:129], v[164:167], v[194:197], v[126:129]
	v_mfma_f32_16x16x32_bf16 v[126:129], v[182:185], v[198:201], v[126:129]
	v_mfma_f32_16x16x32_bf16 v[122:125], v[186:189], v[194:197], v[122:125]
	v_mfma_f32_16x16x32_bf16 v[122:125], v[190:193], v[198:201], v[122:125]
	v_mfma_f32_16x16x32_bf16 v[118:121], v[164:167], v[202:205], v[118:121]
	v_mfma_f32_16x16x32_bf16 v[118:121], v[182:185], v[206:209], v[118:121]
	v_mfma_f32_16x16x32_bf16 v[110:113], v[186:189], v[202:205], v[110:113]
	v_mfma_f32_16x16x32_bf16 v[110:113], v[190:193], v[206:209], v[110:113]
	v_mfma_f32_16x16x32_bf16 v[102:105], v[164:167], v[210:213], v[102:105]
	v_mfma_f32_16x16x32_bf16 v[102:105], v[182:185], v[214:217], v[102:105]
	v_mfma_f32_16x16x32_bf16 v[94:97], v[186:189], v[210:213], v[94:97]
	v_mfma_f32_16x16x32_bf16 v[94:97], v[190:193], v[214:217], v[94:97]
	v_mfma_f32_16x16x32_bf16 v[86:89], v[164:167], v[218:221], v[86:89]
	v_mfma_f32_16x16x32_bf16 v[86:89], v[182:185], v[222:225], v[86:89]
	v_mfma_f32_16x16x32_bf16 v[78:81], v[186:189], v[218:221], v[78:81]
	s_barrier
	v_mfma_f32_16x16x32_bf16 v[78:81], v[190:193], v[222:225], v[78:81]
	s_setprio 0
	s_add_i32 s99, 0, 0x14000
	s_add_i32 s24, s51, s83
	ds_read_b128 v[226:229], v249 offset:16384
	ds_read_b128 v[230:233], v249 offset:17408
	ds_read_b128 v[234:237], v249 offset:18432
	ds_read_b128 v[238:241], v249 offset:19456
	s_mov_b32 m0, s24
	global_load_lds_dwordx4 v134, s[48:49]
	s_add_i32 m0, s24, 0x2000
	s_nop 0
	global_load_lds_dwordx4 v130, s[48:49]
	s_barrier
; #define PG8_STAGE(bufoff, gbase, voff) do { _Pragma("unroll") for (int _i = 0; _i < 2; ++_i) \
;         __builtin_amdgcn_global_load_lds((const unsigned*)((const char*)(gbase) + (voff)[_i]), (LAS unsigned*)(lds + (bufoff) + ldsw + _i * 8192), 16, 0, 0); } while (0)
; #define PG8_LDA(dst, b, h) do { _Pragma("unroll") for (int m = 0; m < 4; ++m) _Pragma("unroll") for (int k = 0; k < 2; ++k) dst[m][k] = *(const LAS bf16x8*)(lds + PG8_SA(b, h) + aoff + m * 2048 + k * 1024); } while (0)
; #define PG8_LDB(dst, b, h) do { _Pragma("unroll") for (int n = 0; n < 2; ++n) _Pragma("unroll") for (int k = 0; k < 2; ++k) dst[n][k] = *(const LAS bf16x8*)(lds + PG8_SB(b, h) + boff + n * 2048 + k * 1024); } while (0)
; #define PG8_MMA(ai, bj, At, Bt) do { __builtin_amdgcn_s_setprio(1); _Pragma("unroll") for (int m = 0; m < 4; ++m) _Pragma("unroll") for (int n = 0; n < 2; ++n) _Pragma("unroll") for (int k = 0; k < 2; ++k) \
;         acc[ai][bj][m][n] = __builtin_amdgcn_mfma_f32_16x16x32_bf16(Bt[n][k], At[m][k], acc[ai][bj][m][n], 0, 0, 0); __builtin_amdgcn_s_setprio(0); } while (0)
; #define PG8_WAIT_V(n) asm volatile("s_waitcnt vmcnt(" #n ")" ::: "memory")
; #define PG8_WAIT_L(n) asm volatile("s_waitcnt lgkmcnt(" #n ")" ::: "memory")
; #define PG8_BAR __builtin_amdgcn_s_barrier()
; #define PG8_SCHED __builtin_amdgcn_sched_barrier(0)
; template <class Epi, class Sched>
; __device__ __forceinline__ void gemm_phase(LAS unsigned char* lds, const Gemm g, const Sched& S, const Epi& E) {
;     ...
;             PG8_BAR; PG8_WAIT_L(0); PG8_MMA(0, 1, At, B1); PG8_BAR;
;             PG8_LDA(At, 0, 1); PG8_STAGE(PG8_SA(0, 0), a2, voffA);
;             PG8_BAR; PG8_WAIT_L(0); PG8_MMA(1, 0, At, B0); PG8_BAR; PG8_SCHED;
;             PG8_STAGE(PG8_SB(0, 1), b2 + hstep, voffB);
;             PG8_WAIT_V(6); PG8_BAR; PG8_MMA(1, 1, At, B1); PG8_BAR;
;             PG8_LDB(B0, 1, 0); PG8_SCHED; PG8_LDA(At, 1, 0); PG8_STAGE(PG8_SA(0, 1), a2 + hstep, voffA);
;             PG8_WAIT_L(8); PG8_BAR; PG8_WAIT_L(0); PG8_MMA(0, 0, At, B0); PG8_BAR; PG8_SCHED;
	s_waitcnt lgkmcnt(0)
	s_setprio 1
	s_waitcnt lgkmcnt(0)
	v_mfma_f32_16x16x32_bf16 v[114:117], v[226:229], v[194:197], v[114:117]
	v_mfma_f32_16x16x32_bf16 v[114:117], v[230:233], v[198:201], v[114:117]
	v_mfma_f32_16x16x32_bf16 v[106:109], v[234:237], v[194:197], v[106:109]
	v_mfma_f32_16x16x32_bf16 v[106:109], v[238:241], v[198:201], v[106:109]
	v_mfma_f32_16x16x32_bf16 v[98:101], v[226:229], v[202:205], v[98:101]
	v_mfma_f32_16x16x32_bf16 v[98:101], v[230:233], v[206:209], v[98:101]
	v_mfma_f32_16x16x32_bf16 v[90:93], v[234:237], v[202:205], v[90:93]
	v_mfma_f32_16x16x32_bf16 v[90:93], v[238:241], v[206:209], v[90:93]
	v_mfma_f32_16x16x32_bf16 v[82:85], v[226:229], v[210:213], v[82:85]
	v_mfma_f32_16x16x32_bf16 v[82:85], v[230:233], v[214:217], v[82:85]
	v_mfma_f32_16x16x32_bf16 v[74:77], v[234:237], v[210:213], v[74:77]
	v_mfma_f32_16x16x32_bf16 v[74:77], v[238:241], v[214:217], v[74:77]
	v_mfma_f32_16x16x32_bf16 v[70:73], v[226:229], v[218:221], v[70:73]
	v_mfma_f32_16x16x32_bf16 v[70:73], v[230:233], v[222:225], v[70:73]
	v_mfma_f32_16x16x32_bf16 v[66:69], v[234:237], v[218:221], v[66:69]
	s_barrier
	v_mfma_f32_16x16x32_bf16 v[66:69], v[238:241], v[222:225], v[66:69]
	s_setprio 0
	s_mov_b32 m0, s86
	s_mov_b64 s[100:101], s[76:77]
	ds_read_b128 v[194:197], v162 offset:16384
	ds_read_b128 v[198:201], v162 offset:17408
	ds_read_b128 v[202:205], v162 offset:18432
	ds_read_b128 v[206:209], v162 offset:19456
	ds_read_b128 v[210:213], v162 offset:20480
	ds_read_b128 v[214:217], v162 offset:21504
	ds_read_b128 v[218:221], v162 offset:22528
	ds_read_b128 v[222:225], v162 offset:23552
	global_load_lds_dwordx4 v136, s[76:77]
	s_mov_b64 s[100:101], s[76:77]
	s_mov_b32 m0, s92
	s_nop 0
	global_load_lds_dwordx4 v132, s[76:77]
	s_waitcnt vmcnt(8)
	s_barrier
	s_waitcnt lgkmcnt(0)
	s_setprio 1
	s_waitcnt lgkmcnt(0)
	v_mfma_f32_16x16x32_bf16 v[62:65], v[164:167], v[194:197], v[62:65]
	v_mfma_f32_16x16x32_bf16 v[62:65], v[182:185], v[198:201], v[62:65]
	v_mfma_f32_16x16x32_bf16 v[58:61], v[186:189], v[194:197], v[58:61]
	v_mfma_f32_16x16x32_bf16 v[58:61], v[190:193], v[198:201], v[58:61]
	v_mfma_f32_16x16x32_bf16 v[54:57], v[164:167], v[202:205], v[54:57]
	v_mfma_f32_16x16x32_bf16 v[54:57], v[182:185], v[206:209], v[54:57]
	v_mfma_f32_16x16x32_bf16 v[46:49], v[186:189], v[202:205], v[46:49]
	v_mfma_f32_16x16x32_bf16 v[46:49], v[190:193], v[206:209], v[46:49]
	v_mfma_f32_16x16x32_bf16 v[38:41], v[164:167], v[210:213], v[38:41]
	v_mfma_f32_16x16x32_bf16 v[38:41], v[182:185], v[214:217], v[38:41]
	v_mfma_f32_16x16x32_bf16 v[30:33], v[186:189], v[210:213], v[30:33]
	v_mfma_f32_16x16x32_bf16 v[30:33], v[190:193], v[214:217], v[30:33]
	v_mfma_f32_16x16x32_bf16 v[22:25], v[164:167], v[218:221], v[22:25]
	v_mfma_f32_16x16x32_bf16 v[22:25], v[182:185], v[222:225], v[22:25]
	v_mfma_f32_16x16x32_bf16 v[14:17], v[186:189], v[218:221], v[14:17]
	s_barrier
	v_mfma_f32_16x16x32_bf16 v[14:17], v[190:193], v[222:225], v[14:17]
	s_setprio 0
	s_add_u32 s24, s48, 0x100000
	s_addc_u32 s25, s49, 0
	s_add_i32 s51, s99, s83
	s_mov_b32 m0, s51
	s_nop 0
	global_load_lds_dwordx4 v134, s[24:25]
	s_add_i32 m0, s51, 0x2000
	s_nop 0
	global_load_lds_dwordx4 v130, s[24:25]
	ds_read_b128 v[164:167], v249 offset:32768
	ds_read_b128 v[182:185], v249 offset:33792
	ds_read_b128 v[186:189], v249 offset:34816
	ds_read_b128 v[190:193], v249 offset:35840
	s_waitcnt vmcnt(6)
	s_barrier
	s_setprio 1
	v_mfma_f32_16x16x32_bf16 v[50:53], v[226:229], v[194:197], v[50:53]
	v_mfma_f32_16x16x32_bf16 v[50:53], v[230:233], v[198:201], v[50:53]
	v_mfma_f32_16x16x32_bf16 v[42:45], v[234:237], v[194:197], v[42:45]
	ds_read_b128 v[194:197], v162 offset:32768
	v_mfma_f32_16x16x32_bf16 v[42:45], v[238:241], v[198:201], v[42:45]
	ds_read_b128 v[198:201], v162 offset:33792
	v_mfma_f32_16x16x32_bf16 v[34:37], v[226:229], v[202:205], v[34:37]
	v_mfma_f32_16x16x32_bf16 v[34:37], v[230:233], v[206:209], v[34:37]
	v_mfma_f32_16x16x32_bf16 v[26:29], v[234:237], v[202:205], v[26:29]
	ds_read_b128 v[202:205], v162 offset:34816
	v_mfma_f32_16x16x32_bf16 v[26:29], v[238:241], v[206:209], v[26:29]
	ds_read_b128 v[206:209], v162 offset:35840
	v_mfma_f32_16x16x32_bf16 v[18:21], v[226:229], v[210:213], v[18:21]
	v_mfma_f32_16x16x32_bf16 v[18:21], v[230:233], v[214:217], v[18:21]
	v_mfma_f32_16x16x32_bf16 v[10:13], v[234:237], v[210:213], v[10:13]
	ds_read_b128 v[210:213], v162 offset:36864
	v_mfma_f32_16x16x32_bf16 v[10:13], v[238:241], v[214:217], v[10:13]
	ds_read_b128 v[214:217], v162 offset:37888
	v_mfma_f32_16x16x32_bf16 v[6:9], v[226:229], v[218:221], v[6:9]
	v_mfma_f32_16x16x32_bf16 v[6:9], v[230:233], v[222:225], v[6:9]
	v_mfma_f32_16x16x32_bf16 v[2:5], v[234:237], v[218:221], v[2:5]
	s_barrier
	v_mfma_f32_16x16x32_bf16 v[2:5], v[238:241], v[222:225], v[2:5]
	s_setprio 0
	s_add_i32 s51, 0, 0x18000
	s_add_u32 s24, s76, 0x100000
	s_addc_u32 s25, s77, 0
	s_mov_b32 m0, s93
	ds_read_b128 v[218:221], v162 offset:38912
	ds_read_b128 v[222:225], v162 offset:39936
	global_load_lds_dwordx4 v136, s[24:25]
	s_mov_b32 m0, s94
	s_nop 0
	global_load_lds_dwordx4 v132, s[24:25]
	s_waitcnt lgkmcnt(8)
	s_barrier
; #define PG8_STAGE(bufoff, gbase, voff) do { _Pragma("unroll") for (int _i = 0; _i < 2; ++_i) \
;         __builtin_amdgcn_global_load_lds((const unsigned*)((const char*)(gbase) + (voff)[_i]), (LAS unsigned*)(lds + (bufoff) + ldsw + _i * 8192), 16, 0, 0); } while (0)
; #define PG8_LDA(dst, b, h) do { _Pragma("unroll") for (int m = 0; m < 4; ++m) _Pragma("unroll") for (int k = 0; k < 2; ++k) dst[m][k] = *(const LAS bf16x8*)(lds + PG8_SA(b, h) + aoff + m * 2048 + k * 1024); } while (0)
; #define PG8_LDB(dst, b, h) do { _Pragma("unroll") for (int n = 0; n < 2; ++n) _Pragma("unroll") for (int k = 0; k < 2; ++k) dst[n][k] = *(const LAS bf16x8*)(lds + PG8_SB(b, h) + boff + n * 2048 + k * 1024); } while (0)
; #define PG8_MMA(ai, bj, At, Bt) do { __builtin_amdgcn_s_setprio(1); _Pragma("unroll") for (int m = 0; m < 4; ++m) _Pragma("unroll") for (int n = 0; n < 2; ++n) _Pragma("unroll") for (int k = 0; k < 2; ++k) \
;         acc[ai][bj][m][n] = __builtin_amdgcn_mfma_f32_16x16x32_bf16(Bt[n][k], At[m][k], acc[ai][bj][m][n], 0, 0, 0); __builtin_amdgcn_s_setprio(0); } while (0)
; #define PG8_WAIT_V(n) asm volatile("s_waitcnt vmcnt(" #n ")" ::: "memory")
; #define PG8_WAIT_L(n) asm volatile("s_waitcnt lgkmcnt(" #n ")" ::: "memory")
; #define PG8_BAR __builtin_amdgcn_s_barrier()
; #define PG8_SCHED __builtin_amdgcn_sched_barrier(0)
; template <class Epi, class Sched>
; __device__ __forceinline__ void gemm_phase(LAS unsigned char* lds, const Gemm g, const Sched& S, const Epi& E) {
;     ...
;             PG8_WAIT_L(8); PG8_BAR; PG8_WAIT_L(0); PG8_MMA(0, 0, At, B0); PG8_BAR; PG8_SCHED;
;             PG8_LDB(B1, 1, 1); PG8_STAGE(PG8_SB(1, 0), b3, voffB);
;             PG8_BAR; PG8_WAIT_L(0); PG8_MMA(0, 1, At, B1); PG8_BAR;
;             PG8_LDA(At, 1, 1); PG8_STAGE(PG8_SA(1, 0), a3, voffA);
;             PG8_BAR; PG8_WAIT_L(0); PG8_MMA(1, 0, At, B0); PG8_BAR; PG8_SCHED;
;             PG8_STAGE(PG8_SB(1, 1), b3 + hstep, voffB);
;             PG8_WAIT_V(6); PG8_BAR; PG8_MMA(1, 1, At, B1); PG8_BAR;
;         }
;         if (wr == 0) PG8_BAR;
	s_waitcnt lgkmcnt(0)
	s_setprio 1
	s_waitcnt lgkmcnt(0)
	v_mfma_f32_16x16x32_bf16 v[126:129], v[164:167], v[194:197], v[126:129]
	v_mfma_f32_16x16x32_bf16 v[126:129], v[182:185], v[198:201], v[126:129]
	v_mfma_f32_16x16x32_bf16 v[122:125], v[186:189], v[194:197], v[122:125]
	v_mfma_f32_16x16x32_bf16 v[122:125], v[190:193], v[198:201], v[122:125]
	v_mfma_f32_16x16x32_bf16 v[118:121], v[164:167], v[202:205], v[118:121]
	v_mfma_f32_16x16x32_bf16 v[118:121], v[182:185], v[206:209], v[118:121]
	v_mfma_f32_16x16x32_bf16 v[110:113], v[186:189], v[202:205], v[110:113]
	v_mfma_f32_16x16x32_bf16 v[110:113], v[190:193], v[206:209], v[110:113]
	v_mfma_f32_16x16x32_bf16 v[102:105], v[164:167], v[210:213], v[102:105]
	v_mfma_f32_16x16x32_bf16 v[102:105], v[182:185], v[214:217], v[102:105]
	v_mfma_f32_16x16x32_bf16 v[94:97], v[186:189], v[210:213], v[94:97]
	v_mfma_f32_16x16x32_bf16 v[94:97], v[190:193], v[214:217], v[94:97]
	v_mfma_f32_16x16x32_bf16 v[86:89], v[164:167], v[218:221], v[86:89]
	v_mfma_f32_16x16x32_bf16 v[86:89], v[182:185], v[222:225], v[86:89]
	v_mfma_f32_16x16x32_bf16 v[78:81], v[186:189], v[218:221], v[78:81]
	s_barrier
	v_mfma_f32_16x16x32_bf16 v[78:81], v[190:193], v[222:225], v[78:81]
	s_setprio 0
	s_add_i32 s76, 0, 0x1c000
	s_add_i32 s24, s51, s83
	s_add_i32 m0, s24, 0xffffff80
	ds_read_b128 v[226:229], v249 offset:49152
	ds_read_b128 v[230:233], v249 offset:50176
	ds_read_b128 v[234:237], v249 offset:51200
	ds_read_b128 v[238:241], v249 offset:52224
	global_load_lds_dwordx4 v134, s[48:49] offset:128
	s_add_i32 m0, s24, 0x1f80
	s_nop 0
	global_load_lds_dwordx4 v130, s[48:49] offset:128
	s_barrier
	s_waitcnt lgkmcnt(0)
	s_setprio 1
	s_waitcnt lgkmcnt(0)
	v_mfma_f32_16x16x32_bf16 v[114:117], v[226:229], v[194:197], v[114:117]
	v_mfma_f32_16x16x32_bf16 v[114:117], v[230:233], v[198:201], v[114:117]
	v_mfma_f32_16x16x32_bf16 v[106:109], v[234:237], v[194:197], v[106:109]
	v_mfma_f32_16x16x32_bf16 v[106:109], v[238:241], v[198:201], v[106:109]
	v_mfma_f32_16x16x32_bf16 v[98:101], v[226:229], v[202:205], v[98:101]
	v_mfma_f32_16x16x32_bf16 v[98:101], v[230:233], v[206:209], v[98:101]
	v_mfma_f32_16x16x32_bf16 v[90:93], v[234:237], v[202:205], v[90:93]
	v_mfma_f32_16x16x32_bf16 v[90:93], v[238:241], v[206:209], v[90:93]
	v_mfma_f32_16x16x32_bf16 v[82:85], v[226:229], v[210:213], v[82:85]
	v_mfma_f32_16x16x32_bf16 v[82:85], v[230:233], v[214:217], v[82:85]
	v_mfma_f32_16x16x32_bf16 v[74:77], v[234:237], v[210:213], v[74:77]
	v_mfma_f32_16x16x32_bf16 v[74:77], v[238:241], v[214:217], v[74:77]
	v_mfma_f32_16x16x32_bf16 v[70:73], v[226:229], v[218:221], v[70:73]
	v_mfma_f32_16x16x32_bf16 v[70:73], v[230:233], v[222:225], v[70:73]
	v_mfma_f32_16x16x32_bf16 v[66:69], v[234:237], v[218:221], v[66:69]
	s_barrier
	v_mfma_f32_16x16x32_bf16 v[66:69], v[238:241], v[222:225], v[66:69]
	s_setprio 0
	s_add_i32 m0, s95, 0xffffff80
	ds_read_b128 v[194:197], v162 offset:49152
	ds_read_b128 v[198:201], v162 offset:50176
	ds_read_b128 v[202:205], v162 offset:51200
	ds_read_b128 v[206:209], v162 offset:52224
	ds_read_b128 v[210:213], v162 offset:53248
	ds_read_b128 v[214:217], v162 offset:54272
	ds_read_b128 v[218:221], v162 offset:55296
	ds_read_b128 v[222:225], v162 offset:56320
	global_load_lds_dwordx4 v136, s[100:101] offset:128
	s_add_i32 m0, s96, 0xffffff80
	s_nop 0
	global_load_lds_dwordx4 v132, s[100:101] offset:128
	s_waitcnt vmcnt(8)
	s_barrier
	s_waitcnt lgkmcnt(0)
	s_setprio 1
	s_waitcnt lgkmcnt(0)
	v_mfma_f32_16x16x32_bf16 v[62:65], v[164:167], v[194:197], v[62:65]
	v_mfma_f32_16x16x32_bf16 v[62:65], v[182:185], v[198:201], v[62:65]
	v_mfma_f32_16x16x32_bf16 v[58:61], v[186:189], v[194:197], v[58:61]
	v_mfma_f32_16x16x32_bf16 v[58:61], v[190:193], v[198:201], v[58:61]
	v_mfma_f32_16x16x32_bf16 v[54:57], v[164:167], v[202:205], v[54:57]
	v_mfma_f32_16x16x32_bf16 v[54:57], v[182:185], v[206:209], v[54:57]
	v_mfma_f32_16x16x32_bf16 v[46:49], v[186:189], v[202:205], v[46:49]
	v_mfma_f32_16x16x32_bf16 v[46:49], v[190:193], v[206:209], v[46:49]
	v_mfma_f32_16x16x32_bf16 v[38:41], v[164:167], v[210:213], v[38:41]
	v_mfma_f32_16x16x32_bf16 v[38:41], v[182:185], v[214:217], v[38:41]
	v_mfma_f32_16x16x32_bf16 v[30:33], v[186:189], v[210:213], v[30:33]
	v_mfma_f32_16x16x32_bf16 v[30:33], v[190:193], v[214:217], v[30:33]
	v_mfma_f32_16x16x32_bf16 v[22:25], v[164:167], v[218:221], v[22:25]
	v_mfma_f32_16x16x32_bf16 v[22:25], v[182:185], v[222:225], v[22:25]
	v_mfma_f32_16x16x32_bf16 v[14:17], v[186:189], v[218:221], v[14:17]
	s_barrier
	v_mfma_f32_16x16x32_bf16 v[14:17], v[190:193], v[222:225], v[14:17]
	s_setprio 0
	s_add_u32 s24, s48, 0x100080
	s_addc_u32 s25, s49, 0
	s_add_i32 s48, s76, s83
	s_mov_b32 m0, s48
	s_nop 0
	global_load_lds_dwordx4 v134, s[24:25]
	s_add_i32 m0, s48, 0x2000
	s_nop 0
	global_load_lds_dwordx4 v130, s[24:25]
	ds_read_b128 v[164:167], v249
	ds_read_b128 v[182:185], v249 offset:1024
	ds_read_b128 v[186:189], v249 offset:2048
	ds_read_b128 v[190:193], v249 offset:3072
	s_waitcnt vmcnt(6)
	s_barrier
	s_setprio 1
	v_mfma_f32_16x16x32_bf16 v[50:53], v[226:229], v[194:197], v[50:53]
	v_mfma_f32_16x16x32_bf16 v[50:53], v[230:233], v[198:201], v[50:53]
	v_mfma_f32_16x16x32_bf16 v[42:45], v[234:237], v[194:197], v[42:45]
	ds_read_b128 v[194:197], v162
	v_mfma_f32_16x16x32_bf16 v[42:45], v[238:241], v[198:201], v[42:45]
	ds_read_b128 v[198:201], v162 offset:1024
	v_mfma_f32_16x16x32_bf16 v[34:37], v[226:229], v[202:205], v[34:37]
	v_mfma_f32_16x16x32_bf16 v[34:37], v[230:233], v[206:209], v[34:37]
	v_mfma_f32_16x16x32_bf16 v[26:29], v[234:237], v[202:205], v[26:29]
	ds_read_b128 v[202:205], v162 offset:2048
	v_mfma_f32_16x16x32_bf16 v[26:29], v[238:241], v[206:209], v[26:29]
	ds_read_b128 v[206:209], v162 offset:3072
	v_mfma_f32_16x16x32_bf16 v[18:21], v[226:229], v[210:213], v[18:21]
	v_mfma_f32_16x16x32_bf16 v[18:21], v[230:233], v[214:217], v[18:21]
	v_mfma_f32_16x16x32_bf16 v[10:13], v[234:237], v[210:213], v[10:13]
	ds_read_b128 v[210:213], v162 offset:4096
	v_mfma_f32_16x16x32_bf16 v[10:13], v[238:241], v[214:217], v[10:13]
	ds_read_b128 v[214:217], v162 offset:5120
	v_mfma_f32_16x16x32_bf16 v[6:9], v[226:229], v[218:221], v[6:9]
	v_mfma_f32_16x16x32_bf16 v[6:9], v[230:233], v[222:225], v[6:9]
	v_mfma_f32_16x16x32_bf16 v[2:5], v[234:237], v[218:221], v[2:5]
	s_barrier
	v_mfma_f32_16x16x32_bf16 v[2:5], v[238:241], v[222:225], v[2:5]
	s_setprio 0
	s_add_i32 s98, s98, 2
	s_add_u32 s35, s35, 0x100
	s_addc_u32 s50, s50, 0
	s_add_u32 s0, s0, 0x100
	s_addc_u32 s1, s1, 0
	s_cmp_gt_u32 s98, 61
	s_cbranch_scc0 .LBB0_627
	s_waitcnt lgkmcnt(0)
	s_and_b64 vcc, exec, s[40:41]
	s_cbranch_vccz .LBB0_630
	s_barrier
